# K-loop MFMA order: accumulate pairs adjacent (SrcC forwarded) with alternating k direction so consecutive pairs share one A/B operand register
# speedup vs baseline: 1.0150x; 1.0100x over previous
; #define PG8_STAGE(bufoff, gbase, voff) do { _Pragma("unroll") for (int _i = 0; _i < 2; ++_i) \
;         __builtin_amdgcn_global_load_lds((const unsigned*)((const char*)(gbase) + (voff)[_i]), (PG8_LAS unsigned*)(lds + (bufoff) + ldsw + _i * 8192), 16, 0, 0); } while (0)
; #define PG8_LDA(dst, b, h) do { _Pragma("unroll") for (int m = 0; m < 4; ++m) _Pragma("unroll") for (int k = 0; k < 2; ++k) dst[m][k] = *(const PG8_LAS bf16x8*)(lds + PG8_SA(b, h) + aoff + m * 2048 + k * 1024); } while (0)
; #define PG8_LDB(dst, b, h) do { _Pragma("unroll") for (int n = 0; n < 2; ++n) _Pragma("unroll") for (int k = 0; k < 2; ++k) dst[n][k] = *(const PG8_LAS bf16x8*)(lds + PG8_SB(b, h) + boff + n * 2048 + k * 1024); } while (0)
; #define PG8_MMA(ai, bj, At, Bt) do { __builtin_amdgcn_s_setprio(1); _Pragma("unroll") for (int m = 0; m < 4; ++m) _Pragma("unroll") for (int n = 0; n < 2; ++n) _Pragma("unroll") for (int k = 0; k < 2; ++k) \
;         acc[ai][bj][m][n] = __builtin_amdgcn_mfma_f32_16x16x32_bf16(Bt[n][k], At[m][k], acc[ai][bj][m][n], 0, 0, 0); __builtin_amdgcn_s_setprio(0); } while (0)
; #define PG8_WAIT_V(n) asm volatile("s_waitcnt vmcnt(" #n ")" ::: "memory")
; #define PG8_WAIT_L(n) asm volatile("s_waitcnt lgkmcnt(" #n ")" ::: "memory")
; #define PG8_BAR __builtin_amdgcn_s_barrier()
; #define PG8_SCHED __builtin_amdgcn_sched_barrier(0)
; template <class Epi, class Sched, bool ALIGN_EPI = false, bool SP2 = false>
; __device__ __forceinline__ void gemm_phase(PG8_LAS unsigned char* lds, const Gemm g, const Sched& S, const Epi& E) {
;     ...
;             const bool last = (t == nt - 2);
;             const char* a1 = cA + (size_t)(t + 1) * kstep;
;             const char* a2 = last ? nA : cA + (size_t)(t + 2) * kstep; const char* b2 = last ? nB : cB + (size_t)(t + 2) * kstep;
;             const char* a3 = a2 + kstep; const char* b3 = b2 + kstep;
;             if (last && has_next) S.a_ready(nxt);
;             if constexpr (SP2) {
;             PG8_LDB(B0, 0, 0); PG8_LDB(B1, 0, 1); PG8_SCHED; PG8_LDA(At, 0, 0); PG8_STAGE(PG8_SA(1, 1), a1 + hstep, voffA);
;             PG8_WAIT_V(8); PG8_WAIT_L(0); PG8_BAR; PG8_MMA(0, 0, At, B0); PG8_MMA(0, 1, At, B1); PG8_BAR; PG8_SCHED;
;             PG8_LDA(At, 0, 1); PG8_STAGE(PG8_SB(0, 0), b2, voffB); PG8_STAGE(PG8_SB(0, 1), b2 + hstep, voffB); PG8_STAGE(PG8_SA(0, 0), a2, voffA);
.LBB0_139:
	ds_read_b128 v[2:5], v187
	ds_read_b128 v[6:9], v187 offset:1024
	ds_read_b128 v[138:141], v187 offset:2048
	ds_read_b128 v[142:145], v187 offset:3072
	ds_read_b128 v[146:149], v197
	ds_read_b128 v[150:153], v197 offset:1024
	ds_read_b128 v[154:157], v197 offset:2048
	ds_read_b128 v[158:161], v197 offset:3072
	s_add_u32 s14, s12, 0xfff00080
	s_addc_u32 s15, s13, -1
	s_cmp_eq_u32 s33, 60
	s_cselect_b32 s17, s2, s15
	s_cselect_b32 s16, s11, s14
	s_cselect_b32 s15, s26, s30
	s_cselect_b32 s14, s28, s29
	v_lshl_add_u64 v[162:163], s[12:13], 0, v[188:189]
	s_add_i32 m0, s27, 0xc000
	ds_read_b128 v[202:205], v199
	ds_read_b128 v[206:209], v199 offset:1024
	ds_read_b128 v[214:217], v199 offset:2048
	ds_read_b128 v[218:221], v199 offset:3072
	ds_read_b128 v[222:225], v199 offset:4096
	ds_read_b128 v[226:229], v199 offset:5120
	ds_read_b128 v[230:233], v199 offset:6144
	ds_read_b128 v[234:237], v199 offset:7168
	global_load_lds_dwordx4 v[162:163], off
	v_lshl_add_u64 v[162:163], s[12:13], 0, v[190:191]
	s_add_i32 m0, s27, 0xe000
	s_nop 0
	global_load_lds_dwordx4 v[162:163], off
	s_waitcnt vmcnt(8)
	s_waitcnt lgkmcnt(0)
	s_setprio 1
	s_barrier
	v_mfma_f32_16x16x32_bf16 v[134:137], v[2:5], v[202:205], v[134:137]
	v_mfma_f32_16x16x32_bf16 v[134:137], v[6:9], v[206:209], v[134:137]
	v_mfma_f32_16x16x32_bf16 v[130:133], v[142:145], v[206:209], v[130:133]
	v_mfma_f32_16x16x32_bf16 v[130:133], v[138:141], v[202:205], v[130:133]
	v_mfma_f32_16x16x32_bf16 v[114:117], v[138:141], v[214:217], v[114:117]
	v_mfma_f32_16x16x32_bf16 v[114:117], v[142:145], v[218:221], v[114:117]
	v_mfma_f32_16x16x32_bf16 v[118:121], v[6:9], v[218:221], v[118:121]
	v_mfma_f32_16x16x32_bf16 v[118:121], v[2:5], v[214:217], v[118:121]
	v_mfma_f32_16x16x32_bf16 v[102:105], v[2:5], v[222:225], v[102:105]
	v_mfma_f32_16x16x32_bf16 v[102:105], v[6:9], v[226:229], v[102:105]
	v_mfma_f32_16x16x32_bf16 v[98:101], v[142:145], v[226:229], v[98:101]
	v_mfma_f32_16x16x32_bf16 v[98:101], v[138:141], v[222:225], v[98:101]
	v_mfma_f32_16x16x32_bf16 v[82:85], v[138:141], v[230:233], v[82:85]
	v_mfma_f32_16x16x32_bf16 v[82:85], v[142:145], v[234:237], v[82:85]
	v_mfma_f32_16x16x32_bf16 v[86:89], v[6:9], v[234:237], v[86:89]
	v_mfma_f32_16x16x32_bf16 v[86:89], v[2:5], v[230:233], v[86:89]
	s_setprio 0
	s_setprio 1
	v_mfma_f32_16x16x32_bf16 v[126:129], v[146:149], v[202:205], v[126:129]
	v_mfma_f32_16x16x32_bf16 v[126:129], v[150:153], v[206:209], v[126:129]
	v_mfma_f32_16x16x32_bf16 v[122:125], v[158:161], v[206:209], v[122:125]
	v_mfma_f32_16x16x32_bf16 v[122:125], v[154:157], v[202:205], v[122:125]
	v_mfma_f32_16x16x32_bf16 v[106:109], v[154:157], v[214:217], v[106:109]
	v_mfma_f32_16x16x32_bf16 v[106:109], v[158:161], v[218:221], v[106:109]
	v_mfma_f32_16x16x32_bf16 v[110:113], v[150:153], v[218:221], v[110:113]
	v_mfma_f32_16x16x32_bf16 v[110:113], v[146:149], v[214:217], v[110:113]
	v_mfma_f32_16x16x32_bf16 v[94:97], v[146:149], v[222:225], v[94:97]
	v_mfma_f32_16x16x32_bf16 v[94:97], v[150:153], v[226:229], v[94:97]
	v_mfma_f32_16x16x32_bf16 v[90:93], v[158:161], v[226:229], v[90:93]
	v_mfma_f32_16x16x32_bf16 v[90:93], v[154:157], v[222:225], v[90:93]
	v_mfma_f32_16x16x32_bf16 v[74:77], v[154:157], v[230:233], v[74:77]
	v_mfma_f32_16x16x32_bf16 v[74:77], v[158:161], v[234:237], v[74:77]
	v_mfma_f32_16x16x32_bf16 v[78:81], v[150:153], v[234:237], v[78:81]
	v_mfma_f32_16x16x32_bf16 v[78:81], v[146:149], v[230:233], v[78:81]
	s_barrier
	s_setprio 0
	s_add_i32 s34, s41, s25
	v_lshl_add_u64 v[162:163], s[14:15], 0, v[168:169]
	s_mov_b32 m0, s34
	ds_read_b128 v[202:205], v199 offset:16384
	ds_read_b128 v[206:209], v199 offset:17408
	ds_read_b128 v[214:217], v199 offset:18432
	ds_read_b128 v[218:221], v199 offset:19456
	ds_read_b128 v[222:225], v199 offset:20480
	ds_read_b128 v[226:229], v199 offset:21504
	ds_read_b128 v[230:233], v199 offset:22528
	ds_read_b128 v[234:237], v199 offset:23552
	global_load_lds_dwordx4 v[162:163], off
	s_add_i32 m0, s34, 0x2000
	s_add_u32 s34, s14, 0x100000
	v_lshl_add_u64 v[210:211], s[14:15], 0, v[172:173]
	s_addc_u32 s35, s15, 0
	s_add_i32 s79, s92, s25
	global_load_lds_dwordx4 v[210:211], off
	v_lshl_add_u64 v[238:239], s[34:35], 0, v[168:169]
	s_mov_b32 m0, s79
	v_lshl_add_u64 v[240:241], s[16:17], 0, v[170:171]
	global_load_lds_dwordx4 v[238:239], off
	v_lshl_add_u64 v[238:239], s[34:35], 0, v[172:173]
	s_add_i32 m0, s79, 0x2000
	s_nop 0
	global_load_lds_dwordx4 v[238:239], off
	v_lshl_add_u64 v[238:239], s[16:17], 0, v[164:165]
	s_mov_b32 m0, s27
	s_nop 0
	global_load_lds_dwordx4 v[238:239], off
	s_mov_b32 m0, s39
	s_nop 0
	global_load_lds_dwordx4 v[240:241], off
	s_waitcnt vmcnt(8)
	s_waitcnt lgkmcnt(0)
	s_setprio 1
	s_barrier
; #define PG8_STAGE(bufoff, gbase, voff) do { _Pragma("unroll") for (int _i = 0; _i < 2; ++_i) \
;         __builtin_amdgcn_global_load_lds((const unsigned*)((const char*)(gbase) + (voff)[_i]), (PG8_LAS unsigned*)(lds + (bufoff) + ldsw + _i * 8192), 16, 0, 0); } while (0)
; #define PG8_LDA(dst, b, h) do { _Pragma("unroll") for (int m = 0; m < 4; ++m) _Pragma("unroll") for (int k = 0; k < 2; ++k) dst[m][k] = *(const PG8_LAS bf16x8*)(lds + PG8_SA(b, h) + aoff + m * 2048 + k * 1024); } while (0)
; #define PG8_LDB(dst, b, h) do { _Pragma("unroll") for (int n = 0; n < 2; ++n) _Pragma("unroll") for (int k = 0; k < 2; ++k) dst[n][k] = *(const PG8_LAS bf16x8*)(lds + PG8_SB(b, h) + boff + n * 2048 + k * 1024); } while (0)
; #define PG8_MMA(ai, bj, At, Bt) do { __builtin_amdgcn_s_setprio(1); _Pragma("unroll") for (int m = 0; m < 4; ++m) _Pragma("unroll") for (int n = 0; n < 2; ++n) _Pragma("unroll") for (int k = 0; k < 2; ++k) \
;         acc[ai][bj][m][n] = __builtin_amdgcn_mfma_f32_16x16x32_bf16(Bt[n][k], At[m][k], acc[ai][bj][m][n], 0, 0, 0); __builtin_amdgcn_s_setprio(0); } while (0)
; #define PG8_WAIT_V(n) asm volatile("s_waitcnt vmcnt(" #n ")" ::: "memory")
; #define PG8_WAIT_L(n) asm volatile("s_waitcnt lgkmcnt(" #n ")" ::: "memory")
; #define PG8_BAR __builtin_amdgcn_s_barrier()
; #define PG8_SCHED __builtin_amdgcn_sched_barrier(0)
; template <class Epi, class Sched, bool ALIGN_EPI = false, bool SP2 = false>
; __device__ __forceinline__ void gemm_phase(PG8_LAS unsigned char* lds, const Gemm g, const Sched& S, const Epi& E) {
;     ...
;             PG8_WAIT_V(8); PG8_WAIT_L(0); PG8_BAR; PG8_MMA(1, 0, At, B0); PG8_MMA(1, 1, At, B1); PG8_BAR; PG8_SCHED;
;             PG8_LDB(B0, 1, 0); PG8_LDB(B1, 1, 1); PG8_SCHED; PG8_LDA(At, 1, 0); PG8_STAGE(PG8_SA(0, 1), a2 + hstep, voffA);
;             PG8_WAIT_V(8); PG8_WAIT_L(0); PG8_BAR; PG8_MMA(0, 0, At, B0); PG8_MMA(0, 1, At, B1); PG8_BAR; PG8_SCHED;
	v_mfma_f32_16x16x32_bf16 v[70:73], v[2:5], v[202:205], v[70:73]
	v_mfma_f32_16x16x32_bf16 v[66:69], v[138:141], v[202:205], v[66:69]
	v_mfma_f32_16x16x32_bf16 v[54:57], v[2:5], v[214:217], v[54:57]
	v_mfma_f32_16x16x32_bf16 v[50:53], v[138:141], v[214:217], v[50:53]
	v_mfma_f32_16x16x32_bf16 v[38:41], v[2:5], v[222:225], v[38:41]
	v_mfma_f32_16x16x32_bf16 v[34:37], v[138:141], v[222:225], v[34:37]
	v_mfma_f32_16x16x32_bf16 v[2:5], v[2:5], v[230:233], v[22:25]
	v_mfma_f32_16x16x32_bf16 v[70:73], v[6:9], v[206:209], v[70:73]
	v_mfma_f32_16x16x32_bf16 v[66:69], v[142:145], v[206:209], v[66:69]
	v_mfma_f32_16x16x32_bf16 v[54:57], v[6:9], v[218:221], v[54:57]
	v_mfma_f32_16x16x32_bf16 v[50:53], v[142:145], v[218:221], v[50:53]
	v_mfma_f32_16x16x32_bf16 v[38:41], v[6:9], v[226:229], v[38:41]
	v_mfma_f32_16x16x32_bf16 v[34:37], v[142:145], v[226:229], v[34:37]
	v_mfma_f32_16x16x32_bf16 v[2:5], v[6:9], v[234:237], v[2:5]
	v_mfma_f32_16x16x32_bf16 v[6:9], v[138:141], v[230:233], v[18:21]
	v_mfma_f32_16x16x32_bf16 v[6:9], v[142:145], v[234:237], v[6:9]
	s_setprio 0
	s_setprio 1
	v_mfma_f32_16x16x32_bf16 v[18:21], v[146:149], v[202:205], v[62:65]
	v_mfma_f32_16x16x32_bf16 v[62:65], v[150:153], v[206:209], v[18:21]
	v_mfma_f32_16x16x32_bf16 v[18:21], v[154:157], v[202:205], v[58:61]
	v_mfma_f32_16x16x32_bf16 v[58:61], v[158:161], v[206:209], v[18:21]
	v_mfma_f32_16x16x32_bf16 v[18:21], v[146:149], v[214:217], v[46:49]
	v_mfma_f32_16x16x32_bf16 v[46:49], v[150:153], v[218:221], v[18:21]
	v_mfma_f32_16x16x32_bf16 v[18:21], v[154:157], v[214:217], v[42:45]
	v_mfma_f32_16x16x32_bf16 v[42:45], v[158:161], v[218:221], v[18:21]
	v_mfma_f32_16x16x32_bf16 v[18:21], v[146:149], v[222:225], v[30:33]
	v_mfma_f32_16x16x32_bf16 v[30:33], v[150:153], v[226:229], v[18:21]
	v_mfma_f32_16x16x32_bf16 v[18:21], v[154:157], v[222:225], v[26:29]
	v_mfma_f32_16x16x32_bf16 v[14:17], v[146:149], v[230:233], v[14:17]
	v_mfma_f32_16x16x32_bf16 v[10:13], v[154:157], v[230:233], v[10:13]
	v_mfma_f32_16x16x32_bf16 v[26:29], v[158:161], v[226:229], v[18:21]
	v_mfma_f32_16x16x32_bf16 v[14:17], v[150:153], v[234:237], v[14:17]
	v_mfma_f32_16x16x32_bf16 v[10:13], v[158:161], v[234:237], v[10:13]
	s_barrier
	s_setprio 0
	s_add_i32 s34, 0, 0x18000
	s_add_i32 s35, 0, 0x1c000
	v_add_u32_e32 v142, s34, v179
	v_add_u32_e32 v158, s35, v179
	ds_read_b128 v[18:21], v142
	ds_read_b128 v[22:25], v142 offset:1024
	ds_read_b128 v[138:141], v142 offset:2048
	ds_read_b128 v[142:145], v142 offset:3072
	ds_read_b128 v[146:149], v158
	ds_read_b128 v[150:153], v158 offset:1024
	ds_read_b128 v[154:157], v158 offset:2048
	ds_read_b128 v[158:161], v158 offset:3072
	s_add_u32 s16, s16, 0x100000
	s_addc_u32 s17, s17, 0
	s_mov_b32 m0, s71
	v_lshl_add_u64 v[242:243], s[16:17], 0, v[164:165]
	ds_read_b128 v[202:205], v199 offset:32768
	ds_read_b128 v[206:209], v199 offset:33792
	ds_read_b128 v[214:217], v199 offset:34816
	ds_read_b128 v[218:221], v199 offset:35840
	ds_read_b128 v[222:225], v199 offset:36864
	ds_read_b128 v[226:229], v199 offset:37888
	ds_read_b128 v[230:233], v199 offset:38912
	ds_read_b128 v[234:237], v199 offset:39936
	global_load_lds_dwordx4 v[242:243], off
	v_lshl_add_u64 v[242:243], s[16:17], 0, v[170:171]
	s_mov_b32 m0, s87
	s_nop 0
	global_load_lds_dwordx4 v[242:243], off
	s_waitcnt vmcnt(8)
	s_waitcnt lgkmcnt(0)
	s_setprio 1
	s_barrier
	v_mfma_f32_16x16x32_bf16 v[134:137], v[18:21], v[202:205], v[134:137]
	v_mfma_f32_16x16x32_bf16 v[134:137], v[22:25], v[206:209], v[134:137]
	v_mfma_f32_16x16x32_bf16 v[130:133], v[142:145], v[206:209], v[130:133]
	v_mfma_f32_16x16x32_bf16 v[130:133], v[138:141], v[202:205], v[130:133]
	v_mfma_f32_16x16x32_bf16 v[114:117], v[138:141], v[214:217], v[114:117]
	v_mfma_f32_16x16x32_bf16 v[114:117], v[142:145], v[218:221], v[114:117]
	v_mfma_f32_16x16x32_bf16 v[118:121], v[22:25], v[218:221], v[118:121]
	v_mfma_f32_16x16x32_bf16 v[118:121], v[18:21], v[214:217], v[118:121]
	v_mfma_f32_16x16x32_bf16 v[102:105], v[18:21], v[222:225], v[102:105]
	v_mfma_f32_16x16x32_bf16 v[102:105], v[22:25], v[226:229], v[102:105]
	v_mfma_f32_16x16x32_bf16 v[98:101], v[142:145], v[226:229], v[98:101]
	v_mfma_f32_16x16x32_bf16 v[98:101], v[138:141], v[222:225], v[98:101]
	v_mfma_f32_16x16x32_bf16 v[82:85], v[138:141], v[230:233], v[82:85]
	v_mfma_f32_16x16x32_bf16 v[82:85], v[142:145], v[234:237], v[82:85]
	v_mfma_f32_16x16x32_bf16 v[86:89], v[22:25], v[234:237], v[86:89]
	v_mfma_f32_16x16x32_bf16 v[86:89], v[18:21], v[230:233], v[86:89]
	s_setprio 0
	s_setprio 1
	v_mfma_f32_16x16x32_bf16 v[126:129], v[146:149], v[202:205], v[126:129]
	v_mfma_f32_16x16x32_bf16 v[126:129], v[150:153], v[206:209], v[126:129]
	v_mfma_f32_16x16x32_bf16 v[122:125], v[158:161], v[206:209], v[122:125]
	v_mfma_f32_16x16x32_bf16 v[122:125], v[154:157], v[202:205], v[122:125]
	v_mfma_f32_16x16x32_bf16 v[106:109], v[154:157], v[214:217], v[106:109]
	v_mfma_f32_16x16x32_bf16 v[106:109], v[158:161], v[218:221], v[106:109]
	v_mfma_f32_16x16x32_bf16 v[110:113], v[150:153], v[218:221], v[110:113]
	v_mfma_f32_16x16x32_bf16 v[110:113], v[146:149], v[214:217], v[110:113]
	v_mfma_f32_16x16x32_bf16 v[94:97], v[146:149], v[222:225], v[94:97]
	v_mfma_f32_16x16x32_bf16 v[94:97], v[150:153], v[226:229], v[94:97]
	v_mfma_f32_16x16x32_bf16 v[90:93], v[158:161], v[226:229], v[90:93]
	v_mfma_f32_16x16x32_bf16 v[90:93], v[154:157], v[222:225], v[90:93]
	v_mfma_f32_16x16x32_bf16 v[74:77], v[154:157], v[230:233], v[74:77]
	v_mfma_f32_16x16x32_bf16 v[74:77], v[158:161], v[234:237], v[74:77]
	v_mfma_f32_16x16x32_bf16 v[78:81], v[150:153], v[234:237], v[78:81]
	v_mfma_f32_16x16x32_bf16 v[78:81], v[146:149], v[230:233], v[78:81]
	s_barrier
; #define PG8_STAGE(bufoff, gbase, voff) do { _Pragma("unroll") for (int _i = 0; _i < 2; ++_i) \
;         __builtin_amdgcn_global_load_lds((const unsigned*)((const char*)(gbase) + (voff)[_i]), (PG8_LAS unsigned*)(lds + (bufoff) + ldsw + _i * 8192), 16, 0, 0); } while (0)
; #define PG8_LDA(dst, b, h) do { _Pragma("unroll") for (int m = 0; m < 4; ++m) _Pragma("unroll") for (int k = 0; k < 2; ++k) dst[m][k] = *(const PG8_LAS bf16x8*)(lds + PG8_SA(b, h) + aoff + m * 2048 + k * 1024); } while (0)
; #define PG8_MMA(ai, bj, At, Bt) do { __builtin_amdgcn_s_setprio(1); _Pragma("unroll") for (int m = 0; m < 4; ++m) _Pragma("unroll") for (int n = 0; n < 2; ++n) _Pragma("unroll") for (int k = 0; k < 2; ++k) \
;         acc[ai][bj][m][n] = __builtin_amdgcn_mfma_f32_16x16x32_bf16(Bt[n][k], At[m][k], acc[ai][bj][m][n], 0, 0, 0); __builtin_amdgcn_s_setprio(0); } while (0)
; #define PG8_WAIT_V(n) asm volatile("s_waitcnt vmcnt(" #n ")" ::: "memory")
; #define PG8_WAIT_L(n) asm volatile("s_waitcnt lgkmcnt(" #n ")" ::: "memory")
; #define PG8_BAR __builtin_amdgcn_s_barrier()
; #define PG8_SCHED __builtin_amdgcn_sched_barrier(0)
; template <class Epi, class Sched, bool ALIGN_EPI = false, bool SP2 = false>
; __device__ __forceinline__ void gemm_phase(PG8_LAS unsigned char* lds, const Gemm g, const Sched& S, const Epi& E) {
;     ...
;         for (int t = 0; t < nt; t += 2) {
;             const bool last = (t == nt - 2);
;             const char* a1 = cA + (size_t)(t + 1) * kstep;
;             const char* a2 = last ? nA : cA + (size_t)(t + 2) * kstep; const char* b2 = last ? nB : cB + (size_t)(t + 2) * kstep;
;             const char* a3 = a2 + kstep; const char* b3 = b2 + kstep;
;     ...
;             PG8_LDA(At, 1, 1); PG8_STAGE(PG8_SB(1, 0), b3, voffB); PG8_STAGE(PG8_SB(1, 1), b3 + hstep, voffB); PG8_STAGE(PG8_SA(1, 0), a3, voffA);
;             PG8_WAIT_V(8); PG8_WAIT_L(0); PG8_BAR; PG8_MMA(1, 0, At, B0); PG8_MMA(1, 1, At, B1); PG8_BAR; PG8_SCHED;
	s_setprio 0
	s_add_i32 s16, s34, s25
	v_lshl_add_u64 v[162:163], v[162:163], 0, s[46:47]
	s_mov_b32 m0, s16
	ds_read_b128 v[202:205], v199 offset:49152
	ds_read_b128 v[206:209], v199 offset:50176
	ds_read_b128 v[214:217], v199 offset:51200
	ds_read_b128 v[218:221], v199 offset:52224
	ds_read_b128 v[222:225], v199 offset:53248
	ds_read_b128 v[226:229], v199 offset:54272
	ds_read_b128 v[230:233], v199 offset:55296
	ds_read_b128 v[234:237], v199 offset:56320
	global_load_lds_dwordx4 v[162:163], off
	s_add_i32 m0, s16, 0x2000
	s_add_u32 s14, s14, 0x100080
	v_lshl_add_u64 v[162:163], v[210:211], 0, s[46:47]
	s_addc_u32 s15, s15, 0
	s_add_i32 s16, s35, s25
	global_load_lds_dwordx4 v[162:163], off
	v_lshl_add_u64 v[162:163], s[14:15], 0, v[168:169]
	s_mov_b32 m0, s16
	s_nop 0
	global_load_lds_dwordx4 v[162:163], off
	v_lshl_add_u64 v[162:163], s[14:15], 0, v[172:173]
	s_add_i32 m0, s16, 0x2000
	s_nop 0
	global_load_lds_dwordx4 v[162:163], off
	v_lshl_add_u64 v[162:163], v[238:239], 0, s[46:47]
	s_mov_b32 m0, s95
	s_nop 0
	global_load_lds_dwordx4 v[162:163], off
	v_lshl_add_u64 v[162:163], v[240:241], 0, s[46:47]
	s_mov_b32 m0, s96
	s_nop 0
	global_load_lds_dwordx4 v[162:163], off
	s_waitcnt vmcnt(8)
	s_waitcnt lgkmcnt(0)
	s_setprio 1
	s_barrier
	v_mfma_f32_16x16x32_bf16 v[70:73], v[18:21], v[202:205], v[70:73]
	v_mfma_f32_16x16x32_bf16 v[54:57], v[18:21], v[214:217], v[54:57]
	v_mfma_f32_16x16x32_bf16 v[38:41], v[18:21], v[222:225], v[38:41]
	v_mfma_f32_16x16x32_bf16 v[2:5], v[18:21], v[230:233], v[2:5]
	v_mfma_f32_16x16x32_bf16 v[70:73], v[22:25], v[206:209], v[70:73]
	v_mfma_f32_16x16x32_bf16 v[66:69], v[138:141], v[202:205], v[66:69]
	v_mfma_f32_16x16x32_bf16 v[54:57], v[22:25], v[218:221], v[54:57]
	v_mfma_f32_16x16x32_bf16 v[50:53], v[138:141], v[214:217], v[50:53]
	v_mfma_f32_16x16x32_bf16 v[38:41], v[22:25], v[226:229], v[38:41]
	v_mfma_f32_16x16x32_bf16 v[34:37], v[138:141], v[222:225], v[34:37]
	v_mfma_f32_16x16x32_bf16 v[22:25], v[22:25], v[234:237], v[2:5]
	v_mfma_f32_16x16x32_bf16 v[2:5], v[138:141], v[230:233], v[6:9]
	v_mfma_f32_16x16x32_bf16 v[66:69], v[142:145], v[206:209], v[66:69]
	v_mfma_f32_16x16x32_bf16 v[50:53], v[142:145], v[218:221], v[50:53]
	v_mfma_f32_16x16x32_bf16 v[34:37], v[142:145], v[226:229], v[34:37]
	v_mfma_f32_16x16x32_bf16 v[18:21], v[142:145], v[234:237], v[2:5]
	s_setprio 0
	s_setprio 1
	v_mfma_f32_16x16x32_bf16 v[2:5], v[146:149], v[202:205], v[62:65]
	v_mfma_f32_16x16x32_bf16 v[62:65], v[150:153], v[206:209], v[2:5]
	v_mfma_f32_16x16x32_bf16 v[2:5], v[154:157], v[202:205], v[58:61]
	v_mfma_f32_16x16x32_bf16 v[58:61], v[158:161], v[206:209], v[2:5]
	v_mfma_f32_16x16x32_bf16 v[2:5], v[146:149], v[214:217], v[46:49]
	v_mfma_f32_16x16x32_bf16 v[46:49], v[150:153], v[218:221], v[2:5]
	v_mfma_f32_16x16x32_bf16 v[2:5], v[154:157], v[214:217], v[42:45]
	v_mfma_f32_16x16x32_bf16 v[42:45], v[158:161], v[218:221], v[2:5]
	v_mfma_f32_16x16x32_bf16 v[2:5], v[146:149], v[222:225], v[30:33]
	v_mfma_f32_16x16x32_bf16 v[30:33], v[150:153], v[226:229], v[2:5]
	v_mfma_f32_16x16x32_bf16 v[2:5], v[154:157], v[222:225], v[26:29]
	v_mfma_f32_16x16x32_bf16 v[26:29], v[158:161], v[226:229], v[2:5]
	v_mfma_f32_16x16x32_bf16 v[2:5], v[146:149], v[230:233], v[14:17]
	v_mfma_f32_16x16x32_bf16 v[14:17], v[150:153], v[234:237], v[2:5]
	v_mfma_f32_16x16x32_bf16 v[2:5], v[154:157], v[230:233], v[10:13]
	v_mfma_f32_16x16x32_bf16 v[10:13], v[158:161], v[234:237], v[2:5]
	s_barrier
	s_setprio 0
	s_add_i32 s33, s33, 2
	s_add_u32 s12, s12, 0x100
	s_addc_u32 s13, s13, 0
	s_add_u32 s29, s29, 0x100
	s_addc_u32 s30, s30, 0
	s_cmp_gt_u32 s33, 61
	s_cbranch_scc0 .LBB0_139
	s_and_b64 vcc, exec, s[48:49]
	s_cbranch_vccz .LBB0_142
	s_barrier

; #define PG8_STAGE(bufoff, gbase, voff) do { _Pragma("unroll") for (int _i = 0; _i < 2; ++_i) \
;         __builtin_amdgcn_global_load_lds((const unsigned*)((const char*)(gbase) + (voff)[_i]), (PG8_LAS unsigned*)(lds + (bufoff) + ldsw + _i * 8192), 16, 0, 0); } while (0)
; #define PG8_LDA(dst, b, h) do { _Pragma("unroll") for (int m = 0; m < 4; ++m) _Pragma("unroll") for (int k = 0; k < 2; ++k) dst[m][k] = *(const PG8_LAS bf16x8*)(lds + PG8_SA(b, h) + aoff + m * 2048 + k * 1024); } while (0)
; #define PG8_LDB(dst, b, h) do { _Pragma("unroll") for (int n = 0; n < 2; ++n) _Pragma("unroll") for (int k = 0; k < 2; ++k) dst[n][k] = *(const PG8_LAS bf16x8*)(lds + PG8_SB(b, h) + boff + n * 2048 + k * 1024); } while (0)
; #define PG8_MMA(ai, bj, At, Bt) do { __builtin_amdgcn_s_setprio(1); _Pragma("unroll") for (int m = 0; m < 4; ++m) _Pragma("unroll") for (int n = 0; n < 2; ++n) _Pragma("unroll") for (int k = 0; k < 2; ++k) \
;         acc[ai][bj][m][n] = __builtin_amdgcn_mfma_f32_16x16x32_bf16(Bt[n][k], At[m][k], acc[ai][bj][m][n], 0, 0, 0); __builtin_amdgcn_s_setprio(0); } while (0)
; #define PG8_WAIT_V(n) asm volatile("s_waitcnt vmcnt(" #n ")" ::: "memory")
; #define PG8_WAIT_L(n) asm volatile("s_waitcnt lgkmcnt(" #n ")" ::: "memory")
; template <class Epi, class Sched, bool ALIGN_EPI = false, bool SP2 = false>
; __device__ __forceinline__ void gemm_phase(PG8_LAS unsigned char* lds, const Gemm g, const Sched& S, const Epi& E) {
;     ...
;             const bool last = (t == nt - 2);
;             const char* a1 = cA + (size_t)(t + 1) * kstep;
;             const char* a2 = last ? nA : cA + (size_t)(t + 2) * kstep; const char* b2 = last ? nB : cB + (size_t)(t + 2) * kstep;
;             const char* a3 = a2 + kstep; const char* b3 = b2 + kstep;
;             if (last && has_next) S.a_ready(nxt);
;             if constexpr (SP2) {
;             PG8_LDB(B0, 0, 0); PG8_LDB(B1, 0, 1); PG8_SCHED; PG8_LDA(At, 0, 0); PG8_STAGE(PG8_SA(1, 1), a1 + hstep, voffA);
;             PG8_WAIT_V(8); PG8_WAIT_L(0); PG8_BAR; PG8_MMA(0, 0, At, B0); PG8_MMA(0, 1, At, B1); PG8_BAR; PG8_SCHED;
;             PG8_LDA(At, 0, 1); PG8_STAGE(PG8_SB(0, 0), b2, voffB); PG8_STAGE(PG8_SB(0, 1), b2 + hstep, voffB); PG8_STAGE(PG8_SA(0, 0), a2, voffA);
;             PG8_WAIT_V(8); PG8_WAIT_L(0); PG8_BAR; PG8_MMA(1, 0, At, B0); PG8_MMA(1, 1, At, B1); PG8_BAR; PG8_SCHED;
.LBB0_592:
	s_or_b32 s10, s52, 1
	s_lshl_b64 s[96:97], s[10:11], 7
	s_add_i32 s10, s52, 2
	s_lshl_b64 s[54:55], s[10:11], 7
	s_cmp_lg_u32 s52, s94
	s_cselect_b32 s52, s54, 0
	s_cselect_b32 s53, s55, 0
	s_add_u32 s54, s50, s52
	s_addc_u32 s55, s51, s53
	s_add_i32 s95, 0, 0x10000
	v_add_u32_e32 v87, s95, v85
	ds_read_b128 v[88:91], v87
	ds_read_b128 v[92:95], v87 offset:1024
	ds_read_b128 v[100:103], v87 offset:2048
	ds_read_b128 v[104:107], v87 offset:3072
	s_add_u32 s52, s48, s52
	s_addc_u32 s53, s49, s53
	s_add_u32 s96, s50, s96
	s_addc_u32 s97, s51, s97
	s_add_u32 s96, s96, 0x100000
	s_addc_u32 s97, s97, 0
	v_lshl_add_u64 v[96:97], s[96:97], 0, v[66:67]
	s_add_i32 m0, s17, 0xc000
	ds_read_b128 v[108:111], v86
	ds_read_b128 v[112:115], v86 offset:1024
	ds_read_b128 v[116:119], v86 offset:2048
	ds_read_b128 v[120:123], v86 offset:3072
	ds_read_b128 v[124:127], v86 offset:4096
	ds_read_b128 v[128:131], v86 offset:5120
	ds_read_b128 v[132:135], v86 offset:6144
	ds_read_b128 v[136:139], v86 offset:7168
	global_load_lds_dwordx4 v[96:97], off
	v_lshl_add_u64 v[96:97], s[96:97], 0, v[76:77]
	s_add_i32 m0, s17, 0xe000
	s_nop 0
	global_load_lds_dwordx4 v[96:97], off
	s_waitcnt vmcnt(8)
	s_waitcnt lgkmcnt(0)
	s_setprio 1
	s_barrier
	v_mfma_f32_16x16x32_bf16 v[62:65], v[88:91], v[108:111], v[62:65]
	v_mfma_f32_16x16x32_bf16 v[62:65], v[92:95], v[112:115], v[62:65]
	v_mfma_f32_16x16x32_bf16 v[58:61], v[104:107], v[112:115], v[58:61]
	v_mfma_f32_16x16x32_bf16 v[58:61], v[100:103], v[108:111], v[58:61]
	v_mfma_f32_16x16x32_bf16 v[50:53], v[100:103], v[116:119], v[50:53]
	v_mfma_f32_16x16x32_bf16 v[50:53], v[104:107], v[120:123], v[50:53]
	v_mfma_f32_16x16x32_bf16 v[54:57], v[92:95], v[120:123], v[54:57]
	v_mfma_f32_16x16x32_bf16 v[54:57], v[88:91], v[116:119], v[54:57]
	v_mfma_f32_16x16x32_bf16 v[46:49], v[88:91], v[124:127], v[46:49]
	v_mfma_f32_16x16x32_bf16 v[46:49], v[92:95], v[128:131], v[46:49]
	v_mfma_f32_16x16x32_bf16 v[42:45], v[104:107], v[128:131], v[42:45]
	v_mfma_f32_16x16x32_bf16 v[42:45], v[100:103], v[124:127], v[42:45]
	v_mfma_f32_16x16x32_bf16 v[34:37], v[100:103], v[132:135], v[34:37]
	v_mfma_f32_16x16x32_bf16 v[34:37], v[104:107], v[136:139], v[34:37]
	v_mfma_f32_16x16x32_bf16 v[38:41], v[92:95], v[136:139], v[38:41]
	v_mfma_f32_16x16x32_bf16 v[38:41], v[88:91], v[132:135], v[38:41]
	s_setprio 0
	s_setprio 1
	s_setprio 0
	s_barrier
	s_add_i32 s95, s95, s29
	v_lshl_add_u64 v[96:97], s[52:53], 0, v[78:79]
	s_mov_b32 m0, s95
	ds_read_b128 v[108:111], v86 offset:16384
	ds_read_b128 v[112:115], v86 offset:17408
	ds_read_b128 v[116:119], v86 offset:18432
	ds_read_b128 v[120:123], v86 offset:19456
	ds_read_b128 v[124:127], v86 offset:20480
	ds_read_b128 v[128:131], v86 offset:21504
	ds_read_b128 v[132:135], v86 offset:22528
	ds_read_b128 v[136:139], v86 offset:23552
	global_load_lds_dwordx4 v[96:97], off
	s_add_i32 m0, s95, 0x2000
	s_add_u32 s96, s52, 0x100000
	v_lshl_add_u64 v[140:141], s[52:53], 0, v[74:75]
	s_addc_u32 s97, s53, 0
	global_load_lds_dwordx4 v[140:141], off
	v_lshl_add_u64 v[142:143], s[96:97], 0, v[78:79]
	s_mov_b32 m0, s30
	v_lshl_add_u64 v[144:145], s[54:55], 0, v[76:77]
	global_load_lds_dwordx4 v[142:143], off
	v_lshl_add_u64 v[142:143], s[96:97], 0, v[74:75]
	s_mov_b32 m0, s33
	s_nop 0
	global_load_lds_dwordx4 v[142:143], off
	v_lshl_add_u64 v[142:143], s[54:55], 0, v[66:67]
	s_mov_b32 m0, s17
	s_nop 0
	global_load_lds_dwordx4 v[142:143], off
	s_mov_b32 m0, s34
	s_nop 0
	global_load_lds_dwordx4 v[144:145], off
	s_waitcnt vmcnt(8)
	s_waitcnt lgkmcnt(0)
	s_setprio 1
	s_barrier
	v_mfma_f32_16x16x32_bf16 v[30:33], v[88:91], v[108:111], v[30:33]
	v_mfma_f32_16x16x32_bf16 v[30:33], v[92:95], v[112:115], v[30:33]
	v_mfma_f32_16x16x32_bf16 v[26:29], v[104:107], v[112:115], v[26:29]
	v_mfma_f32_16x16x32_bf16 v[26:29], v[100:103], v[108:111], v[26:29]
	v_mfma_f32_16x16x32_bf16 v[18:21], v[100:103], v[116:119], v[18:21]
	v_mfma_f32_16x16x32_bf16 v[18:21], v[104:107], v[120:123], v[18:21]
	v_mfma_f32_16x16x32_bf16 v[22:25], v[92:95], v[120:123], v[22:25]
	v_mfma_f32_16x16x32_bf16 v[22:25], v[88:91], v[116:119], v[22:25]
	v_mfma_f32_16x16x32_bf16 v[14:17], v[88:91], v[124:127], v[14:17]
	v_mfma_f32_16x16x32_bf16 v[14:17], v[92:95], v[128:131], v[14:17]
	v_mfma_f32_16x16x32_bf16 v[10:13], v[104:107], v[128:131], v[10:13]
	v_mfma_f32_16x16x32_bf16 v[10:13], v[100:103], v[124:127], v[10:13]
	v_mfma_f32_16x16x32_bf16 v[2:5], v[100:103], v[132:135], v[2:5]
	v_mfma_f32_16x16x32_bf16 v[2:5], v[104:107], v[136:139], v[2:5]
	v_mfma_f32_16x16x32_bf16 v[6:9], v[92:95], v[136:139], v[6:9]
	v_mfma_f32_16x16x32_bf16 v[6:9], v[88:91], v[132:135], v[6:9]
	s_setprio 0
	s_setprio 1
	s_setprio 0
	s_barrier
; #define PG8_STAGE(bufoff, gbase, voff) do { _Pragma("unroll") for (int _i = 0; _i < 2; ++_i) \
;         __builtin_amdgcn_global_load_lds((const unsigned*)((const char*)(gbase) + (voff)[_i]), (PG8_LAS unsigned*)(lds + (bufoff) + ldsw + _i * 8192), 16, 0, 0); } while (0)
; #define PG8_LDA(dst, b, h) do { _Pragma("unroll") for (int m = 0; m < 4; ++m) _Pragma("unroll") for (int k = 0; k < 2; ++k) dst[m][k] = *(const PG8_LAS bf16x8*)(lds + PG8_SA(b, h) + aoff + m * 2048 + k * 1024); } while (0)
; #define PG8_LDB(dst, b, h) do { _Pragma("unroll") for (int n = 0; n < 2; ++n) _Pragma("unroll") for (int k = 0; k < 2; ++k) dst[n][k] = *(const PG8_LAS bf16x8*)(lds + PG8_SB(b, h) + boff + n * 2048 + k * 1024); } while (0)
; #define PG8_MMA(ai, bj, At, Bt) do { __builtin_amdgcn_s_setprio(1); _Pragma("unroll") for (int m = 0; m < 4; ++m) _Pragma("unroll") for (int n = 0; n < 2; ++n) _Pragma("unroll") for (int k = 0; k < 2; ++k) \
;         acc[ai][bj][m][n] = __builtin_amdgcn_mfma_f32_16x16x32_bf16(Bt[n][k], At[m][k], acc[ai][bj][m][n], 0, 0, 0); __builtin_amdgcn_s_setprio(0); } while (0)
; #define PG8_WAIT_V(n) asm volatile("s_waitcnt vmcnt(" #n ")" ::: "memory")
; #define PG8_WAIT_L(n) asm volatile("s_waitcnt lgkmcnt(" #n ")" ::: "memory")
; #define PG8_BAR __builtin_amdgcn_s_barrier()
; #define PG8_SCHED __builtin_amdgcn_sched_barrier(0)
; template <class Epi, class Sched, bool ALIGN_EPI = false, bool SP2 = false>
; __device__ __forceinline__ void gemm_phase(PG8_LAS unsigned char* lds, const Gemm g, const Sched& S, const Epi& E) {
;     ...
;             PG8_LDB(B0, 1, 0); PG8_LDB(B1, 1, 1); PG8_SCHED; PG8_LDA(At, 1, 0); PG8_STAGE(PG8_SA(0, 1), a2 + hstep, voffA);
;             PG8_WAIT_V(8); PG8_WAIT_L(0); PG8_BAR; PG8_MMA(0, 0, At, B0); PG8_MMA(0, 1, At, B1); PG8_BAR; PG8_SCHED;
;             PG8_LDA(At, 1, 1); PG8_STAGE(PG8_SB(1, 0), b3, voffB); PG8_STAGE(PG8_SB(1, 1), b3 + hstep, voffB); PG8_STAGE(PG8_SA(1, 0), a3, voffA);
;             PG8_WAIT_V(8); PG8_WAIT_L(0); PG8_BAR; PG8_MMA(1, 0, At, B0); PG8_MMA(1, 1, At, B1); PG8_BAR; PG8_SCHED;
;     ...
;         if constexpr (ALIGN_EPI) { if (wr == 0) PG8_BAR; }
	s_add_i32 s95, 0, 0x18000
	v_add_u32_e32 v87, s95, v85
	ds_read_b128 v[88:91], v87
	ds_read_b128 v[92:95], v87 offset:1024
	ds_read_b128 v[100:103], v87 offset:2048
	ds_read_b128 v[104:107], v87 offset:3072
	s_add_u32 s54, s54, 0x100000
	s_addc_u32 s55, s55, 0
	s_mov_b32 m0, s35
	v_lshl_add_u64 v[146:147], s[54:55], 0, v[66:67]
	ds_read_b128 v[108:111], v86 offset:32768
	ds_read_b128 v[112:115], v86 offset:33792
	ds_read_b128 v[116:119], v86 offset:34816
	ds_read_b128 v[120:123], v86 offset:35840
	ds_read_b128 v[124:127], v86 offset:36864
	ds_read_b128 v[128:131], v86 offset:37888
	ds_read_b128 v[132:135], v86 offset:38912
	ds_read_b128 v[136:139], v86 offset:39936
	global_load_lds_dwordx4 v[146:147], off
	v_lshl_add_u64 v[146:147], s[54:55], 0, v[76:77]
	s_mov_b32 m0, s88
	s_nop 0
	global_load_lds_dwordx4 v[146:147], off
	s_waitcnt vmcnt(8)
	s_waitcnt lgkmcnt(0)
	s_setprio 1
	s_barrier
	v_mfma_f32_16x16x32_bf16 v[62:65], v[88:91], v[108:111], v[62:65]
	v_mfma_f32_16x16x32_bf16 v[62:65], v[92:95], v[112:115], v[62:65]
	v_mfma_f32_16x16x32_bf16 v[58:61], v[104:107], v[112:115], v[58:61]
	v_mfma_f32_16x16x32_bf16 v[58:61], v[100:103], v[108:111], v[58:61]
	v_mfma_f32_16x16x32_bf16 v[50:53], v[100:103], v[116:119], v[50:53]
	v_mfma_f32_16x16x32_bf16 v[50:53], v[104:107], v[120:123], v[50:53]
	v_mfma_f32_16x16x32_bf16 v[54:57], v[92:95], v[120:123], v[54:57]
	v_mfma_f32_16x16x32_bf16 v[54:57], v[88:91], v[116:119], v[54:57]
	v_mfma_f32_16x16x32_bf16 v[46:49], v[88:91], v[124:127], v[46:49]
	v_mfma_f32_16x16x32_bf16 v[46:49], v[92:95], v[128:131], v[46:49]
	v_mfma_f32_16x16x32_bf16 v[42:45], v[104:107], v[128:131], v[42:45]
	v_mfma_f32_16x16x32_bf16 v[42:45], v[100:103], v[124:127], v[42:45]
	v_mfma_f32_16x16x32_bf16 v[34:37], v[100:103], v[132:135], v[34:37]
	v_mfma_f32_16x16x32_bf16 v[34:37], v[104:107], v[136:139], v[34:37]
	v_mfma_f32_16x16x32_bf16 v[38:41], v[92:95], v[136:139], v[38:41]
	v_mfma_f32_16x16x32_bf16 v[38:41], v[88:91], v[132:135], v[38:41]
	s_setprio 0
	s_setprio 1
	s_setprio 0
	s_barrier
	s_add_i32 s54, s95, s29
	v_lshl_add_u64 v[96:97], v[96:97], 0, s[14:15]
	s_mov_b32 m0, s54
	ds_read_b128 v[108:111], v86 offset:49152
	ds_read_b128 v[112:115], v86 offset:50176
	ds_read_b128 v[116:119], v86 offset:51200
	ds_read_b128 v[120:123], v86 offset:52224
	ds_read_b128 v[124:127], v86 offset:53248
	ds_read_b128 v[128:131], v86 offset:54272
	ds_read_b128 v[132:135], v86 offset:55296
	ds_read_b128 v[136:139], v86 offset:56320
	global_load_lds_dwordx4 v[96:97], off
	s_add_i32 m0, s54, 0x2000
	s_add_u32 s52, s52, 0x100080
	v_lshl_add_u64 v[96:97], v[140:141], 0, s[14:15]
	s_addc_u32 s53, s53, 0
	global_load_lds_dwordx4 v[96:97], off
	v_lshl_add_u64 v[96:97], s[52:53], 0, v[78:79]
	s_mov_b32 m0, s92
	s_nop 0
	global_load_lds_dwordx4 v[96:97], off
	v_lshl_add_u64 v[96:97], s[52:53], 0, v[74:75]
	s_mov_b32 m0, s93
	s_nop 0
	global_load_lds_dwordx4 v[96:97], off
	v_lshl_add_u64 v[96:97], v[142:143], 0, s[14:15]
	s_mov_b32 m0, s90
	s_nop 0
	global_load_lds_dwordx4 v[96:97], off
	v_lshl_add_u64 v[96:97], v[144:145], 0, s[14:15]
	s_mov_b32 m0, s91
	s_nop 0
	global_load_lds_dwordx4 v[96:97], off
	s_waitcnt vmcnt(8)
	s_waitcnt lgkmcnt(0)
	s_setprio 1
	s_barrier
	v_mfma_f32_16x16x32_bf16 v[30:33], v[88:91], v[108:111], v[30:33]
	v_mfma_f32_16x16x32_bf16 v[30:33], v[92:95], v[112:115], v[30:33]
	v_mfma_f32_16x16x32_bf16 v[26:29], v[104:107], v[112:115], v[26:29]
	v_mfma_f32_16x16x32_bf16 v[26:29], v[100:103], v[108:111], v[26:29]
	v_mfma_f32_16x16x32_bf16 v[18:21], v[100:103], v[116:119], v[18:21]
	v_mfma_f32_16x16x32_bf16 v[18:21], v[104:107], v[120:123], v[18:21]
	v_mfma_f32_16x16x32_bf16 v[22:25], v[92:95], v[120:123], v[22:25]
	v_mfma_f32_16x16x32_bf16 v[22:25], v[88:91], v[116:119], v[22:25]
	v_mfma_f32_16x16x32_bf16 v[14:17], v[88:91], v[124:127], v[14:17]
	v_mfma_f32_16x16x32_bf16 v[14:17], v[92:95], v[128:131], v[14:17]
	v_mfma_f32_16x16x32_bf16 v[10:13], v[104:107], v[128:131], v[10:13]
	v_mfma_f32_16x16x32_bf16 v[10:13], v[100:103], v[124:127], v[10:13]
	v_mfma_f32_16x16x32_bf16 v[2:5], v[100:103], v[132:135], v[2:5]
	v_mfma_f32_16x16x32_bf16 v[2:5], v[104:107], v[136:139], v[2:5]
	v_mfma_f32_16x16x32_bf16 v[6:9], v[92:95], v[136:139], v[6:9]
	v_mfma_f32_16x16x32_bf16 v[6:9], v[88:91], v[132:135], v[6:9]
	s_setprio 0
	s_setprio 1
	s_setprio 0
	s_barrier
	s_cmp_ge_u32 s10, s28
	s_mov_b32 s52, s10
	s_cbranch_scc0 .LBB0_592
	s_cmpk_lt_u32 s26, 0x100
	s_cbranch_scc0 .LBB0_482
	s_barrier
	s_branch .LBB0_482

; #define PG8_STAGE(bufoff, gbase, voff) do { _Pragma("unroll") for (int _i = 0; _i < 2; ++_i) \
;         __builtin_amdgcn_global_load_lds((const unsigned*)((const char*)(gbase) + (voff)[_i]), (PG8_LAS unsigned*)(lds + (bufoff) + ldsw + _i * 8192), 16, 0, 0); } while (0)
; #define PG8_LDA(dst, b, h) do { _Pragma("unroll") for (int m = 0; m < 4; ++m) _Pragma("unroll") for (int k = 0; k < 2; ++k) dst[m][k] = *(const PG8_LAS bf16x8*)(lds + PG8_SA(b, h) + aoff + m * 2048 + k * 1024); } while (0)
; #define PG8_LDB(dst, b, h) do { _Pragma("unroll") for (int n = 0; n < 2; ++n) _Pragma("unroll") for (int k = 0; k < 2; ++k) dst[n][k] = *(const PG8_LAS bf16x8*)(lds + PG8_SB(b, h) + boff + n * 2048 + k * 1024); } while (0)
; #define PG8_MMA(ai, bj, At, Bt) do { __builtin_amdgcn_s_setprio(1); _Pragma("unroll") for (int m = 0; m < 4; ++m) _Pragma("unroll") for (int n = 0; n < 2; ++n) _Pragma("unroll") for (int k = 0; k < 2; ++k) \
;         acc[ai][bj][m][n] = __builtin_amdgcn_mfma_f32_16x16x32_bf16(Bt[n][k], At[m][k], acc[ai][bj][m][n], 0, 0, 0); __builtin_amdgcn_s_setprio(0); } while (0)
; #define PG8_WAIT_V(n) asm volatile("s_waitcnt vmcnt(" #n ")" ::: "memory")
; #define PG8_WAIT_L(n) asm volatile("s_waitcnt lgkmcnt(" #n ")" ::: "memory")
; template <class Epi, class Sched, bool ALIGN_EPI = false, bool SP2 = false>
; __device__ __forceinline__ void gemm_phase(PG8_LAS unsigned char* lds, const Gemm g, const Sched& S, const Epi& E) {
;     ...
;             const bool last = (t == nt - 2);
;             const char* a1 = cA + (size_t)(t + 1) * kstep;
;             const char* a2 = last ? nA : cA + (size_t)(t + 2) * kstep; const char* b2 = last ? nB : cB + (size_t)(t + 2) * kstep;
;             const char* a3 = a2 + kstep; const char* b3 = b2 + kstep;
;             if (last && has_next) S.a_ready(nxt);
;             if constexpr (SP2) {
;             PG8_LDB(B0, 0, 0); PG8_LDB(B1, 0, 1); PG8_SCHED; PG8_LDA(At, 0, 0); PG8_STAGE(PG8_SA(1, 1), a1 + hstep, voffA);
;             PG8_WAIT_V(8); PG8_WAIT_L(0); PG8_BAR; PG8_MMA(0, 0, At, B0); PG8_MMA(0, 1, At, B1); PG8_BAR; PG8_SCHED;
;             PG8_LDA(At, 0, 1); PG8_STAGE(PG8_SB(0, 0), b2, voffB); PG8_STAGE(PG8_SB(0, 1), b2 + hstep, voffB); PG8_STAGE(PG8_SA(0, 0), a2, voffA);
;             PG8_WAIT_V(8); PG8_WAIT_L(0); PG8_BAR; PG8_MMA(1, 0, At, B0); PG8_MMA(1, 1, At, B1); PG8_BAR; PG8_SCHED;
.LBB0_1062:
	ds_read_b128 v[146:149], v155
	ds_read_b128 v[158:161], v155 offset:1024
	ds_read_b128 v[168:171], v155 offset:2048
	ds_read_b128 v[172:175], v155 offset:3072
	ds_read_b128 v[176:179], v156
	ds_read_b128 v[180:183], v156 offset:1024
	ds_read_b128 v[184:187], v156 offset:2048
	ds_read_b128 v[188:191], v156 offset:3072
	s_add_u32 s72, s70, 0xfff80080
	s_addc_u32 s73, s71, -1
	s_cmp_eq_u32 s77, 28
	s_cselect_b32 s75, s34, s73
	s_cselect_b32 s74, s35, s72
	s_cselect_b32 s73, s61, s76
	s_cselect_b32 s72, s63, s69
	v_lshl_add_u64 v[150:151], s[70:71], 0, v[138:139]
	s_add_i32 m0, s25, 0xc000
	ds_read_b128 v[200:203], v157
	ds_read_b128 v[204:207], v157 offset:1024
	ds_read_b128 v[208:211], v157 offset:2048
	ds_read_b128 v[212:215], v157 offset:3072
	ds_read_b128 v[216:219], v157 offset:4096
	ds_read_b128 v[220:223], v157 offset:5120
	ds_read_b128 v[224:227], v157 offset:6144
	ds_read_b128 v[228:231], v157 offset:7168
	global_load_lds_dwordx4 v[150:151], off
	v_lshl_add_u64 v[150:151], s[70:71], 0, v[140:141]
	s_add_i32 m0, s25, 0xe000
	s_nop 0
	global_load_lds_dwordx4 v[150:151], off
	s_waitcnt vmcnt(8)
	s_waitcnt lgkmcnt(0)
	s_setprio 1
	s_barrier
	v_mfma_f32_16x16x32_bf16 v[126:129], v[146:149], v[200:203], v[126:129]
	v_mfma_f32_16x16x32_bf16 v[126:129], v[158:161], v[204:207], v[126:129]
	v_mfma_f32_16x16x32_bf16 v[122:125], v[172:175], v[204:207], v[122:125]
	v_mfma_f32_16x16x32_bf16 v[122:125], v[168:171], v[200:203], v[122:125]
	v_mfma_f32_16x16x32_bf16 v[106:109], v[168:171], v[208:211], v[106:109]
	v_mfma_f32_16x16x32_bf16 v[106:109], v[172:175], v[212:215], v[106:109]
	v_mfma_f32_16x16x32_bf16 v[110:113], v[158:161], v[212:215], v[110:113]
	v_mfma_f32_16x16x32_bf16 v[110:113], v[146:149], v[208:211], v[110:113]
	v_mfma_f32_16x16x32_bf16 v[94:97], v[146:149], v[216:219], v[94:97]
	v_mfma_f32_16x16x32_bf16 v[94:97], v[158:161], v[220:223], v[94:97]
	v_mfma_f32_16x16x32_bf16 v[90:93], v[172:175], v[220:223], v[90:93]
	v_mfma_f32_16x16x32_bf16 v[90:93], v[168:171], v[216:219], v[90:93]
	v_mfma_f32_16x16x32_bf16 v[74:77], v[168:171], v[224:227], v[74:77]
	v_mfma_f32_16x16x32_bf16 v[74:77], v[172:175], v[228:231], v[74:77]
	v_mfma_f32_16x16x32_bf16 v[78:81], v[158:161], v[228:231], v[78:81]
	v_mfma_f32_16x16x32_bf16 v[78:81], v[146:149], v[224:227], v[78:81]
	s_setprio 0
	s_setprio 1
	v_mfma_f32_16x16x32_bf16 v[118:121], v[176:179], v[200:203], v[118:121]
	v_mfma_f32_16x16x32_bf16 v[118:121], v[180:183], v[204:207], v[118:121]
	v_mfma_f32_16x16x32_bf16 v[114:117], v[188:191], v[204:207], v[114:117]
	v_mfma_f32_16x16x32_bf16 v[114:117], v[184:187], v[200:203], v[114:117]
	v_mfma_f32_16x16x32_bf16 v[98:101], v[184:187], v[208:211], v[98:101]
	v_mfma_f32_16x16x32_bf16 v[98:101], v[188:191], v[212:215], v[98:101]
	v_mfma_f32_16x16x32_bf16 v[102:105], v[180:183], v[212:215], v[102:105]
	v_mfma_f32_16x16x32_bf16 v[102:105], v[176:179], v[208:211], v[102:105]
	v_mfma_f32_16x16x32_bf16 v[86:89], v[176:179], v[216:219], v[86:89]
	v_mfma_f32_16x16x32_bf16 v[86:89], v[180:183], v[220:223], v[86:89]
	v_mfma_f32_16x16x32_bf16 v[82:85], v[188:191], v[220:223], v[82:85]
	v_mfma_f32_16x16x32_bf16 v[82:85], v[184:187], v[216:219], v[82:85]
	v_mfma_f32_16x16x32_bf16 v[66:69], v[184:187], v[224:227], v[66:69]
	v_mfma_f32_16x16x32_bf16 v[66:69], v[188:191], v[228:231], v[66:69]
	v_mfma_f32_16x16x32_bf16 v[70:73], v[180:183], v[228:231], v[70:73]
	v_mfma_f32_16x16x32_bf16 v[70:73], v[176:179], v[224:227], v[70:73]
	s_barrier
	s_setprio 0
	s_add_i32 s78, s31, s2
	v_lshl_add_u64 v[150:151], s[72:73], 0, v[134:135]
	s_mov_b32 m0, s78
	ds_read_b128 v[200:203], v157 offset:16384
	ds_read_b128 v[204:207], v157 offset:17408
	ds_read_b128 v[208:211], v157 offset:18432
	ds_read_b128 v[212:215], v157 offset:19456
	ds_read_b128 v[216:219], v157 offset:20480
	ds_read_b128 v[220:223], v157 offset:21504
	ds_read_b128 v[224:227], v157 offset:22528
	ds_read_b128 v[228:231], v157 offset:23552
	global_load_lds_dwordx4 v[150:151], off
	s_add_i32 m0, s78, 0x2000
	s_add_u32 s78, s72, 0x80000
	v_lshl_add_u64 v[162:163], s[72:73], 0, v[130:131]
	s_addc_u32 s79, s73, 0
	s_add_i32 s80, s40, s2
	global_load_lds_dwordx4 v[162:163], off
	v_lshl_add_u64 v[192:193], s[78:79], 0, v[134:135]
	s_mov_b32 m0, s80
	v_lshl_add_u64 v[232:233], s[74:75], 0, v[132:133]
	global_load_lds_dwordx4 v[192:193], off
	v_lshl_add_u64 v[192:193], s[78:79], 0, v[130:131]
	s_add_i32 m0, s80, 0x2000
	s_nop 0
	global_load_lds_dwordx4 v[192:193], off
	v_lshl_add_u64 v[192:193], s[74:75], 0, v[136:137]
	s_mov_b32 m0, s25
	s_nop 0
	global_load_lds_dwordx4 v[192:193], off
	s_mov_b32 m0, s26
	s_nop 0
	global_load_lds_dwordx4 v[232:233], off
	s_waitcnt vmcnt(8)
	s_waitcnt lgkmcnt(0)
	s_setprio 1
	s_barrier
; #define PG8_STAGE(bufoff, gbase, voff) do { _Pragma("unroll") for (int _i = 0; _i < 2; ++_i) \
;         __builtin_amdgcn_global_load_lds((const unsigned*)((const char*)(gbase) + (voff)[_i]), (PG8_LAS unsigned*)(lds + (bufoff) + ldsw + _i * 8192), 16, 0, 0); } while (0)
; #define PG8_LDA(dst, b, h) do { _Pragma("unroll") for (int m = 0; m < 4; ++m) _Pragma("unroll") for (int k = 0; k < 2; ++k) dst[m][k] = *(const PG8_LAS bf16x8*)(lds + PG8_SA(b, h) + aoff + m * 2048 + k * 1024); } while (0)
; #define PG8_LDB(dst, b, h) do { _Pragma("unroll") for (int n = 0; n < 2; ++n) _Pragma("unroll") for (int k = 0; k < 2; ++k) dst[n][k] = *(const PG8_LAS bf16x8*)(lds + PG8_SB(b, h) + boff + n * 2048 + k * 1024); } while (0)
; #define PG8_MMA(ai, bj, At, Bt) do { __builtin_amdgcn_s_setprio(1); _Pragma("unroll") for (int m = 0; m < 4; ++m) _Pragma("unroll") for (int n = 0; n < 2; ++n) _Pragma("unroll") for (int k = 0; k < 2; ++k) \
;         acc[ai][bj][m][n] = __builtin_amdgcn_mfma_f32_16x16x32_bf16(Bt[n][k], At[m][k], acc[ai][bj][m][n], 0, 0, 0); __builtin_amdgcn_s_setprio(0); } while (0)
; #define PG8_WAIT_V(n) asm volatile("s_waitcnt vmcnt(" #n ")" ::: "memory")
; #define PG8_WAIT_L(n) asm volatile("s_waitcnt lgkmcnt(" #n ")" ::: "memory")
; #define PG8_BAR __builtin_amdgcn_s_barrier()
; #define PG8_SCHED __builtin_amdgcn_sched_barrier(0)
; template <class Epi, class Sched, bool ALIGN_EPI = false, bool SP2 = false>
; __device__ __forceinline__ void gemm_phase(PG8_LAS unsigned char* lds, const Gemm g, const Sched& S, const Epi& E) {
;     ...
;             PG8_WAIT_V(8); PG8_WAIT_L(0); PG8_BAR; PG8_MMA(1, 0, At, B0); PG8_MMA(1, 1, At, B1); PG8_BAR; PG8_SCHED;
;             PG8_LDB(B0, 1, 0); PG8_LDB(B1, 1, 1); PG8_SCHED; PG8_LDA(At, 1, 0); PG8_STAGE(PG8_SA(0, 1), a2 + hstep, voffA);
;             PG8_WAIT_V(8); PG8_WAIT_L(0); PG8_BAR; PG8_MMA(0, 0, At, B0); PG8_MMA(0, 1, At, B1); PG8_BAR; PG8_SCHED;
	v_mfma_f32_16x16x32_bf16 v[62:65], v[146:149], v[200:203], v[62:65]
	v_mfma_f32_16x16x32_bf16 v[62:65], v[158:161], v[204:207], v[62:65]
	v_mfma_f32_16x16x32_bf16 v[58:61], v[172:175], v[204:207], v[58:61]
	v_mfma_f32_16x16x32_bf16 v[58:61], v[168:171], v[200:203], v[58:61]
	v_mfma_f32_16x16x32_bf16 v[42:45], v[168:171], v[208:211], v[42:45]
	v_mfma_f32_16x16x32_bf16 v[42:45], v[172:175], v[212:215], v[42:45]
	v_mfma_f32_16x16x32_bf16 v[46:49], v[158:161], v[212:215], v[46:49]
	v_mfma_f32_16x16x32_bf16 v[46:49], v[146:149], v[208:211], v[46:49]
	v_mfma_f32_16x16x32_bf16 v[30:33], v[146:149], v[216:219], v[30:33]
	v_mfma_f32_16x16x32_bf16 v[30:33], v[158:161], v[220:223], v[30:33]
	v_mfma_f32_16x16x32_bf16 v[26:29], v[172:175], v[220:223], v[26:29]
	v_mfma_f32_16x16x32_bf16 v[26:29], v[168:171], v[216:219], v[26:29]
	v_mfma_f32_16x16x32_bf16 v[10:13], v[168:171], v[224:227], v[10:13]
	v_mfma_f32_16x16x32_bf16 v[10:13], v[172:175], v[228:231], v[10:13]
	v_mfma_f32_16x16x32_bf16 v[14:17], v[158:161], v[228:231], v[14:17]
	v_mfma_f32_16x16x32_bf16 v[14:17], v[146:149], v[224:227], v[14:17]
	s_setprio 0
	s_setprio 1
	v_mfma_f32_16x16x32_bf16 v[54:57], v[176:179], v[200:203], v[54:57]
	v_mfma_f32_16x16x32_bf16 v[54:57], v[180:183], v[204:207], v[54:57]
	v_mfma_f32_16x16x32_bf16 v[50:53], v[188:191], v[204:207], v[50:53]
	v_mfma_f32_16x16x32_bf16 v[50:53], v[184:187], v[200:203], v[50:53]
	v_mfma_f32_16x16x32_bf16 v[34:37], v[184:187], v[208:211], v[34:37]
	v_mfma_f32_16x16x32_bf16 v[34:37], v[188:191], v[212:215], v[34:37]
	v_mfma_f32_16x16x32_bf16 v[38:41], v[180:183], v[212:215], v[38:41]
	v_mfma_f32_16x16x32_bf16 v[38:41], v[176:179], v[208:211], v[38:41]
	v_mfma_f32_16x16x32_bf16 v[22:25], v[176:179], v[216:219], v[22:25]
	v_mfma_f32_16x16x32_bf16 v[22:25], v[180:183], v[220:223], v[22:25]
	v_mfma_f32_16x16x32_bf16 v[18:21], v[188:191], v[220:223], v[18:21]
	v_mfma_f32_16x16x32_bf16 v[18:21], v[184:187], v[216:219], v[18:21]
	v_mfma_f32_16x16x32_bf16 v[2:5], v[184:187], v[224:227], v[2:5]
	v_mfma_f32_16x16x32_bf16 v[2:5], v[188:191], v[228:231], v[2:5]
	v_mfma_f32_16x16x32_bf16 v[6:9], v[180:183], v[228:231], v[6:9]
	v_mfma_f32_16x16x32_bf16 v[6:9], v[176:179], v[224:227], v[6:9]
	s_barrier
	s_setprio 0
	s_add_i32 s78, 0, 0x18000
	v_add_u32_e32 v166, s78, v153
	s_add_i32 s79, 0, 0x1c000
	ds_read_b128 v[146:149], v166
	ds_read_b128 v[158:161], v166 offset:1024
	ds_read_b128 v[168:171], v166 offset:2048
	ds_read_b128 v[172:175], v166 offset:3072
	v_add_u32_e32 v166, s79, v153
	ds_read_b128 v[176:179], v166
	ds_read_b128 v[180:183], v166 offset:1024
	ds_read_b128 v[184:187], v166 offset:2048
	ds_read_b128 v[188:191], v166 offset:3072
	s_add_u32 s74, s74, 0x80000
	s_addc_u32 s75, s75, 0
	s_mov_b32 m0, s27
	v_lshl_add_u64 v[240:241], s[74:75], 0, v[136:137]
	ds_read_b128 v[200:203], v157 offset:32768
	ds_read_b128 v[204:207], v157 offset:33792
	ds_read_b128 v[208:211], v157 offset:34816
	ds_read_b128 v[212:215], v157 offset:35840
	ds_read_b128 v[216:219], v157 offset:36864
	ds_read_b128 v[220:223], v157 offset:37888
	ds_read_b128 v[224:227], v157 offset:38912
	ds_read_b128 v[228:231], v157 offset:39936
	global_load_lds_dwordx4 v[240:241], off
	v_lshl_add_u64 v[240:241], s[74:75], 0, v[132:133]
	s_mov_b32 m0, s28
	s_nop 0
	global_load_lds_dwordx4 v[240:241], off
	s_waitcnt vmcnt(8)
	s_waitcnt lgkmcnt(0)
	s_setprio 1
	s_barrier
	v_mfma_f32_16x16x32_bf16 v[126:129], v[146:149], v[200:203], v[126:129]
	v_mfma_f32_16x16x32_bf16 v[126:129], v[158:161], v[204:207], v[126:129]
	v_mfma_f32_16x16x32_bf16 v[122:125], v[172:175], v[204:207], v[122:125]
	v_mfma_f32_16x16x32_bf16 v[122:125], v[168:171], v[200:203], v[122:125]
	v_mfma_f32_16x16x32_bf16 v[106:109], v[168:171], v[208:211], v[106:109]
	v_mfma_f32_16x16x32_bf16 v[106:109], v[172:175], v[212:215], v[106:109]
	v_mfma_f32_16x16x32_bf16 v[110:113], v[158:161], v[212:215], v[110:113]
	v_mfma_f32_16x16x32_bf16 v[110:113], v[146:149], v[208:211], v[110:113]
	v_mfma_f32_16x16x32_bf16 v[94:97], v[146:149], v[216:219], v[94:97]
	v_mfma_f32_16x16x32_bf16 v[94:97], v[158:161], v[220:223], v[94:97]
	v_mfma_f32_16x16x32_bf16 v[90:93], v[172:175], v[220:223], v[90:93]
	v_mfma_f32_16x16x32_bf16 v[90:93], v[168:171], v[216:219], v[90:93]
	v_mfma_f32_16x16x32_bf16 v[74:77], v[168:171], v[224:227], v[74:77]
	v_mfma_f32_16x16x32_bf16 v[74:77], v[172:175], v[228:231], v[74:77]
	v_mfma_f32_16x16x32_bf16 v[78:81], v[158:161], v[228:231], v[78:81]
	v_mfma_f32_16x16x32_bf16 v[78:81], v[146:149], v[224:227], v[78:81]
	s_setprio 0
	s_setprio 1
	v_mfma_f32_16x16x32_bf16 v[118:121], v[176:179], v[200:203], v[118:121]
	v_mfma_f32_16x16x32_bf16 v[118:121], v[180:183], v[204:207], v[118:121]
	v_mfma_f32_16x16x32_bf16 v[114:117], v[188:191], v[204:207], v[114:117]
	v_mfma_f32_16x16x32_bf16 v[114:117], v[184:187], v[200:203], v[114:117]
	v_mfma_f32_16x16x32_bf16 v[98:101], v[184:187], v[208:211], v[98:101]
	v_mfma_f32_16x16x32_bf16 v[98:101], v[188:191], v[212:215], v[98:101]
	v_mfma_f32_16x16x32_bf16 v[102:105], v[180:183], v[212:215], v[102:105]
	v_mfma_f32_16x16x32_bf16 v[102:105], v[176:179], v[208:211], v[102:105]
	v_mfma_f32_16x16x32_bf16 v[86:89], v[176:179], v[216:219], v[86:89]
	v_mfma_f32_16x16x32_bf16 v[86:89], v[180:183], v[220:223], v[86:89]
	v_mfma_f32_16x16x32_bf16 v[82:85], v[188:191], v[220:223], v[82:85]
	v_mfma_f32_16x16x32_bf16 v[82:85], v[184:187], v[216:219], v[82:85]
	v_mfma_f32_16x16x32_bf16 v[66:69], v[184:187], v[224:227], v[66:69]
	v_mfma_f32_16x16x32_bf16 v[66:69], v[188:191], v[228:231], v[66:69]
	v_mfma_f32_16x16x32_bf16 v[70:73], v[180:183], v[228:231], v[70:73]
	v_mfma_f32_16x16x32_bf16 v[70:73], v[176:179], v[224:227], v[70:73]
	s_barrier
; #define PG8_STAGE(bufoff, gbase, voff) do { _Pragma("unroll") for (int _i = 0; _i < 2; ++_i) \
;         __builtin_amdgcn_global_load_lds((const unsigned*)((const char*)(gbase) + (voff)[_i]), (PG8_LAS unsigned*)(lds + (bufoff) + ldsw + _i * 8192), 16, 0, 0); } while (0)
; #define PG8_LDA(dst, b, h) do { _Pragma("unroll") for (int m = 0; m < 4; ++m) _Pragma("unroll") for (int k = 0; k < 2; ++k) dst[m][k] = *(const PG8_LAS bf16x8*)(lds + PG8_SA(b, h) + aoff + m * 2048 + k * 1024); } while (0)
; #define PG8_MMA(ai, bj, At, Bt) do { __builtin_amdgcn_s_setprio(1); _Pragma("unroll") for (int m = 0; m < 4; ++m) _Pragma("unroll") for (int n = 0; n < 2; ++n) _Pragma("unroll") for (int k = 0; k < 2; ++k) \
;         acc[ai][bj][m][n] = __builtin_amdgcn_mfma_f32_16x16x32_bf16(Bt[n][k], At[m][k], acc[ai][bj][m][n], 0, 0, 0); __builtin_amdgcn_s_setprio(0); } while (0)
; #define PG8_WAIT_V(n) asm volatile("s_waitcnt vmcnt(" #n ")" ::: "memory")
; #define PG8_WAIT_L(n) asm volatile("s_waitcnt lgkmcnt(" #n ")" ::: "memory")
; #define PG8_BAR __builtin_amdgcn_s_barrier()
; #define PG8_SCHED __builtin_amdgcn_sched_barrier(0)
; template <class Epi, class Sched, bool ALIGN_EPI = false, bool SP2 = false>
; __device__ __forceinline__ void gemm_phase(PG8_LAS unsigned char* lds, const Gemm g, const Sched& S, const Epi& E) {
;     ...
;             PG8_LDA(At, 1, 1); PG8_STAGE(PG8_SB(1, 0), b3, voffB); PG8_STAGE(PG8_SB(1, 1), b3 + hstep, voffB); PG8_STAGE(PG8_SA(1, 0), a3, voffA);
;             PG8_WAIT_V(8); PG8_WAIT_L(0); PG8_BAR; PG8_MMA(1, 0, At, B0); PG8_MMA(1, 1, At, B1); PG8_BAR; PG8_SCHED;
;     ...
;         if constexpr (ALIGN_EPI) { if (wr == 0) PG8_BAR; }
	s_setprio 0
	s_add_i32 s74, s78, s2
	v_lshl_add_u64 v[150:151], v[150:151], 0, s[10:11]
	s_mov_b32 m0, s74
	ds_read_b128 v[200:203], v157 offset:49152
	ds_read_b128 v[204:207], v157 offset:50176
	ds_read_b128 v[208:211], v157 offset:51200
	ds_read_b128 v[212:215], v157 offset:52224
	ds_read_b128 v[216:219], v157 offset:53248
	ds_read_b128 v[220:223], v157 offset:54272
	ds_read_b128 v[224:227], v157 offset:55296
	ds_read_b128 v[228:231], v157 offset:56320
	global_load_lds_dwordx4 v[150:151], off
	s_add_i32 m0, s74, 0x2000
	s_add_u32 s72, s72, 0x80080
	v_lshl_add_u64 v[150:151], v[162:163], 0, s[10:11]
	s_addc_u32 s73, s73, 0
	s_add_i32 s74, s79, s2
	global_load_lds_dwordx4 v[150:151], off
	v_lshl_add_u64 v[150:151], s[72:73], 0, v[134:135]
	s_mov_b32 m0, s74
	s_nop 0
	global_load_lds_dwordx4 v[150:151], off
	v_lshl_add_u64 v[150:151], s[72:73], 0, v[130:131]
	s_add_i32 m0, s74, 0x2000
	s_nop 0
	global_load_lds_dwordx4 v[150:151], off
	v_lshl_add_u64 v[150:151], v[192:193], 0, s[10:11]
	s_mov_b32 m0, s30
	s_nop 0
	global_load_lds_dwordx4 v[150:151], off
	v_lshl_add_u64 v[150:151], v[232:233], 0, s[10:11]
	s_mov_b32 m0, s33
	s_nop 0
	global_load_lds_dwordx4 v[150:151], off
	s_waitcnt vmcnt(8)
	s_waitcnt lgkmcnt(0)
	s_setprio 1
	s_barrier
	v_mfma_f32_16x16x32_bf16 v[62:65], v[146:149], v[200:203], v[62:65]
	v_mfma_f32_16x16x32_bf16 v[62:65], v[158:161], v[204:207], v[62:65]
	v_mfma_f32_16x16x32_bf16 v[58:61], v[172:175], v[204:207], v[58:61]
	v_mfma_f32_16x16x32_bf16 v[58:61], v[168:171], v[200:203], v[58:61]
	v_mfma_f32_16x16x32_bf16 v[42:45], v[168:171], v[208:211], v[42:45]
	v_mfma_f32_16x16x32_bf16 v[42:45], v[172:175], v[212:215], v[42:45]
	v_mfma_f32_16x16x32_bf16 v[46:49], v[158:161], v[212:215], v[46:49]
	v_mfma_f32_16x16x32_bf16 v[46:49], v[146:149], v[208:211], v[46:49]
	v_mfma_f32_16x16x32_bf16 v[30:33], v[146:149], v[216:219], v[30:33]
	v_mfma_f32_16x16x32_bf16 v[30:33], v[158:161], v[220:223], v[30:33]
	v_mfma_f32_16x16x32_bf16 v[26:29], v[172:175], v[220:223], v[26:29]
	v_mfma_f32_16x16x32_bf16 v[26:29], v[168:171], v[216:219], v[26:29]
	v_mfma_f32_16x16x32_bf16 v[10:13], v[168:171], v[224:227], v[10:13]
	v_mfma_f32_16x16x32_bf16 v[10:13], v[172:175], v[228:231], v[10:13]
	v_mfma_f32_16x16x32_bf16 v[14:17], v[158:161], v[228:231], v[14:17]
	v_mfma_f32_16x16x32_bf16 v[14:17], v[146:149], v[224:227], v[14:17]
	s_setprio 0
	s_setprio 1
	v_mfma_f32_16x16x32_bf16 v[54:57], v[176:179], v[200:203], v[54:57]
	v_mfma_f32_16x16x32_bf16 v[54:57], v[180:183], v[204:207], v[54:57]
	v_mfma_f32_16x16x32_bf16 v[50:53], v[188:191], v[204:207], v[50:53]
	v_mfma_f32_16x16x32_bf16 v[50:53], v[184:187], v[200:203], v[50:53]
	v_mfma_f32_16x16x32_bf16 v[34:37], v[184:187], v[208:211], v[34:37]
	v_mfma_f32_16x16x32_bf16 v[34:37], v[188:191], v[212:215], v[34:37]
	v_mfma_f32_16x16x32_bf16 v[38:41], v[180:183], v[212:215], v[38:41]
	v_mfma_f32_16x16x32_bf16 v[38:41], v[176:179], v[208:211], v[38:41]
	v_mfma_f32_16x16x32_bf16 v[22:25], v[176:179], v[216:219], v[22:25]
	v_mfma_f32_16x16x32_bf16 v[22:25], v[180:183], v[220:223], v[22:25]
	v_mfma_f32_16x16x32_bf16 v[18:21], v[188:191], v[220:223], v[18:21]
	v_mfma_f32_16x16x32_bf16 v[18:21], v[184:187], v[216:219], v[18:21]
	v_mfma_f32_16x16x32_bf16 v[2:5], v[184:187], v[224:227], v[2:5]
	v_mfma_f32_16x16x32_bf16 v[2:5], v[188:191], v[228:231], v[2:5]
	v_mfma_f32_16x16x32_bf16 v[6:9], v[180:183], v[228:231], v[6:9]
	v_mfma_f32_16x16x32_bf16 v[6:9], v[176:179], v[224:227], v[6:9]
	s_barrier
	s_setprio 0
	s_add_i32 s77, s77, 2
	s_add_u32 s70, s70, 0x100
	s_addc_u32 s71, s71, 0
	s_add_u32 s69, s69, 0x100
	s_addc_u32 s76, s76, 0
	s_cmp_gt_u32 s77, 29
	s_cbranch_scc0 .LBB0_1062
	s_and_b64 vcc, exec, s[48:49]
	s_cbranch_vccz .LBB0_1065
	s_barrier

; #define PG8_STAGE(bufoff, gbase, voff) do { _Pragma("unroll") for (int _i = 0; _i < 2; ++_i) \
;         __builtin_amdgcn_global_load_lds((const unsigned*)((const char*)(gbase) + (voff)[_i]), (PG8_LAS unsigned*)(lds + (bufoff) + ldsw + _i * 8192), 16, 0, 0); } while (0)
; #define PG8_LDA(dst, b, h) do { _Pragma("unroll") for (int m = 0; m < 4; ++m) _Pragma("unroll") for (int k = 0; k < 2; ++k) dst[m][k] = *(const PG8_LAS bf16x8*)(lds + PG8_SA(b, h) + aoff + m * 2048 + k * 1024); } while (0)
; #define PG8_LDB(dst, b, h) do { _Pragma("unroll") for (int n = 0; n < 2; ++n) _Pragma("unroll") for (int k = 0; k < 2; ++k) dst[n][k] = *(const PG8_LAS bf16x8*)(lds + PG8_SB(b, h) + boff + n * 2048 + k * 1024); } while (0)
; #define PG8_MMA(ai, bj, At, Bt) do { __builtin_amdgcn_s_setprio(1); _Pragma("unroll") for (int m = 0; m < 4; ++m) _Pragma("unroll") for (int n = 0; n < 2; ++n) _Pragma("unroll") for (int k = 0; k < 2; ++k) \
;         acc[ai][bj][m][n] = __builtin_amdgcn_mfma_f32_16x16x32_bf16(Bt[n][k], At[m][k], acc[ai][bj][m][n], 0, 0, 0); __builtin_amdgcn_s_setprio(0); } while (0)
; #define PG8_WAIT_V(n) asm volatile("s_waitcnt vmcnt(" #n ")" ::: "memory")
; #define PG8_WAIT_L(n) asm volatile("s_waitcnt lgkmcnt(" #n ")" ::: "memory")
; template <class Epi, class Sched, bool ALIGN_EPI = false, bool SP2 = false>
; __device__ __forceinline__ void gemm_phase(PG8_LAS unsigned char* lds, const Gemm g, const Sched& S, const Epi& E) {
;     ...
;             const bool last = (t == nt - 2);
;             const char* a1 = cA + (size_t)(t + 1) * kstep;
;             const char* a2 = last ? nA : cA + (size_t)(t + 2) * kstep; const char* b2 = last ? nB : cB + (size_t)(t + 2) * kstep;
;             const char* a3 = a2 + kstep; const char* b3 = b2 + kstep;
;             if (last && has_next) S.a_ready(nxt);
;             if constexpr (SP2) {
;             PG8_LDB(B0, 0, 0); PG8_LDB(B1, 0, 1); PG8_SCHED; PG8_LDA(At, 0, 0); PG8_STAGE(PG8_SA(1, 1), a1 + hstep, voffA);
;             PG8_WAIT_V(8); PG8_WAIT_L(0); PG8_BAR; PG8_MMA(0, 0, At, B0); PG8_MMA(0, 1, At, B1); PG8_BAR; PG8_SCHED;
;             PG8_LDA(At, 0, 1); PG8_STAGE(PG8_SB(0, 0), b2, voffB); PG8_STAGE(PG8_SB(0, 1), b2 + hstep, voffB); PG8_STAGE(PG8_SA(0, 0), a2, voffA);
;             PG8_WAIT_V(8); PG8_WAIT_L(0); PG8_BAR; PG8_MMA(1, 0, At, B0); PG8_MMA(1, 1, At, B1); PG8_BAR; PG8_SCHED;
.LBB0_1078:
	ds_read_b128 v[146:149], v155
	ds_read_b128 v[158:161], v155 offset:1024
	ds_read_b128 v[168:171], v155 offset:2048
	ds_read_b128 v[172:175], v155 offset:3072
	ds_read_b128 v[176:179], v156
	ds_read_b128 v[180:183], v156 offset:1024
	ds_read_b128 v[184:187], v156 offset:2048
	ds_read_b128 v[188:191], v156 offset:3072
	s_add_u32 s68, s66, 0xfff80080
	s_addc_u32 s69, s67, -1
	s_cmp_eq_u32 s73, 28
	s_cselect_b32 s71, s34, s69
	s_cselect_b32 s70, s35, s68
	s_cselect_b32 s69, s57, s72
	s_cselect_b32 s68, s59, s65
	v_lshl_add_u64 v[150:151], s[66:67], 0, v[138:139]
	s_add_i32 m0, s25, 0xc000
	ds_read_b128 v[200:203], v157
	ds_read_b128 v[204:207], v157 offset:1024
	ds_read_b128 v[208:211], v157 offset:2048
	ds_read_b128 v[212:215], v157 offset:3072
	ds_read_b128 v[216:219], v157 offset:4096
	ds_read_b128 v[220:223], v157 offset:5120
	ds_read_b128 v[224:227], v157 offset:6144
	ds_read_b128 v[228:231], v157 offset:7168
	global_load_lds_dwordx4 v[150:151], off
	v_lshl_add_u64 v[150:151], s[66:67], 0, v[140:141]
	s_add_i32 m0, s25, 0xe000
	s_nop 0
	global_load_lds_dwordx4 v[150:151], off
	s_waitcnt vmcnt(8)
	s_waitcnt lgkmcnt(0)
	s_setprio 1
	s_barrier
	v_mfma_f32_16x16x32_bf16 v[126:129], v[146:149], v[200:203], v[126:129]
	v_mfma_f32_16x16x32_bf16 v[126:129], v[158:161], v[204:207], v[126:129]
	v_mfma_f32_16x16x32_bf16 v[122:125], v[172:175], v[204:207], v[122:125]
	v_mfma_f32_16x16x32_bf16 v[122:125], v[168:171], v[200:203], v[122:125]
	v_mfma_f32_16x16x32_bf16 v[106:109], v[168:171], v[208:211], v[106:109]
	v_mfma_f32_16x16x32_bf16 v[106:109], v[172:175], v[212:215], v[106:109]
	v_mfma_f32_16x16x32_bf16 v[110:113], v[158:161], v[212:215], v[110:113]
	v_mfma_f32_16x16x32_bf16 v[110:113], v[146:149], v[208:211], v[110:113]
	v_mfma_f32_16x16x32_bf16 v[94:97], v[146:149], v[216:219], v[94:97]
	v_mfma_f32_16x16x32_bf16 v[94:97], v[158:161], v[220:223], v[94:97]
	v_mfma_f32_16x16x32_bf16 v[90:93], v[172:175], v[220:223], v[90:93]
	v_mfma_f32_16x16x32_bf16 v[90:93], v[168:171], v[216:219], v[90:93]
	v_mfma_f32_16x16x32_bf16 v[74:77], v[168:171], v[224:227], v[74:77]
	v_mfma_f32_16x16x32_bf16 v[74:77], v[172:175], v[228:231], v[74:77]
	v_mfma_f32_16x16x32_bf16 v[78:81], v[158:161], v[228:231], v[78:81]
	v_mfma_f32_16x16x32_bf16 v[78:81], v[146:149], v[224:227], v[78:81]
	s_setprio 0
	s_setprio 1
	v_mfma_f32_16x16x32_bf16 v[118:121], v[176:179], v[200:203], v[118:121]
	v_mfma_f32_16x16x32_bf16 v[118:121], v[180:183], v[204:207], v[118:121]
	v_mfma_f32_16x16x32_bf16 v[114:117], v[188:191], v[204:207], v[114:117]
	v_mfma_f32_16x16x32_bf16 v[114:117], v[184:187], v[200:203], v[114:117]
	v_mfma_f32_16x16x32_bf16 v[98:101], v[184:187], v[208:211], v[98:101]
	v_mfma_f32_16x16x32_bf16 v[98:101], v[188:191], v[212:215], v[98:101]
	v_mfma_f32_16x16x32_bf16 v[102:105], v[180:183], v[212:215], v[102:105]
	v_mfma_f32_16x16x32_bf16 v[102:105], v[176:179], v[208:211], v[102:105]
	v_mfma_f32_16x16x32_bf16 v[86:89], v[176:179], v[216:219], v[86:89]
	v_mfma_f32_16x16x32_bf16 v[86:89], v[180:183], v[220:223], v[86:89]
	v_mfma_f32_16x16x32_bf16 v[82:85], v[188:191], v[220:223], v[82:85]
	v_mfma_f32_16x16x32_bf16 v[82:85], v[184:187], v[216:219], v[82:85]
	v_mfma_f32_16x16x32_bf16 v[66:69], v[184:187], v[224:227], v[66:69]
	v_mfma_f32_16x16x32_bf16 v[66:69], v[188:191], v[228:231], v[66:69]
	v_mfma_f32_16x16x32_bf16 v[70:73], v[180:183], v[228:231], v[70:73]
	v_mfma_f32_16x16x32_bf16 v[70:73], v[176:179], v[224:227], v[70:73]
	s_barrier
	s_setprio 0
	s_add_i32 s74, s31, s2
	v_lshl_add_u64 v[150:151], s[68:69], 0, v[134:135]
	s_mov_b32 m0, s74
	ds_read_b128 v[200:203], v157 offset:16384
	ds_read_b128 v[204:207], v157 offset:17408
	ds_read_b128 v[208:211], v157 offset:18432
	ds_read_b128 v[212:215], v157 offset:19456
	ds_read_b128 v[216:219], v157 offset:20480
	ds_read_b128 v[220:223], v157 offset:21504
	ds_read_b128 v[224:227], v157 offset:22528
	ds_read_b128 v[228:231], v157 offset:23552
	global_load_lds_dwordx4 v[150:151], off
	s_add_i32 m0, s74, 0x2000
	s_add_u32 s74, s68, 0x80000
	v_lshl_add_u64 v[162:163], s[68:69], 0, v[130:131]
	s_addc_u32 s75, s69, 0
	s_add_i32 s76, s40, s2
	global_load_lds_dwordx4 v[162:163], off
	v_lshl_add_u64 v[192:193], s[74:75], 0, v[134:135]
	s_mov_b32 m0, s76
	v_lshl_add_u64 v[232:233], s[70:71], 0, v[132:133]
	global_load_lds_dwordx4 v[192:193], off
	v_lshl_add_u64 v[192:193], s[74:75], 0, v[130:131]
	s_add_i32 m0, s76, 0x2000
	s_nop 0
	global_load_lds_dwordx4 v[192:193], off
	v_lshl_add_u64 v[192:193], s[70:71], 0, v[136:137]
	s_mov_b32 m0, s25
	s_nop 0
	global_load_lds_dwordx4 v[192:193], off
	s_mov_b32 m0, s26
	s_nop 0
	global_load_lds_dwordx4 v[232:233], off
	s_waitcnt vmcnt(8)
	s_waitcnt lgkmcnt(0)
	s_setprio 1
	s_barrier
; #define PG8_STAGE(bufoff, gbase, voff) do { _Pragma("unroll") for (int _i = 0; _i < 2; ++_i) \
;         __builtin_amdgcn_global_load_lds((const unsigned*)((const char*)(gbase) + (voff)[_i]), (PG8_LAS unsigned*)(lds + (bufoff) + ldsw + _i * 8192), 16, 0, 0); } while (0)
; #define PG8_LDA(dst, b, h) do { _Pragma("unroll") for (int m = 0; m < 4; ++m) _Pragma("unroll") for (int k = 0; k < 2; ++k) dst[m][k] = *(const PG8_LAS bf16x8*)(lds + PG8_SA(b, h) + aoff + m * 2048 + k * 1024); } while (0)
; #define PG8_LDB(dst, b, h) do { _Pragma("unroll") for (int n = 0; n < 2; ++n) _Pragma("unroll") for (int k = 0; k < 2; ++k) dst[n][k] = *(const PG8_LAS bf16x8*)(lds + PG8_SB(b, h) + boff + n * 2048 + k * 1024); } while (0)
; #define PG8_MMA(ai, bj, At, Bt) do { __builtin_amdgcn_s_setprio(1); _Pragma("unroll") for (int m = 0; m < 4; ++m) _Pragma("unroll") for (int n = 0; n < 2; ++n) _Pragma("unroll") for (int k = 0; k < 2; ++k) \
;         acc[ai][bj][m][n] = __builtin_amdgcn_mfma_f32_16x16x32_bf16(Bt[n][k], At[m][k], acc[ai][bj][m][n], 0, 0, 0); __builtin_amdgcn_s_setprio(0); } while (0)
; #define PG8_WAIT_V(n) asm volatile("s_waitcnt vmcnt(" #n ")" ::: "memory")
; #define PG8_WAIT_L(n) asm volatile("s_waitcnt lgkmcnt(" #n ")" ::: "memory")
; #define PG8_BAR __builtin_amdgcn_s_barrier()
; #define PG8_SCHED __builtin_amdgcn_sched_barrier(0)
; template <class Epi, class Sched, bool ALIGN_EPI = false, bool SP2 = false>
; __device__ __forceinline__ void gemm_phase(PG8_LAS unsigned char* lds, const Gemm g, const Sched& S, const Epi& E) {
;     ...
;             PG8_WAIT_V(8); PG8_WAIT_L(0); PG8_BAR; PG8_MMA(1, 0, At, B0); PG8_MMA(1, 1, At, B1); PG8_BAR; PG8_SCHED;
;             PG8_LDB(B0, 1, 0); PG8_LDB(B1, 1, 1); PG8_SCHED; PG8_LDA(At, 1, 0); PG8_STAGE(PG8_SA(0, 1), a2 + hstep, voffA);
;             PG8_WAIT_V(8); PG8_WAIT_L(0); PG8_BAR; PG8_MMA(0, 0, At, B0); PG8_MMA(0, 1, At, B1); PG8_BAR; PG8_SCHED;
	v_mfma_f32_16x16x32_bf16 v[62:65], v[146:149], v[200:203], v[62:65]
	v_mfma_f32_16x16x32_bf16 v[62:65], v[158:161], v[204:207], v[62:65]
	v_mfma_f32_16x16x32_bf16 v[58:61], v[172:175], v[204:207], v[58:61]
	v_mfma_f32_16x16x32_bf16 v[58:61], v[168:171], v[200:203], v[58:61]
	v_mfma_f32_16x16x32_bf16 v[42:45], v[168:171], v[208:211], v[42:45]
	v_mfma_f32_16x16x32_bf16 v[42:45], v[172:175], v[212:215], v[42:45]
	v_mfma_f32_16x16x32_bf16 v[46:49], v[158:161], v[212:215], v[46:49]
	v_mfma_f32_16x16x32_bf16 v[46:49], v[146:149], v[208:211], v[46:49]
	v_mfma_f32_16x16x32_bf16 v[30:33], v[146:149], v[216:219], v[30:33]
	v_mfma_f32_16x16x32_bf16 v[30:33], v[158:161], v[220:223], v[30:33]
	v_mfma_f32_16x16x32_bf16 v[26:29], v[172:175], v[220:223], v[26:29]
	v_mfma_f32_16x16x32_bf16 v[26:29], v[168:171], v[216:219], v[26:29]
	v_mfma_f32_16x16x32_bf16 v[10:13], v[168:171], v[224:227], v[10:13]
	v_mfma_f32_16x16x32_bf16 v[10:13], v[172:175], v[228:231], v[10:13]
	v_mfma_f32_16x16x32_bf16 v[14:17], v[158:161], v[228:231], v[14:17]
	v_mfma_f32_16x16x32_bf16 v[14:17], v[146:149], v[224:227], v[14:17]
	s_setprio 0
	s_setprio 1
	v_mfma_f32_16x16x32_bf16 v[54:57], v[176:179], v[200:203], v[54:57]
	v_mfma_f32_16x16x32_bf16 v[54:57], v[180:183], v[204:207], v[54:57]
	v_mfma_f32_16x16x32_bf16 v[50:53], v[188:191], v[204:207], v[50:53]
	v_mfma_f32_16x16x32_bf16 v[50:53], v[184:187], v[200:203], v[50:53]
	v_mfma_f32_16x16x32_bf16 v[34:37], v[184:187], v[208:211], v[34:37]
	v_mfma_f32_16x16x32_bf16 v[34:37], v[188:191], v[212:215], v[34:37]
	v_mfma_f32_16x16x32_bf16 v[38:41], v[180:183], v[212:215], v[38:41]
	v_mfma_f32_16x16x32_bf16 v[38:41], v[176:179], v[208:211], v[38:41]
	v_mfma_f32_16x16x32_bf16 v[22:25], v[176:179], v[216:219], v[22:25]
	v_mfma_f32_16x16x32_bf16 v[22:25], v[180:183], v[220:223], v[22:25]
	v_mfma_f32_16x16x32_bf16 v[18:21], v[188:191], v[220:223], v[18:21]
	v_mfma_f32_16x16x32_bf16 v[18:21], v[184:187], v[216:219], v[18:21]
	v_mfma_f32_16x16x32_bf16 v[2:5], v[184:187], v[224:227], v[2:5]
	v_mfma_f32_16x16x32_bf16 v[2:5], v[188:191], v[228:231], v[2:5]
	v_mfma_f32_16x16x32_bf16 v[6:9], v[180:183], v[228:231], v[6:9]
	v_mfma_f32_16x16x32_bf16 v[6:9], v[176:179], v[224:227], v[6:9]
	s_barrier
	s_setprio 0
	s_add_i32 s74, 0, 0x18000
	v_add_u32_e32 v166, s74, v153
	s_add_i32 s75, 0, 0x1c000
	ds_read_b128 v[146:149], v166
	ds_read_b128 v[158:161], v166 offset:1024
	ds_read_b128 v[168:171], v166 offset:2048
	ds_read_b128 v[172:175], v166 offset:3072
	v_add_u32_e32 v166, s75, v153
	ds_read_b128 v[176:179], v166
	ds_read_b128 v[180:183], v166 offset:1024
	ds_read_b128 v[184:187], v166 offset:2048
	ds_read_b128 v[188:191], v166 offset:3072
	s_add_u32 s70, s70, 0x80000
	s_addc_u32 s71, s71, 0
	s_mov_b32 m0, s27
	v_lshl_add_u64 v[240:241], s[70:71], 0, v[136:137]
	ds_read_b128 v[200:203], v157 offset:32768
	ds_read_b128 v[204:207], v157 offset:33792
	ds_read_b128 v[208:211], v157 offset:34816
	ds_read_b128 v[212:215], v157 offset:35840
	ds_read_b128 v[216:219], v157 offset:36864
	ds_read_b128 v[220:223], v157 offset:37888
	ds_read_b128 v[224:227], v157 offset:38912
	ds_read_b128 v[228:231], v157 offset:39936
	global_load_lds_dwordx4 v[240:241], off
	v_lshl_add_u64 v[240:241], s[70:71], 0, v[132:133]
	s_mov_b32 m0, s28
	s_nop 0
	global_load_lds_dwordx4 v[240:241], off
	s_waitcnt vmcnt(8)
	s_waitcnt lgkmcnt(0)
	s_setprio 1
	s_barrier
	v_mfma_f32_16x16x32_bf16 v[126:129], v[146:149], v[200:203], v[126:129]
	v_mfma_f32_16x16x32_bf16 v[126:129], v[158:161], v[204:207], v[126:129]
	v_mfma_f32_16x16x32_bf16 v[122:125], v[172:175], v[204:207], v[122:125]
	v_mfma_f32_16x16x32_bf16 v[122:125], v[168:171], v[200:203], v[122:125]
	v_mfma_f32_16x16x32_bf16 v[106:109], v[168:171], v[208:211], v[106:109]
	v_mfma_f32_16x16x32_bf16 v[106:109], v[172:175], v[212:215], v[106:109]
	v_mfma_f32_16x16x32_bf16 v[110:113], v[158:161], v[212:215], v[110:113]
	v_mfma_f32_16x16x32_bf16 v[110:113], v[146:149], v[208:211], v[110:113]
	v_mfma_f32_16x16x32_bf16 v[94:97], v[146:149], v[216:219], v[94:97]
	v_mfma_f32_16x16x32_bf16 v[94:97], v[158:161], v[220:223], v[94:97]
	v_mfma_f32_16x16x32_bf16 v[90:93], v[172:175], v[220:223], v[90:93]
	v_mfma_f32_16x16x32_bf16 v[90:93], v[168:171], v[216:219], v[90:93]
	v_mfma_f32_16x16x32_bf16 v[74:77], v[168:171], v[224:227], v[74:77]
	v_mfma_f32_16x16x32_bf16 v[74:77], v[172:175], v[228:231], v[74:77]
	v_mfma_f32_16x16x32_bf16 v[78:81], v[158:161], v[228:231], v[78:81]
	v_mfma_f32_16x16x32_bf16 v[78:81], v[146:149], v[224:227], v[78:81]
	s_setprio 0
	s_setprio 1
	v_mfma_f32_16x16x32_bf16 v[118:121], v[176:179], v[200:203], v[118:121]
	v_mfma_f32_16x16x32_bf16 v[118:121], v[180:183], v[204:207], v[118:121]
	v_mfma_f32_16x16x32_bf16 v[114:117], v[188:191], v[204:207], v[114:117]
	v_mfma_f32_16x16x32_bf16 v[114:117], v[184:187], v[200:203], v[114:117]
	v_mfma_f32_16x16x32_bf16 v[98:101], v[184:187], v[208:211], v[98:101]
	v_mfma_f32_16x16x32_bf16 v[98:101], v[188:191], v[212:215], v[98:101]
	v_mfma_f32_16x16x32_bf16 v[102:105], v[180:183], v[212:215], v[102:105]
	v_mfma_f32_16x16x32_bf16 v[102:105], v[176:179], v[208:211], v[102:105]
	v_mfma_f32_16x16x32_bf16 v[86:89], v[176:179], v[216:219], v[86:89]
	v_mfma_f32_16x16x32_bf16 v[86:89], v[180:183], v[220:223], v[86:89]
	v_mfma_f32_16x16x32_bf16 v[82:85], v[188:191], v[220:223], v[82:85]
	v_mfma_f32_16x16x32_bf16 v[82:85], v[184:187], v[216:219], v[82:85]
	v_mfma_f32_16x16x32_bf16 v[66:69], v[184:187], v[224:227], v[66:69]
	v_mfma_f32_16x16x32_bf16 v[66:69], v[188:191], v[228:231], v[66:69]
	v_mfma_f32_16x16x32_bf16 v[70:73], v[180:183], v[228:231], v[70:73]
	v_mfma_f32_16x16x32_bf16 v[70:73], v[176:179], v[224:227], v[70:73]
	s_barrier
; #define PG8_STAGE(bufoff, gbase, voff) do { _Pragma("unroll") for (int _i = 0; _i < 2; ++_i) \
;         __builtin_amdgcn_global_load_lds((const unsigned*)((const char*)(gbase) + (voff)[_i]), (PG8_LAS unsigned*)(lds + (bufoff) + ldsw + _i * 8192), 16, 0, 0); } while (0)
; #define PG8_LDA(dst, b, h) do { _Pragma("unroll") for (int m = 0; m < 4; ++m) _Pragma("unroll") for (int k = 0; k < 2; ++k) dst[m][k] = *(const PG8_LAS bf16x8*)(lds + PG8_SA(b, h) + aoff + m * 2048 + k * 1024); } while (0)
; #define PG8_MMA(ai, bj, At, Bt) do { __builtin_amdgcn_s_setprio(1); _Pragma("unroll") for (int m = 0; m < 4; ++m) _Pragma("unroll") for (int n = 0; n < 2; ++n) _Pragma("unroll") for (int k = 0; k < 2; ++k) \
;         acc[ai][bj][m][n] = __builtin_amdgcn_mfma_f32_16x16x32_bf16(Bt[n][k], At[m][k], acc[ai][bj][m][n], 0, 0, 0); __builtin_amdgcn_s_setprio(0); } while (0)
; #define PG8_WAIT_V(n) asm volatile("s_waitcnt vmcnt(" #n ")" ::: "memory")
; #define PG8_WAIT_L(n) asm volatile("s_waitcnt lgkmcnt(" #n ")" ::: "memory")
; #define PG8_BAR __builtin_amdgcn_s_barrier()
; #define PG8_SCHED __builtin_amdgcn_sched_barrier(0)
; template <class Epi, class Sched, bool ALIGN_EPI = false, bool SP2 = false>
; __device__ __forceinline__ void gemm_phase(PG8_LAS unsigned char* lds, const Gemm g, const Sched& S, const Epi& E) {
;     ...
;             PG8_LDA(At, 1, 1); PG8_STAGE(PG8_SB(1, 0), b3, voffB); PG8_STAGE(PG8_SB(1, 1), b3 + hstep, voffB); PG8_STAGE(PG8_SA(1, 0), a3, voffA);
;             PG8_WAIT_V(8); PG8_WAIT_L(0); PG8_BAR; PG8_MMA(1, 0, At, B0); PG8_MMA(1, 1, At, B1); PG8_BAR; PG8_SCHED;
;     ...
;         if constexpr (ALIGN_EPI) { if (wr == 0) PG8_BAR; }
	s_setprio 0
	s_add_i32 s70, s74, s2
	v_lshl_add_u64 v[150:151], v[150:151], 0, s[8:9]
	s_mov_b32 m0, s70
	ds_read_b128 v[200:203], v157 offset:49152
	ds_read_b128 v[204:207], v157 offset:50176
	ds_read_b128 v[208:211], v157 offset:51200
	ds_read_b128 v[212:215], v157 offset:52224
	ds_read_b128 v[216:219], v157 offset:53248
	ds_read_b128 v[220:223], v157 offset:54272
	ds_read_b128 v[224:227], v157 offset:55296
	ds_read_b128 v[228:231], v157 offset:56320
	global_load_lds_dwordx4 v[150:151], off
	s_add_i32 m0, s70, 0x2000
	s_add_u32 s68, s68, 0x80080
	v_lshl_add_u64 v[150:151], v[162:163], 0, s[8:9]
	s_addc_u32 s69, s69, 0
	s_add_i32 s70, s75, s2
	global_load_lds_dwordx4 v[150:151], off
	v_lshl_add_u64 v[150:151], s[68:69], 0, v[134:135]
	s_mov_b32 m0, s70
	s_nop 0
	global_load_lds_dwordx4 v[150:151], off
	v_lshl_add_u64 v[150:151], s[68:69], 0, v[130:131]
	s_add_i32 m0, s70, 0x2000
	s_nop 0
	global_load_lds_dwordx4 v[150:151], off
	v_lshl_add_u64 v[150:151], v[192:193], 0, s[8:9]
	s_mov_b32 m0, s30
	s_nop 0
	global_load_lds_dwordx4 v[150:151], off
	v_lshl_add_u64 v[150:151], v[232:233], 0, s[8:9]
	s_mov_b32 m0, s33
	s_nop 0
	global_load_lds_dwordx4 v[150:151], off
	s_waitcnt vmcnt(8)
	s_waitcnt lgkmcnt(0)
	s_setprio 1
	s_barrier
	v_mfma_f32_16x16x32_bf16 v[62:65], v[146:149], v[200:203], v[62:65]
	v_mfma_f32_16x16x32_bf16 v[62:65], v[158:161], v[204:207], v[62:65]
	v_mfma_f32_16x16x32_bf16 v[58:61], v[172:175], v[204:207], v[58:61]
	v_mfma_f32_16x16x32_bf16 v[58:61], v[168:171], v[200:203], v[58:61]
	v_mfma_f32_16x16x32_bf16 v[42:45], v[168:171], v[208:211], v[42:45]
	v_mfma_f32_16x16x32_bf16 v[42:45], v[172:175], v[212:215], v[42:45]
	v_mfma_f32_16x16x32_bf16 v[46:49], v[158:161], v[212:215], v[46:49]
	v_mfma_f32_16x16x32_bf16 v[46:49], v[146:149], v[208:211], v[46:49]
	v_mfma_f32_16x16x32_bf16 v[30:33], v[146:149], v[216:219], v[30:33]
	v_mfma_f32_16x16x32_bf16 v[30:33], v[158:161], v[220:223], v[30:33]
	v_mfma_f32_16x16x32_bf16 v[26:29], v[172:175], v[220:223], v[26:29]
	v_mfma_f32_16x16x32_bf16 v[26:29], v[168:171], v[216:219], v[26:29]
	v_mfma_f32_16x16x32_bf16 v[10:13], v[168:171], v[224:227], v[10:13]
	v_mfma_f32_16x16x32_bf16 v[10:13], v[172:175], v[228:231], v[10:13]
	v_mfma_f32_16x16x32_bf16 v[14:17], v[158:161], v[228:231], v[14:17]
	v_mfma_f32_16x16x32_bf16 v[14:17], v[146:149], v[224:227], v[14:17]
	s_setprio 0
	s_setprio 1
	v_mfma_f32_16x16x32_bf16 v[54:57], v[176:179], v[200:203], v[54:57]
	v_mfma_f32_16x16x32_bf16 v[54:57], v[180:183], v[204:207], v[54:57]
	v_mfma_f32_16x16x32_bf16 v[50:53], v[188:191], v[204:207], v[50:53]
	v_mfma_f32_16x16x32_bf16 v[50:53], v[184:187], v[200:203], v[50:53]
	v_mfma_f32_16x16x32_bf16 v[34:37], v[184:187], v[208:211], v[34:37]
	v_mfma_f32_16x16x32_bf16 v[34:37], v[188:191], v[212:215], v[34:37]
	v_mfma_f32_16x16x32_bf16 v[38:41], v[180:183], v[212:215], v[38:41]
	v_mfma_f32_16x16x32_bf16 v[38:41], v[176:179], v[208:211], v[38:41]
	v_mfma_f32_16x16x32_bf16 v[22:25], v[176:179], v[216:219], v[22:25]
	v_mfma_f32_16x16x32_bf16 v[22:25], v[180:183], v[220:223], v[22:25]
	v_mfma_f32_16x16x32_bf16 v[18:21], v[188:191], v[220:223], v[18:21]
	v_mfma_f32_16x16x32_bf16 v[18:21], v[184:187], v[216:219], v[18:21]
	v_mfma_f32_16x16x32_bf16 v[2:5], v[184:187], v[224:227], v[2:5]
	v_mfma_f32_16x16x32_bf16 v[2:5], v[188:191], v[228:231], v[2:5]
	v_mfma_f32_16x16x32_bf16 v[6:9], v[180:183], v[228:231], v[6:9]
	v_mfma_f32_16x16x32_bf16 v[6:9], v[176:179], v[224:227], v[6:9]
	s_barrier
	s_setprio 0
	s_add_i32 s73, s73, 2
	s_add_u32 s66, s66, 0x100
	s_addc_u32 s67, s67, 0
	s_add_u32 s65, s65, 0x100
	s_addc_u32 s72, s72, 0
	s_cmp_gt_u32 s73, 29
	s_cbranch_scc0 .LBB0_1078
	s_and_b64 vcc, exec, s[10:11]
	s_cbranch_vccz .LBB0_1081
	s_barrier

; #define PG8_STAGE(bufoff, gbase, voff) do { _Pragma("unroll") for (int _i = 0; _i < 2; ++_i) \
;         __builtin_amdgcn_global_load_lds((const unsigned*)((const char*)(gbase) + (voff)[_i]), (PG8_LAS unsigned*)(lds + (bufoff) + ldsw + _i * 8192), 16, 0, 0); } while (0)
; #define PG8_LDA(dst, b, h) do { _Pragma("unroll") for (int m = 0; m < 4; ++m) _Pragma("unroll") for (int k = 0; k < 2; ++k) dst[m][k] = *(const PG8_LAS bf16x8*)(lds + PG8_SA(b, h) + aoff + m * 2048 + k * 1024); } while (0)
; #define PG8_LDB(dst, b, h) do { _Pragma("unroll") for (int n = 0; n < 2; ++n) _Pragma("unroll") for (int k = 0; k < 2; ++k) dst[n][k] = *(const PG8_LAS bf16x8*)(lds + PG8_SB(b, h) + boff + n * 2048 + k * 1024); } while (0)
; #define PG8_MMA(ai, bj, At, Bt) do { __builtin_amdgcn_s_setprio(1); _Pragma("unroll") for (int m = 0; m < 4; ++m) _Pragma("unroll") for (int n = 0; n < 2; ++n) _Pragma("unroll") for (int k = 0; k < 2; ++k) \
;         acc[ai][bj][m][n] = __builtin_amdgcn_mfma_f32_16x16x32_bf16(Bt[n][k], At[m][k], acc[ai][bj][m][n], 0, 0, 0); __builtin_amdgcn_s_setprio(0); } while (0)
; #define PG8_WAIT_V(n) asm volatile("s_waitcnt vmcnt(" #n ")" ::: "memory")
; #define PG8_WAIT_L(n) asm volatile("s_waitcnt lgkmcnt(" #n ")" ::: "memory")
; template <class Epi, class Sched, bool ALIGN_EPI = false, bool SP2 = false>
; __device__ __forceinline__ void gemm_phase(PG8_LAS unsigned char* lds, const Gemm g, const Sched& S, const Epi& E) {
;     ...
;             const bool last = (t == nt - 2);
;             const char* a1 = cA + (size_t)(t + 1) * kstep;
;             const char* a2 = last ? nA : cA + (size_t)(t + 2) * kstep; const char* b2 = last ? nB : cB + (size_t)(t + 2) * kstep;
;             const char* a3 = a2 + kstep; const char* b3 = b2 + kstep;
;             if (last && has_next) S.a_ready(nxt);
;             if constexpr (SP2) {
;             PG8_LDB(B0, 0, 0); PG8_LDB(B1, 0, 1); PG8_SCHED; PG8_LDA(At, 0, 0); PG8_STAGE(PG8_SA(1, 1), a1 + hstep, voffA);
;             PG8_WAIT_V(8); PG8_WAIT_L(0); PG8_BAR; PG8_MMA(0, 0, At, B0); PG8_MMA(0, 1, At, B1); PG8_BAR; PG8_SCHED;
;             PG8_LDA(At, 0, 1); PG8_STAGE(PG8_SB(0, 0), b2, voffB); PG8_STAGE(PG8_SB(0, 1), b2 + hstep, voffB); PG8_STAGE(PG8_SA(0, 0), a2, voffA);
;             PG8_WAIT_V(8); PG8_WAIT_L(0); PG8_BAR; PG8_MMA(1, 0, At, B0); PG8_MMA(1, 1, At, B1); PG8_BAR; PG8_SCHED;
.LBB0_1203:
	ds_read_b128 v[146:149], v171
	ds_read_b128 v[176:179], v171 offset:1024
	ds_read_b128 v[180:183], v171 offset:2048
	ds_read_b128 v[184:187], v171 offset:3072
	ds_read_b128 v[188:191], v172
	ds_read_b128 v[200:203], v172 offset:1024
	ds_read_b128 v[204:207], v172 offset:2048
	ds_read_b128 v[208:211], v172 offset:3072
	s_add_u32 s63, s64, 0xfff00080
	s_addc_u32 s66, s65, -1
	s_cmp_eq_u32 s61, 60
	s_cselect_b32 s69, s34, s66
	s_cselect_b32 s68, s35, s63
	s_cselect_b32 s67, s40, s55
	s_cselect_b32 s66, s41, s53
	v_lshl_add_u64 v[150:151], s[64:65], 0, v[138:139]
	s_add_i32 m0, s4, 0xc000
	ds_read_b128 v[212:215], v173
	ds_read_b128 v[216:219], v173 offset:1024
	ds_read_b128 v[220:223], v173 offset:2048
	ds_read_b128 v[224:227], v173 offset:3072
	ds_read_b128 v[228:231], v173 offset:4096
	ds_read_b128 v[240:243], v173 offset:5120
	ds_read_b128 v[244:247], v173 offset:6144
	ds_read_b128 v[248:251], v173 offset:7168
	global_load_lds_dwordx4 v[150:151], off
	v_lshl_add_u64 v[150:151], s[64:65], 0, v[140:141]
	s_add_i32 m0, s4, 0xe000
	s_nop 0
	global_load_lds_dwordx4 v[150:151], off
	s_waitcnt vmcnt(8)
	s_waitcnt lgkmcnt(0)
	s_setprio 1
	s_barrier
	v_mfma_f32_16x16x32_bf16 v[126:129], v[146:149], v[212:215], v[126:129]
	v_mfma_f32_16x16x32_bf16 v[126:129], v[176:179], v[216:219], v[126:129]
	v_mfma_f32_16x16x32_bf16 v[122:125], v[184:187], v[216:219], v[122:125]
	v_mfma_f32_16x16x32_bf16 v[122:125], v[180:183], v[212:215], v[122:125]
	v_mfma_f32_16x16x32_bf16 v[106:109], v[180:183], v[220:223], v[106:109]
	v_mfma_f32_16x16x32_bf16 v[106:109], v[184:187], v[224:227], v[106:109]
	v_mfma_f32_16x16x32_bf16 v[110:113], v[176:179], v[224:227], v[110:113]
	v_mfma_f32_16x16x32_bf16 v[110:113], v[146:149], v[220:223], v[110:113]
	v_mfma_f32_16x16x32_bf16 v[94:97], v[146:149], v[228:231], v[94:97]
	v_mfma_f32_16x16x32_bf16 v[94:97], v[176:179], v[240:243], v[94:97]
	v_mfma_f32_16x16x32_bf16 v[90:93], v[184:187], v[240:243], v[90:93]
	v_mfma_f32_16x16x32_bf16 v[90:93], v[180:183], v[228:231], v[90:93]
	v_mfma_f32_16x16x32_bf16 v[74:77], v[180:183], v[244:247], v[74:77]
	v_mfma_f32_16x16x32_bf16 v[74:77], v[184:187], v[248:251], v[74:77]
	v_mfma_f32_16x16x32_bf16 v[78:81], v[176:179], v[248:251], v[78:81]
	v_mfma_f32_16x16x32_bf16 v[78:81], v[146:149], v[244:247], v[78:81]
	s_setprio 0
	s_setprio 1
	v_mfma_f32_16x16x32_bf16 v[118:121], v[188:191], v[212:215], v[118:121]
	v_mfma_f32_16x16x32_bf16 v[118:121], v[200:203], v[216:219], v[118:121]
	v_mfma_f32_16x16x32_bf16 v[114:117], v[208:211], v[216:219], v[114:117]
	v_mfma_f32_16x16x32_bf16 v[114:117], v[204:207], v[212:215], v[114:117]
	v_mfma_f32_16x16x32_bf16 v[98:101], v[204:207], v[220:223], v[98:101]
	v_mfma_f32_16x16x32_bf16 v[98:101], v[208:211], v[224:227], v[98:101]
	v_mfma_f32_16x16x32_bf16 v[102:105], v[200:203], v[224:227], v[102:105]
	v_mfma_f32_16x16x32_bf16 v[102:105], v[188:191], v[220:223], v[102:105]
	v_mfma_f32_16x16x32_bf16 v[86:89], v[188:191], v[228:231], v[86:89]
	v_mfma_f32_16x16x32_bf16 v[86:89], v[200:203], v[240:243], v[86:89]
	v_mfma_f32_16x16x32_bf16 v[82:85], v[208:211], v[240:243], v[82:85]
	v_mfma_f32_16x16x32_bf16 v[82:85], v[204:207], v[228:231], v[82:85]
	v_mfma_f32_16x16x32_bf16 v[66:69], v[204:207], v[244:247], v[66:69]
	v_mfma_f32_16x16x32_bf16 v[66:69], v[208:211], v[248:251], v[66:69]
	v_mfma_f32_16x16x32_bf16 v[70:73], v[200:203], v[248:251], v[70:73]
	v_mfma_f32_16x16x32_bf16 v[70:73], v[188:191], v[244:247], v[70:73]
	s_barrier
	s_setprio 0
	s_add_i32 s63, s31, s2
	v_lshl_add_u64 v[150:151], s[66:67], 0, v[132:133]
	s_mov_b32 m0, s63
	ds_read_b128 v[212:215], v173 offset:16384
	ds_read_b128 v[216:219], v173 offset:17408
	ds_read_b128 v[220:223], v173 offset:18432
	ds_read_b128 v[224:227], v173 offset:19456
	ds_read_b128 v[228:231], v173 offset:20480
	ds_read_b128 v[240:243], v173 offset:21504
	ds_read_b128 v[244:247], v173 offset:22528
	ds_read_b128 v[248:251], v173 offset:23552
	global_load_lds_dwordx4 v[150:151], off
	s_add_i32 m0, s63, 0x2000
	s_add_u32 s70, s66, 0x100000
	v_lshl_add_u64 v[192:193], s[66:67], 0, v[136:137]
	s_addc_u32 s71, s67, 0
	s_add_i32 s63, s39, s2
	global_load_lds_dwordx4 v[192:193], off
	v_lshl_add_u64 v[232:233], s[70:71], 0, v[132:133]
	s_mov_b32 m0, s63
	v_lshl_add_u64 v[252:253], s[68:69], 0, v[134:135]
	global_load_lds_dwordx4 v[232:233], off
	v_lshl_add_u64 v[232:233], s[70:71], 0, v[136:137]
	s_add_i32 m0, s63, 0x2000
	s_nop 0
	global_load_lds_dwordx4 v[232:233], off
	v_lshl_add_u64 v[232:233], s[68:69], 0, v[130:131]
	s_mov_b32 m0, s4
	s_nop 0
	global_load_lds_dwordx4 v[232:233], off
	s_mov_b32 m0, s5
	s_nop 0
	global_load_lds_dwordx4 v[252:253], off
	s_waitcnt vmcnt(8)
	s_waitcnt lgkmcnt(0)
	s_setprio 1
	s_barrier
; #define PG8_STAGE(bufoff, gbase, voff) do { _Pragma("unroll") for (int _i = 0; _i < 2; ++_i) \
;         __builtin_amdgcn_global_load_lds((const unsigned*)((const char*)(gbase) + (voff)[_i]), (PG8_LAS unsigned*)(lds + (bufoff) + ldsw + _i * 8192), 16, 0, 0); } while (0)
; #define PG8_LDA(dst, b, h) do { _Pragma("unroll") for (int m = 0; m < 4; ++m) _Pragma("unroll") for (int k = 0; k < 2; ++k) dst[m][k] = *(const PG8_LAS bf16x8*)(lds + PG8_SA(b, h) + aoff + m * 2048 + k * 1024); } while (0)
; #define PG8_LDB(dst, b, h) do { _Pragma("unroll") for (int n = 0; n < 2; ++n) _Pragma("unroll") for (int k = 0; k < 2; ++k) dst[n][k] = *(const PG8_LAS bf16x8*)(lds + PG8_SB(b, h) + boff + n * 2048 + k * 1024); } while (0)
; #define PG8_MMA(ai, bj, At, Bt) do { __builtin_amdgcn_s_setprio(1); _Pragma("unroll") for (int m = 0; m < 4; ++m) _Pragma("unroll") for (int n = 0; n < 2; ++n) _Pragma("unroll") for (int k = 0; k < 2; ++k) \
;         acc[ai][bj][m][n] = __builtin_amdgcn_mfma_f32_16x16x32_bf16(Bt[n][k], At[m][k], acc[ai][bj][m][n], 0, 0, 0); __builtin_amdgcn_s_setprio(0); } while (0)
; #define PG8_WAIT_V(n) asm volatile("s_waitcnt vmcnt(" #n ")" ::: "memory")
; #define PG8_WAIT_L(n) asm volatile("s_waitcnt lgkmcnt(" #n ")" ::: "memory")
; #define PG8_BAR __builtin_amdgcn_s_barrier()
; #define PG8_SCHED __builtin_amdgcn_sched_barrier(0)
; template <class Epi, class Sched, bool ALIGN_EPI = false, bool SP2 = false>
; __device__ __forceinline__ void gemm_phase(PG8_LAS unsigned char* lds, const Gemm g, const Sched& S, const Epi& E) {
;     ...
;             PG8_WAIT_V(8); PG8_WAIT_L(0); PG8_BAR; PG8_MMA(1, 0, At, B0); PG8_MMA(1, 1, At, B1); PG8_BAR; PG8_SCHED;
;             PG8_LDB(B0, 1, 0); PG8_LDB(B1, 1, 1); PG8_SCHED; PG8_LDA(At, 1, 0); PG8_STAGE(PG8_SA(0, 1), a2 + hstep, voffA);
;             PG8_WAIT_V(8); PG8_WAIT_L(0); PG8_BAR; PG8_MMA(0, 0, At, B0); PG8_MMA(0, 1, At, B1); PG8_BAR; PG8_SCHED;
	v_mfma_f32_16x16x32_bf16 v[62:65], v[146:149], v[212:215], v[62:65]
	v_mfma_f32_16x16x32_bf16 v[62:65], v[176:179], v[216:219], v[62:65]
	v_mfma_f32_16x16x32_bf16 v[58:61], v[184:187], v[216:219], v[58:61]
	v_mfma_f32_16x16x32_bf16 v[58:61], v[180:183], v[212:215], v[58:61]
	v_mfma_f32_16x16x32_bf16 v[42:45], v[180:183], v[220:223], v[42:45]
	v_mfma_f32_16x16x32_bf16 v[42:45], v[184:187], v[224:227], v[42:45]
	v_mfma_f32_16x16x32_bf16 v[46:49], v[176:179], v[224:227], v[46:49]
	v_mfma_f32_16x16x32_bf16 v[46:49], v[146:149], v[220:223], v[46:49]
	v_mfma_f32_16x16x32_bf16 v[30:33], v[146:149], v[228:231], v[30:33]
	v_mfma_f32_16x16x32_bf16 v[30:33], v[176:179], v[240:243], v[30:33]
	v_mfma_f32_16x16x32_bf16 v[26:29], v[184:187], v[240:243], v[26:29]
	v_mfma_f32_16x16x32_bf16 v[26:29], v[180:183], v[228:231], v[26:29]
	v_mfma_f32_16x16x32_bf16 v[10:13], v[180:183], v[244:247], v[10:13]
	v_mfma_f32_16x16x32_bf16 v[10:13], v[184:187], v[248:251], v[10:13]
	v_mfma_f32_16x16x32_bf16 v[14:17], v[176:179], v[248:251], v[14:17]
	v_mfma_f32_16x16x32_bf16 v[14:17], v[146:149], v[244:247], v[14:17]
	s_setprio 0
	s_setprio 1
	v_mfma_f32_16x16x32_bf16 v[54:57], v[188:191], v[212:215], v[54:57]
	v_mfma_f32_16x16x32_bf16 v[54:57], v[200:203], v[216:219], v[54:57]
	v_mfma_f32_16x16x32_bf16 v[50:53], v[208:211], v[216:219], v[50:53]
	v_mfma_f32_16x16x32_bf16 v[50:53], v[204:207], v[212:215], v[50:53]
	v_mfma_f32_16x16x32_bf16 v[34:37], v[204:207], v[220:223], v[34:37]
	v_mfma_f32_16x16x32_bf16 v[34:37], v[208:211], v[224:227], v[34:37]
	v_mfma_f32_16x16x32_bf16 v[38:41], v[200:203], v[224:227], v[38:41]
	v_mfma_f32_16x16x32_bf16 v[38:41], v[188:191], v[220:223], v[38:41]
	v_mfma_f32_16x16x32_bf16 v[22:25], v[188:191], v[228:231], v[22:25]
	v_mfma_f32_16x16x32_bf16 v[22:25], v[200:203], v[240:243], v[22:25]
	v_mfma_f32_16x16x32_bf16 v[18:21], v[208:211], v[240:243], v[18:21]
	v_mfma_f32_16x16x32_bf16 v[18:21], v[204:207], v[228:231], v[18:21]
	v_mfma_f32_16x16x32_bf16 v[2:5], v[204:207], v[244:247], v[2:5]
	v_mfma_f32_16x16x32_bf16 v[2:5], v[208:211], v[248:251], v[2:5]
	v_mfma_f32_16x16x32_bf16 v[6:9], v[200:203], v[248:251], v[6:9]
	v_mfma_f32_16x16x32_bf16 v[6:9], v[188:191], v[244:247], v[6:9]
	s_barrier
	s_setprio 0
	s_add_i32 s63, 0, 0x18000
	v_add_u32_e32 v175, s63, v153
	s_add_i32 s70, 0, 0x1c000
	ds_read_b128 v[146:149], v175
	ds_read_b128 v[176:179], v175 offset:1024
	ds_read_b128 v[180:183], v175 offset:2048
	ds_read_b128 v[184:187], v175 offset:3072
	v_add_u32_e32 v175, s70, v153
	ds_read_b128 v[188:191], v175
	ds_read_b128 v[200:203], v175 offset:1024
	ds_read_b128 v[204:207], v175 offset:2048
	ds_read_b128 v[208:211], v175 offset:3072
	s_add_u32 s68, s68, 0x100000
	s_addc_u32 s69, s69, 0
	s_mov_b32 m0, s16
	v_lshl_add_u64 v[194:195], s[68:69], 0, v[130:131]
	ds_read_b128 v[212:215], v173 offset:32768
	ds_read_b128 v[216:219], v173 offset:33792
	ds_read_b128 v[220:223], v173 offset:34816
	ds_read_b128 v[224:227], v173 offset:35840
	ds_read_b128 v[228:231], v173 offset:36864
	ds_read_b128 v[240:243], v173 offset:37888
	ds_read_b128 v[244:247], v173 offset:38912
	ds_read_b128 v[248:251], v173 offset:39936
	global_load_lds_dwordx4 v[194:195], off
	v_lshl_add_u64 v[194:195], s[68:69], 0, v[134:135]
	s_mov_b32 m0, s17
	s_nop 0
	global_load_lds_dwordx4 v[194:195], off
	s_waitcnt vmcnt(8)
	s_waitcnt lgkmcnt(0)
	s_setprio 1
	s_barrier
	v_mfma_f32_16x16x32_bf16 v[126:129], v[146:149], v[212:215], v[126:129]
	v_mfma_f32_16x16x32_bf16 v[126:129], v[176:179], v[216:219], v[126:129]
	v_mfma_f32_16x16x32_bf16 v[122:125], v[184:187], v[216:219], v[122:125]
	v_mfma_f32_16x16x32_bf16 v[122:125], v[180:183], v[212:215], v[122:125]
	v_mfma_f32_16x16x32_bf16 v[106:109], v[180:183], v[220:223], v[106:109]
	v_mfma_f32_16x16x32_bf16 v[106:109], v[184:187], v[224:227], v[106:109]
	v_mfma_f32_16x16x32_bf16 v[110:113], v[176:179], v[224:227], v[110:113]
	v_mfma_f32_16x16x32_bf16 v[110:113], v[146:149], v[220:223], v[110:113]
	v_mfma_f32_16x16x32_bf16 v[94:97], v[146:149], v[228:231], v[94:97]
	v_mfma_f32_16x16x32_bf16 v[94:97], v[176:179], v[240:243], v[94:97]
	v_mfma_f32_16x16x32_bf16 v[90:93], v[184:187], v[240:243], v[90:93]
	v_mfma_f32_16x16x32_bf16 v[90:93], v[180:183], v[228:231], v[90:93]
	v_mfma_f32_16x16x32_bf16 v[74:77], v[180:183], v[244:247], v[74:77]
	v_mfma_f32_16x16x32_bf16 v[74:77], v[184:187], v[248:251], v[74:77]
	v_mfma_f32_16x16x32_bf16 v[78:81], v[176:179], v[248:251], v[78:81]
	v_mfma_f32_16x16x32_bf16 v[78:81], v[146:149], v[244:247], v[78:81]
	s_setprio 0
	s_setprio 1
	v_mfma_f32_16x16x32_bf16 v[118:121], v[188:191], v[212:215], v[118:121]
	v_mfma_f32_16x16x32_bf16 v[118:121], v[200:203], v[216:219], v[118:121]
	v_mfma_f32_16x16x32_bf16 v[114:117], v[208:211], v[216:219], v[114:117]
	v_mfma_f32_16x16x32_bf16 v[114:117], v[204:207], v[212:215], v[114:117]
	v_mfma_f32_16x16x32_bf16 v[98:101], v[204:207], v[220:223], v[98:101]
	v_mfma_f32_16x16x32_bf16 v[98:101], v[208:211], v[224:227], v[98:101]
	v_mfma_f32_16x16x32_bf16 v[102:105], v[200:203], v[224:227], v[102:105]
	v_mfma_f32_16x16x32_bf16 v[102:105], v[188:191], v[220:223], v[102:105]
	v_mfma_f32_16x16x32_bf16 v[86:89], v[188:191], v[228:231], v[86:89]
	v_mfma_f32_16x16x32_bf16 v[86:89], v[200:203], v[240:243], v[86:89]
	v_mfma_f32_16x16x32_bf16 v[82:85], v[208:211], v[240:243], v[82:85]
	v_mfma_f32_16x16x32_bf16 v[82:85], v[204:207], v[228:231], v[82:85]
	v_mfma_f32_16x16x32_bf16 v[66:69], v[204:207], v[244:247], v[66:69]
	v_mfma_f32_16x16x32_bf16 v[66:69], v[208:211], v[248:251], v[66:69]
	v_mfma_f32_16x16x32_bf16 v[70:73], v[200:203], v[248:251], v[70:73]
	v_mfma_f32_16x16x32_bf16 v[70:73], v[188:191], v[244:247], v[70:73]
	s_barrier
; #define PG8_STAGE(bufoff, gbase, voff) do { _Pragma("unroll") for (int _i = 0; _i < 2; ++_i) \
;         __builtin_amdgcn_global_load_lds((const unsigned*)((const char*)(gbase) + (voff)[_i]), (PG8_LAS unsigned*)(lds + (bufoff) + ldsw + _i * 8192), 16, 0, 0); } while (0)
; #define PG8_LDA(dst, b, h) do { _Pragma("unroll") for (int m = 0; m < 4; ++m) _Pragma("unroll") for (int k = 0; k < 2; ++k) dst[m][k] = *(const PG8_LAS bf16x8*)(lds + PG8_SA(b, h) + aoff + m * 2048 + k * 1024); } while (0)
; #define PG8_MMA(ai, bj, At, Bt) do { __builtin_amdgcn_s_setprio(1); _Pragma("unroll") for (int m = 0; m < 4; ++m) _Pragma("unroll") for (int n = 0; n < 2; ++n) _Pragma("unroll") for (int k = 0; k < 2; ++k) \
;         acc[ai][bj][m][n] = __builtin_amdgcn_mfma_f32_16x16x32_bf16(Bt[n][k], At[m][k], acc[ai][bj][m][n], 0, 0, 0); __builtin_amdgcn_s_setprio(0); } while (0)
; #define PG8_WAIT_V(n) asm volatile("s_waitcnt vmcnt(" #n ")" ::: "memory")
; #define PG8_WAIT_L(n) asm volatile("s_waitcnt lgkmcnt(" #n ")" ::: "memory")
; #define PG8_BAR __builtin_amdgcn_s_barrier()
; #define PG8_SCHED __builtin_amdgcn_sched_barrier(0)
; template <class Epi, class Sched, bool ALIGN_EPI = false, bool SP2 = false>
; __device__ __forceinline__ void gemm_phase(PG8_LAS unsigned char* lds, const Gemm g, const Sched& S, const Epi& E) {
;     ...
;             PG8_LDA(At, 1, 1); PG8_STAGE(PG8_SB(1, 0), b3, voffB); PG8_STAGE(PG8_SB(1, 1), b3 + hstep, voffB); PG8_STAGE(PG8_SA(1, 0), a3, voffA);
;             PG8_WAIT_V(8); PG8_WAIT_L(0); PG8_BAR; PG8_MMA(1, 0, At, B0); PG8_MMA(1, 1, At, B1); PG8_BAR; PG8_SCHED;
;     ...
;         if constexpr (ALIGN_EPI) { if (wr == 0) PG8_BAR; }
	s_setprio 0
	s_add_i32 s63, s63, s2
	v_lshl_add_u64 v[150:151], v[150:151], 0, s[44:45]
	s_mov_b32 m0, s63
	ds_read_b128 v[212:215], v173 offset:49152
	ds_read_b128 v[216:219], v173 offset:50176
	ds_read_b128 v[220:223], v173 offset:51200
	ds_read_b128 v[224:227], v173 offset:52224
	ds_read_b128 v[228:231], v173 offset:53248
	ds_read_b128 v[240:243], v173 offset:54272
	ds_read_b128 v[244:247], v173 offset:55296
	ds_read_b128 v[248:251], v173 offset:56320
	global_load_lds_dwordx4 v[150:151], off
	s_add_i32 m0, s63, 0x2000
	s_add_u32 s66, s66, 0x100080
	v_lshl_add_u64 v[150:151], v[192:193], 0, s[44:45]
	s_addc_u32 s67, s67, 0
	s_add_i32 s63, s70, s2
	global_load_lds_dwordx4 v[150:151], off
	v_lshl_add_u64 v[150:151], s[66:67], 0, v[132:133]
	s_mov_b32 m0, s63
	s_nop 0
	global_load_lds_dwordx4 v[150:151], off
	v_lshl_add_u64 v[150:151], s[66:67], 0, v[136:137]
	s_add_i32 m0, s63, 0x2000
	s_nop 0
	global_load_lds_dwordx4 v[150:151], off
	v_lshl_add_u64 v[150:151], v[232:233], 0, s[44:45]
	s_mov_b32 m0, s26
	s_nop 0
	global_load_lds_dwordx4 v[150:151], off
	v_lshl_add_u64 v[150:151], v[252:253], 0, s[44:45]
	s_mov_b32 m0, s27
	s_nop 0
	global_load_lds_dwordx4 v[150:151], off
	s_waitcnt vmcnt(8)
	s_waitcnt lgkmcnt(0)
	s_setprio 1
	s_barrier
	v_mfma_f32_16x16x32_bf16 v[62:65], v[146:149], v[212:215], v[62:65]
	v_mfma_f32_16x16x32_bf16 v[62:65], v[176:179], v[216:219], v[62:65]
	v_mfma_f32_16x16x32_bf16 v[58:61], v[184:187], v[216:219], v[58:61]
	v_mfma_f32_16x16x32_bf16 v[58:61], v[180:183], v[212:215], v[58:61]
	v_mfma_f32_16x16x32_bf16 v[42:45], v[180:183], v[220:223], v[42:45]
	v_mfma_f32_16x16x32_bf16 v[42:45], v[184:187], v[224:227], v[42:45]
	v_mfma_f32_16x16x32_bf16 v[46:49], v[176:179], v[224:227], v[46:49]
	v_mfma_f32_16x16x32_bf16 v[46:49], v[146:149], v[220:223], v[46:49]
	v_mfma_f32_16x16x32_bf16 v[30:33], v[146:149], v[228:231], v[30:33]
	v_mfma_f32_16x16x32_bf16 v[30:33], v[176:179], v[240:243], v[30:33]
	v_mfma_f32_16x16x32_bf16 v[26:29], v[184:187], v[240:243], v[26:29]
	v_mfma_f32_16x16x32_bf16 v[26:29], v[180:183], v[228:231], v[26:29]
	v_mfma_f32_16x16x32_bf16 v[10:13], v[180:183], v[244:247], v[10:13]
	v_mfma_f32_16x16x32_bf16 v[10:13], v[184:187], v[248:251], v[10:13]
	v_mfma_f32_16x16x32_bf16 v[14:17], v[176:179], v[248:251], v[14:17]
	v_mfma_f32_16x16x32_bf16 v[14:17], v[146:149], v[244:247], v[14:17]
	s_setprio 0
	s_setprio 1
	v_mfma_f32_16x16x32_bf16 v[54:57], v[188:191], v[212:215], v[54:57]
	v_mfma_f32_16x16x32_bf16 v[54:57], v[200:203], v[216:219], v[54:57]
	v_mfma_f32_16x16x32_bf16 v[50:53], v[208:211], v[216:219], v[50:53]
	v_mfma_f32_16x16x32_bf16 v[50:53], v[204:207], v[212:215], v[50:53]
	v_mfma_f32_16x16x32_bf16 v[34:37], v[204:207], v[220:223], v[34:37]
	v_mfma_f32_16x16x32_bf16 v[34:37], v[208:211], v[224:227], v[34:37]
	v_mfma_f32_16x16x32_bf16 v[38:41], v[200:203], v[224:227], v[38:41]
	v_mfma_f32_16x16x32_bf16 v[38:41], v[188:191], v[220:223], v[38:41]
	v_mfma_f32_16x16x32_bf16 v[22:25], v[188:191], v[228:231], v[22:25]
	v_mfma_f32_16x16x32_bf16 v[22:25], v[200:203], v[240:243], v[22:25]
	v_mfma_f32_16x16x32_bf16 v[18:21], v[208:211], v[240:243], v[18:21]
	v_mfma_f32_16x16x32_bf16 v[18:21], v[204:207], v[228:231], v[18:21]
	v_mfma_f32_16x16x32_bf16 v[2:5], v[204:207], v[244:247], v[2:5]
	v_mfma_f32_16x16x32_bf16 v[2:5], v[208:211], v[248:251], v[2:5]
	v_mfma_f32_16x16x32_bf16 v[6:9], v[200:203], v[248:251], v[6:9]
	v_mfma_f32_16x16x32_bf16 v[6:9], v[188:191], v[244:247], v[6:9]
	s_barrier
	s_setprio 0
	s_add_i32 s61, s61, 2
	s_add_u32 s64, s64, 0x100
	s_addc_u32 s65, s65, 0
	s_add_u32 s53, s53, 0x100
	s_addc_u32 s55, s55, 0
	s_cmp_gt_u32 s61, 61
	s_cbranch_scc0 .LBB0_1203
	s_and_b64 vcc, exec, s[46:47]
	s_cbranch_vccz .LBB0_1206
	s_barrier

; #define PG8_STAGE(bufoff, gbase, voff) do { _Pragma("unroll") for (int _i = 0; _i < 2; ++_i) \
;         __builtin_amdgcn_global_load_lds((const unsigned*)((const char*)(gbase) + (voff)[_i]), (PG8_LAS unsigned*)(lds + (bufoff) + ldsw + _i * 8192), 16, 0, 0); } while (0)
; #define PG8_LDA(dst, b, h) do { _Pragma("unroll") for (int m = 0; m < 4; ++m) _Pragma("unroll") for (int k = 0; k < 2; ++k) dst[m][k] = *(const PG8_LAS bf16x8*)(lds + PG8_SA(b, h) + aoff + m * 2048 + k * 1024); } while (0)
; #define PG8_LDB(dst, b, h) do { _Pragma("unroll") for (int n = 0; n < 2; ++n) _Pragma("unroll") for (int k = 0; k < 2; ++k) dst[n][k] = *(const PG8_LAS bf16x8*)(lds + PG8_SB(b, h) + boff + n * 2048 + k * 1024); } while (0)
; #define PG8_MMA(ai, bj, At, Bt) do { __builtin_amdgcn_s_setprio(1); _Pragma("unroll") for (int m = 0; m < 4; ++m) _Pragma("unroll") for (int n = 0; n < 2; ++n) _Pragma("unroll") for (int k = 0; k < 2; ++k) \
;         acc[ai][bj][m][n] = __builtin_amdgcn_mfma_f32_16x16x32_bf16(Bt[n][k], At[m][k], acc[ai][bj][m][n], 0, 0, 0); __builtin_amdgcn_s_setprio(0); } while (0)
; #define PG8_WAIT_V(n) asm volatile("s_waitcnt vmcnt(" #n ")" ::: "memory")
; #define PG8_WAIT_L(n) asm volatile("s_waitcnt lgkmcnt(" #n ")" ::: "memory")
; template <class Epi, class Sched, bool ALIGN_EPI = false, bool SP2 = false>
; __device__ __forceinline__ void gemm_phase(PG8_LAS unsigned char* lds, const Gemm g, const Sched& S, const Epi& E) {
;     ...
;             const bool last = (t == nt - 2);
;             const char* a1 = cA + (size_t)(t + 1) * kstep;
;             const char* a2 = last ? nA : cA + (size_t)(t + 2) * kstep; const char* b2 = last ? nB : cB + (size_t)(t + 2) * kstep;
;             const char* a3 = a2 + kstep; const char* b3 = b2 + kstep;
;             if (last && has_next) S.a_ready(nxt);
;             if constexpr (SP2) {
;             PG8_LDB(B0, 0, 0); PG8_LDB(B1, 0, 1); PG8_SCHED; PG8_LDA(At, 0, 0); PG8_STAGE(PG8_SA(1, 1), a1 + hstep, voffA);
;             PG8_WAIT_V(8); PG8_WAIT_L(0); PG8_BAR; PG8_MMA(0, 0, At, B0); PG8_MMA(0, 1, At, B1); PG8_BAR; PG8_SCHED;
;             PG8_LDA(At, 0, 1); PG8_STAGE(PG8_SB(0, 0), b2, voffB); PG8_STAGE(PG8_SB(0, 1), b2 + hstep, voffB); PG8_STAGE(PG8_SA(0, 0), a2, voffA);
;             PG8_WAIT_V(8); PG8_WAIT_L(0); PG8_BAR; PG8_MMA(1, 0, At, B0); PG8_MMA(1, 1, At, B1); PG8_BAR; PG8_SCHED;
.LBB0_1230:
	ds_read_b128 v[146:149], v140
	ds_read_b128 v[150:153], v140 offset:1024
	ds_read_b128 v[154:157], v140 offset:2048
	ds_read_b128 v[158:161], v140 offset:3072
	ds_read_b128 v[168:171], v141
	ds_read_b128 v[172:175], v141 offset:1024
	ds_read_b128 v[176:179], v141 offset:2048
	ds_read_b128 v[180:183], v141 offset:3072
	s_add_u32 s50, s46, 0x100
	s_addc_u32 s51, s47, 0
	s_cmp_lg_u32 s30, 12
	s_cselect_b32 s52, s50, 0
	s_cselect_b32 s53, s51, 0
	s_add_u32 s54, s10, s52
	s_addc_u32 s55, s11, s53
	s_add_u32 s52, s8, s52
	s_addc_u32 s53, s9, s53
	s_mov_b32 m0, s33
	v_lshl_add_u64 v[162:163], v[134:135], 0, s[46:47]
	ds_read_b128 v[184:187], v142
	ds_read_b128 v[188:191], v142 offset:1024
	ds_read_b128 v[200:203], v142 offset:2048
	ds_read_b128 v[204:207], v142 offset:3072
	ds_read_b128 v[208:211], v142 offset:4096
	ds_read_b128 v[212:215], v142 offset:5120
	ds_read_b128 v[216:219], v142 offset:6144
	ds_read_b128 v[220:223], v142 offset:7168
	global_load_lds_dwordx4 v[162:163], off
	v_lshl_add_u64 v[162:163], v[136:137], 0, s[46:47]
	s_mov_b32 m0, s34
	s_nop 0
	global_load_lds_dwordx4 v[162:163], off
	s_waitcnt vmcnt(8)
	s_waitcnt lgkmcnt(0)
	s_setprio 1
	s_barrier
	v_mfma_f32_16x16x32_bf16 v[126:129], v[146:149], v[184:187], v[126:129]
	v_mfma_f32_16x16x32_bf16 v[126:129], v[150:153], v[188:191], v[126:129]
	v_mfma_f32_16x16x32_bf16 v[122:125], v[158:161], v[188:191], v[122:125]
	v_mfma_f32_16x16x32_bf16 v[122:125], v[154:157], v[184:187], v[122:125]
	v_mfma_f32_16x16x32_bf16 v[114:117], v[154:157], v[200:203], v[114:117]
	v_mfma_f32_16x16x32_bf16 v[114:117], v[158:161], v[204:207], v[114:117]
	v_mfma_f32_16x16x32_bf16 v[118:121], v[150:153], v[204:207], v[118:121]
	v_mfma_f32_16x16x32_bf16 v[118:121], v[146:149], v[200:203], v[118:121]
	v_mfma_f32_16x16x32_bf16 v[106:109], v[146:149], v[208:211], v[106:109]
	v_mfma_f32_16x16x32_bf16 v[106:109], v[150:153], v[212:215], v[106:109]
	v_mfma_f32_16x16x32_bf16 v[98:101], v[158:161], v[212:215], v[98:101]
	v_mfma_f32_16x16x32_bf16 v[98:101], v[154:157], v[208:211], v[98:101]
	v_mfma_f32_16x16x32_bf16 v[82:85], v[154:157], v[216:219], v[82:85]
	v_mfma_f32_16x16x32_bf16 v[82:85], v[158:161], v[220:223], v[82:85]
	v_mfma_f32_16x16x32_bf16 v[90:93], v[150:153], v[220:223], v[90:93]
	v_mfma_f32_16x16x32_bf16 v[90:93], v[146:149], v[216:219], v[90:93]
	s_setprio 0
	s_setprio 1
	v_mfma_f32_16x16x32_bf16 v[110:113], v[168:171], v[184:187], v[110:113]
	v_mfma_f32_16x16x32_bf16 v[110:113], v[172:175], v[188:191], v[110:113]
	v_mfma_f32_16x16x32_bf16 v[102:105], v[180:183], v[188:191], v[102:105]
	v_mfma_f32_16x16x32_bf16 v[102:105], v[176:179], v[184:187], v[102:105]
	v_mfma_f32_16x16x32_bf16 v[86:89], v[176:179], v[200:203], v[86:89]
	v_mfma_f32_16x16x32_bf16 v[86:89], v[180:183], v[204:207], v[86:89]
	v_mfma_f32_16x16x32_bf16 v[94:97], v[172:175], v[204:207], v[94:97]
	v_mfma_f32_16x16x32_bf16 v[94:97], v[168:171], v[200:203], v[94:97]
	v_mfma_f32_16x16x32_bf16 v[78:81], v[168:171], v[208:211], v[78:81]
	v_mfma_f32_16x16x32_bf16 v[78:81], v[172:175], v[212:215], v[78:81]
	v_mfma_f32_16x16x32_bf16 v[74:77], v[180:183], v[212:215], v[74:77]
	v_mfma_f32_16x16x32_bf16 v[74:77], v[176:179], v[208:211], v[74:77]
	v_mfma_f32_16x16x32_bf16 v[66:69], v[176:179], v[216:219], v[66:69]
	v_mfma_f32_16x16x32_bf16 v[66:69], v[180:183], v[220:223], v[66:69]
	v_mfma_f32_16x16x32_bf16 v[70:73], v[172:175], v[220:223], v[70:73]
	v_mfma_f32_16x16x32_bf16 v[70:73], v[168:171], v[216:219], v[70:73]
	s_barrier
	s_setprio 0
	s_mov_b32 m0, s35
	v_lshl_add_u64 v[162:163], s[52:53], 0, v[130:131]
	s_add_u32 s46, s52, 0x100000
	ds_read_b128 v[184:187], v142 offset:16384
	ds_read_b128 v[188:191], v142 offset:17408
	ds_read_b128 v[200:203], v142 offset:18432
	ds_read_b128 v[204:207], v142 offset:19456
	ds_read_b128 v[208:211], v142 offset:20480
	ds_read_b128 v[212:215], v142 offset:21504
	ds_read_b128 v[216:219], v142 offset:22528
	ds_read_b128 v[220:223], v142 offset:23552
	global_load_lds_dwordx4 v[162:163], off
	v_lshl_add_u64 v[192:193], s[52:53], 0, v[132:133]
	s_mov_b32 m0, s39
	s_addc_u32 s47, s53, 0
	global_load_lds_dwordx4 v[192:193], off
	v_lshl_add_u64 v[194:195], s[46:47], 0, v[130:131]
	s_mov_b32 m0, s40
	v_lshl_add_u64 v[224:225], s[54:55], 0, v[132:133]
	global_load_lds_dwordx4 v[194:195], off
	v_lshl_add_u64 v[194:195], s[46:47], 0, v[132:133]
	s_mov_b32 m0, s41
	s_nop 0
	global_load_lds_dwordx4 v[194:195], off
	v_lshl_add_u64 v[194:195], s[54:55], 0, v[130:131]
	s_mov_b32 m0, s7
	s_nop 0
	global_load_lds_dwordx4 v[194:195], off
	s_mov_b32 m0, s16
	s_nop 0
	global_load_lds_dwordx4 v[224:225], off
	s_waitcnt vmcnt(8)
	s_waitcnt lgkmcnt(0)
	s_setprio 1
	s_barrier
; #define PG8_STAGE(bufoff, gbase, voff) do { _Pragma("unroll") for (int _i = 0; _i < 2; ++_i) \
;         __builtin_amdgcn_global_load_lds((const unsigned*)((const char*)(gbase) + (voff)[_i]), (PG8_LAS unsigned*)(lds + (bufoff) + ldsw + _i * 8192), 16, 0, 0); } while (0)
; #define PG8_LDA(dst, b, h) do { _Pragma("unroll") for (int m = 0; m < 4; ++m) _Pragma("unroll") for (int k = 0; k < 2; ++k) dst[m][k] = *(const PG8_LAS bf16x8*)(lds + PG8_SA(b, h) + aoff + m * 2048 + k * 1024); } while (0)
; #define PG8_LDB(dst, b, h) do { _Pragma("unroll") for (int n = 0; n < 2; ++n) _Pragma("unroll") for (int k = 0; k < 2; ++k) dst[n][k] = *(const PG8_LAS bf16x8*)(lds + PG8_SB(b, h) + boff + n * 2048 + k * 1024); } while (0)
; #define PG8_MMA(ai, bj, At, Bt) do { __builtin_amdgcn_s_setprio(1); _Pragma("unroll") for (int m = 0; m < 4; ++m) _Pragma("unroll") for (int n = 0; n < 2; ++n) _Pragma("unroll") for (int k = 0; k < 2; ++k) \
;         acc[ai][bj][m][n] = __builtin_amdgcn_mfma_f32_16x16x32_bf16(Bt[n][k], At[m][k], acc[ai][bj][m][n], 0, 0, 0); __builtin_amdgcn_s_setprio(0); } while (0)
; #define PG8_WAIT_V(n) asm volatile("s_waitcnt vmcnt(" #n ")" ::: "memory")
; #define PG8_WAIT_L(n) asm volatile("s_waitcnt lgkmcnt(" #n ")" ::: "memory")
; #define PG8_BAR __builtin_amdgcn_s_barrier()
; #define PG8_SCHED __builtin_amdgcn_sched_barrier(0)
; template <class Epi, class Sched, bool ALIGN_EPI = false, bool SP2 = false>
; __device__ __forceinline__ void gemm_phase(PG8_LAS unsigned char* lds, const Gemm g, const Sched& S, const Epi& E) {
;     ...
;             PG8_WAIT_V(8); PG8_WAIT_L(0); PG8_BAR; PG8_MMA(1, 0, At, B0); PG8_MMA(1, 1, At, B1); PG8_BAR; PG8_SCHED;
;             PG8_LDB(B0, 1, 0); PG8_LDB(B1, 1, 1); PG8_SCHED; PG8_LDA(At, 1, 0); PG8_STAGE(PG8_SA(0, 1), a2 + hstep, voffA);
;             PG8_WAIT_V(8); PG8_WAIT_L(0); PG8_BAR; PG8_MMA(0, 0, At, B0); PG8_MMA(0, 1, At, B1); PG8_BAR; PG8_SCHED;
	v_mfma_f32_16x16x32_bf16 v[62:65], v[146:149], v[184:187], v[62:65]
	v_mfma_f32_16x16x32_bf16 v[62:65], v[150:153], v[188:191], v[62:65]
	v_mfma_f32_16x16x32_bf16 v[58:61], v[158:161], v[188:191], v[58:61]
	v_mfma_f32_16x16x32_bf16 v[58:61], v[154:157], v[184:187], v[58:61]
	v_mfma_f32_16x16x32_bf16 v[50:53], v[154:157], v[200:203], v[50:53]
	v_mfma_f32_16x16x32_bf16 v[50:53], v[158:161], v[204:207], v[50:53]
	v_mfma_f32_16x16x32_bf16 v[54:57], v[150:153], v[204:207], v[54:57]
	v_mfma_f32_16x16x32_bf16 v[54:57], v[146:149], v[200:203], v[54:57]
	v_mfma_f32_16x16x32_bf16 v[42:45], v[146:149], v[208:211], v[42:45]
	v_mfma_f32_16x16x32_bf16 v[42:45], v[150:153], v[212:215], v[42:45]
	v_mfma_f32_16x16x32_bf16 v[34:37], v[158:161], v[212:215], v[34:37]
	v_mfma_f32_16x16x32_bf16 v[34:37], v[154:157], v[208:211], v[34:37]
	v_mfma_f32_16x16x32_bf16 v[18:21], v[154:157], v[216:219], v[18:21]
	v_mfma_f32_16x16x32_bf16 v[18:21], v[158:161], v[220:223], v[18:21]
	v_mfma_f32_16x16x32_bf16 v[26:29], v[150:153], v[220:223], v[26:29]
	v_mfma_f32_16x16x32_bf16 v[26:29], v[146:149], v[216:219], v[26:29]
	s_setprio 0
	s_setprio 1
	v_mfma_f32_16x16x32_bf16 v[46:49], v[168:171], v[184:187], v[46:49]
	v_mfma_f32_16x16x32_bf16 v[46:49], v[172:175], v[188:191], v[46:49]
	v_mfma_f32_16x16x32_bf16 v[38:41], v[180:183], v[188:191], v[38:41]
	v_mfma_f32_16x16x32_bf16 v[38:41], v[176:179], v[184:187], v[38:41]
	v_mfma_f32_16x16x32_bf16 v[22:25], v[176:179], v[200:203], v[22:25]
	v_mfma_f32_16x16x32_bf16 v[22:25], v[180:183], v[204:207], v[22:25]
	v_mfma_f32_16x16x32_bf16 v[30:33], v[172:175], v[204:207], v[30:33]
	v_mfma_f32_16x16x32_bf16 v[30:33], v[168:171], v[200:203], v[30:33]
	v_mfma_f32_16x16x32_bf16 v[14:17], v[168:171], v[208:211], v[14:17]
	v_mfma_f32_16x16x32_bf16 v[14:17], v[172:175], v[212:215], v[14:17]
	v_mfma_f32_16x16x32_bf16 v[10:13], v[180:183], v[212:215], v[10:13]
	v_mfma_f32_16x16x32_bf16 v[10:13], v[176:179], v[208:211], v[10:13]
	v_mfma_f32_16x16x32_bf16 v[2:5], v[176:179], v[216:219], v[2:5]
	v_mfma_f32_16x16x32_bf16 v[2:5], v[180:183], v[220:223], v[2:5]
	v_mfma_f32_16x16x32_bf16 v[6:9], v[172:175], v[220:223], v[6:9]
	v_mfma_f32_16x16x32_bf16 v[6:9], v[168:171], v[216:219], v[6:9]
	s_barrier
	s_setprio 0
	ds_read_b128 v[146:149], v143
	ds_read_b128 v[150:153], v143 offset:1024
	ds_read_b128 v[154:157], v143 offset:2048
	ds_read_b128 v[158:161], v143 offset:3072
	ds_read_b128 v[168:171], v144
	ds_read_b128 v[172:175], v144 offset:1024
	ds_read_b128 v[176:179], v144 offset:2048
	ds_read_b128 v[180:183], v144 offset:3072
	s_add_u32 s46, s54, 0x100000
	s_addc_u32 s47, s55, 0
	s_mov_b32 m0, s17
	v_lshl_add_u64 v[226:227], s[46:47], 0, v[130:131]
	ds_read_b128 v[184:187], v142 offset:32768
	ds_read_b128 v[188:191], v142 offset:33792
	ds_read_b128 v[200:203], v142 offset:34816
	ds_read_b128 v[204:207], v142 offset:35840
	ds_read_b128 v[208:211], v142 offset:36864
	ds_read_b128 v[212:215], v142 offset:37888
	ds_read_b128 v[216:219], v142 offset:38912
	ds_read_b128 v[220:223], v142 offset:39936
	global_load_lds_dwordx4 v[226:227], off
	v_lshl_add_u64 v[226:227], s[46:47], 0, v[132:133]
	s_mov_b32 m0, s26
	s_nop 0
	global_load_lds_dwordx4 v[226:227], off
	s_waitcnt vmcnt(8)
	s_waitcnt lgkmcnt(0)
	s_setprio 1
	s_barrier
	v_mfma_f32_16x16x32_bf16 v[126:129], v[146:149], v[184:187], v[126:129]
	v_mfma_f32_16x16x32_bf16 v[126:129], v[150:153], v[188:191], v[126:129]
	v_mfma_f32_16x16x32_bf16 v[122:125], v[158:161], v[188:191], v[122:125]
	v_mfma_f32_16x16x32_bf16 v[122:125], v[154:157], v[184:187], v[122:125]
	v_mfma_f32_16x16x32_bf16 v[114:117], v[154:157], v[200:203], v[114:117]
	v_mfma_f32_16x16x32_bf16 v[114:117], v[158:161], v[204:207], v[114:117]
	v_mfma_f32_16x16x32_bf16 v[118:121], v[150:153], v[204:207], v[118:121]
	v_mfma_f32_16x16x32_bf16 v[118:121], v[146:149], v[200:203], v[118:121]
	v_mfma_f32_16x16x32_bf16 v[106:109], v[146:149], v[208:211], v[106:109]
	v_mfma_f32_16x16x32_bf16 v[106:109], v[150:153], v[212:215], v[106:109]
	v_mfma_f32_16x16x32_bf16 v[98:101], v[158:161], v[212:215], v[98:101]
	v_mfma_f32_16x16x32_bf16 v[98:101], v[154:157], v[208:211], v[98:101]
	v_mfma_f32_16x16x32_bf16 v[82:85], v[154:157], v[216:219], v[82:85]
	v_mfma_f32_16x16x32_bf16 v[82:85], v[158:161], v[220:223], v[82:85]
	v_mfma_f32_16x16x32_bf16 v[90:93], v[150:153], v[220:223], v[90:93]
	v_mfma_f32_16x16x32_bf16 v[90:93], v[146:149], v[216:219], v[90:93]
	s_setprio 0
	s_setprio 1
	v_mfma_f32_16x16x32_bf16 v[110:113], v[168:171], v[184:187], v[110:113]
	v_mfma_f32_16x16x32_bf16 v[110:113], v[172:175], v[188:191], v[110:113]
	v_mfma_f32_16x16x32_bf16 v[102:105], v[180:183], v[188:191], v[102:105]
	v_mfma_f32_16x16x32_bf16 v[102:105], v[176:179], v[184:187], v[102:105]
	v_mfma_f32_16x16x32_bf16 v[86:89], v[176:179], v[200:203], v[86:89]
	v_mfma_f32_16x16x32_bf16 v[86:89], v[180:183], v[204:207], v[86:89]
	v_mfma_f32_16x16x32_bf16 v[94:97], v[172:175], v[204:207], v[94:97]
	v_mfma_f32_16x16x32_bf16 v[94:97], v[168:171], v[200:203], v[94:97]
	v_mfma_f32_16x16x32_bf16 v[78:81], v[168:171], v[208:211], v[78:81]
	v_mfma_f32_16x16x32_bf16 v[78:81], v[172:175], v[212:215], v[78:81]
	v_mfma_f32_16x16x32_bf16 v[74:77], v[180:183], v[212:215], v[74:77]
	v_mfma_f32_16x16x32_bf16 v[74:77], v[176:179], v[208:211], v[74:77]
	v_mfma_f32_16x16x32_bf16 v[66:69], v[176:179], v[216:219], v[66:69]
	v_mfma_f32_16x16x32_bf16 v[66:69], v[180:183], v[220:223], v[66:69]
	v_mfma_f32_16x16x32_bf16 v[70:73], v[172:175], v[220:223], v[70:73]
	v_mfma_f32_16x16x32_bf16 v[70:73], v[168:171], v[216:219], v[70:73]
	s_barrier
; #define PG8_STAGE(bufoff, gbase, voff) do { _Pragma("unroll") for (int _i = 0; _i < 2; ++_i) \
;         __builtin_amdgcn_global_load_lds((const unsigned*)((const char*)(gbase) + (voff)[_i]), (PG8_LAS unsigned*)(lds + (bufoff) + ldsw + _i * 8192), 16, 0, 0); } while (0)
; #define PG8_LDA(dst, b, h) do { _Pragma("unroll") for (int m = 0; m < 4; ++m) _Pragma("unroll") for (int k = 0; k < 2; ++k) dst[m][k] = *(const PG8_LAS bf16x8*)(lds + PG8_SA(b, h) + aoff + m * 2048 + k * 1024); } while (0)
; #define PG8_MMA(ai, bj, At, Bt) do { __builtin_amdgcn_s_setprio(1); _Pragma("unroll") for (int m = 0; m < 4; ++m) _Pragma("unroll") for (int n = 0; n < 2; ++n) _Pragma("unroll") for (int k = 0; k < 2; ++k) \
;         acc[ai][bj][m][n] = __builtin_amdgcn_mfma_f32_16x16x32_bf16(Bt[n][k], At[m][k], acc[ai][bj][m][n], 0, 0, 0); __builtin_amdgcn_s_setprio(0); } while (0)
; #define PG8_WAIT_V(n) asm volatile("s_waitcnt vmcnt(" #n ")" ::: "memory")
; #define PG8_WAIT_L(n) asm volatile("s_waitcnt lgkmcnt(" #n ")" ::: "memory")
; #define PG8_BAR __builtin_amdgcn_s_barrier()
; #define PG8_SCHED __builtin_amdgcn_sched_barrier(0)
; template <class Epi, class Sched, bool ALIGN_EPI = false, bool SP2 = false>
; __device__ __forceinline__ void gemm_phase(PG8_LAS unsigned char* lds, const Gemm g, const Sched& S, const Epi& E) {
;     ...
;             PG8_LDA(At, 1, 1); PG8_STAGE(PG8_SB(1, 0), b3, voffB); PG8_STAGE(PG8_SB(1, 1), b3 + hstep, voffB); PG8_STAGE(PG8_SA(1, 0), a3, voffA);
;             PG8_WAIT_V(8); PG8_WAIT_L(0); PG8_BAR; PG8_MMA(1, 0, At, B0); PG8_MMA(1, 1, At, B1); PG8_BAR; PG8_SCHED;
;     ...
;         if constexpr (ALIGN_EPI) { if (wr == 0) PG8_BAR; }
	s_setprio 0
	s_mov_b32 m0, s44
	v_lshl_add_u64 v[162:163], v[162:163], 0, s[12:13]
	s_add_u32 s46, s52, 0x100080
	ds_read_b128 v[184:187], v142 offset:49152
	ds_read_b128 v[188:191], v142 offset:50176
	ds_read_b128 v[200:203], v142 offset:51200
	ds_read_b128 v[204:207], v142 offset:52224
	ds_read_b128 v[208:211], v142 offset:53248
	ds_read_b128 v[212:215], v142 offset:54272
	ds_read_b128 v[216:219], v142 offset:55296
	ds_read_b128 v[220:223], v142 offset:56320
	global_load_lds_dwordx4 v[162:163], off
	v_lshl_add_u64 v[162:163], v[192:193], 0, s[12:13]
	s_mov_b32 m0, s45
	s_addc_u32 s47, s53, 0
	global_load_lds_dwordx4 v[162:163], off
	v_lshl_add_u64 v[162:163], s[46:47], 0, v[130:131]
	s_mov_b32 m0, s56
	s_nop 0
	global_load_lds_dwordx4 v[162:163], off
	v_lshl_add_u64 v[162:163], s[46:47], 0, v[132:133]
	s_mov_b32 m0, s57
	s_nop 0
	global_load_lds_dwordx4 v[162:163], off
	v_lshl_add_u64 v[162:163], v[194:195], 0, s[12:13]
	s_mov_b32 m0, s28
	s_nop 0
	global_load_lds_dwordx4 v[162:163], off
	v_lshl_add_u64 v[162:163], v[224:225], 0, s[12:13]
	s_mov_b32 m0, s29
	s_nop 0
	global_load_lds_dwordx4 v[162:163], off
	s_waitcnt vmcnt(8)
	s_waitcnt lgkmcnt(0)
	s_setprio 1
	s_barrier
	v_mfma_f32_16x16x32_bf16 v[62:65], v[146:149], v[184:187], v[62:65]
	v_mfma_f32_16x16x32_bf16 v[62:65], v[150:153], v[188:191], v[62:65]
	v_mfma_f32_16x16x32_bf16 v[58:61], v[158:161], v[188:191], v[58:61]
	v_mfma_f32_16x16x32_bf16 v[58:61], v[154:157], v[184:187], v[58:61]
	v_mfma_f32_16x16x32_bf16 v[50:53], v[154:157], v[200:203], v[50:53]
	v_mfma_f32_16x16x32_bf16 v[50:53], v[158:161], v[204:207], v[50:53]
	v_mfma_f32_16x16x32_bf16 v[54:57], v[150:153], v[204:207], v[54:57]
	v_mfma_f32_16x16x32_bf16 v[54:57], v[146:149], v[200:203], v[54:57]
	v_mfma_f32_16x16x32_bf16 v[42:45], v[146:149], v[208:211], v[42:45]
	v_mfma_f32_16x16x32_bf16 v[42:45], v[150:153], v[212:215], v[42:45]
	v_mfma_f32_16x16x32_bf16 v[34:37], v[158:161], v[212:215], v[34:37]
	v_mfma_f32_16x16x32_bf16 v[34:37], v[154:157], v[208:211], v[34:37]
	v_mfma_f32_16x16x32_bf16 v[18:21], v[154:157], v[216:219], v[18:21]
	v_mfma_f32_16x16x32_bf16 v[18:21], v[158:161], v[220:223], v[18:21]
	v_mfma_f32_16x16x32_bf16 v[26:29], v[150:153], v[220:223], v[26:29]
	v_mfma_f32_16x16x32_bf16 v[26:29], v[146:149], v[216:219], v[26:29]
	s_setprio 0
	s_setprio 1
	v_mfma_f32_16x16x32_bf16 v[46:49], v[168:171], v[184:187], v[46:49]
	v_mfma_f32_16x16x32_bf16 v[46:49], v[172:175], v[188:191], v[46:49]
	v_mfma_f32_16x16x32_bf16 v[38:41], v[180:183], v[188:191], v[38:41]
	v_mfma_f32_16x16x32_bf16 v[38:41], v[176:179], v[184:187], v[38:41]
	v_mfma_f32_16x16x32_bf16 v[22:25], v[176:179], v[200:203], v[22:25]
	v_mfma_f32_16x16x32_bf16 v[22:25], v[180:183], v[204:207], v[22:25]
	v_mfma_f32_16x16x32_bf16 v[30:33], v[172:175], v[204:207], v[30:33]
	v_mfma_f32_16x16x32_bf16 v[30:33], v[168:171], v[200:203], v[30:33]
	v_mfma_f32_16x16x32_bf16 v[14:17], v[168:171], v[208:211], v[14:17]
	v_mfma_f32_16x16x32_bf16 v[14:17], v[172:175], v[212:215], v[14:17]
	v_mfma_f32_16x16x32_bf16 v[10:13], v[180:183], v[212:215], v[10:13]
	v_mfma_f32_16x16x32_bf16 v[10:13], v[176:179], v[208:211], v[10:13]
	v_mfma_f32_16x16x32_bf16 v[2:5], v[176:179], v[216:219], v[2:5]
	v_mfma_f32_16x16x32_bf16 v[2:5], v[180:183], v[220:223], v[2:5]
	v_mfma_f32_16x16x32_bf16 v[6:9], v[172:175], v[220:223], v[6:9]
	v_mfma_f32_16x16x32_bf16 v[6:9], v[168:171], v[216:219], v[6:9]
	s_barrier
	s_setprio 0
	s_add_i32 s30, s30, 2
	s_cmp_gt_u32 s30, 13
	s_mov_b64 s[46:47], s[50:51]
	s_cbranch_scc0 .LBB0_1230
	s_cmpk_lt_u32 s2, 0x100
	s_cbranch_scc0 .LBB0_1233
	s_barrier

; #define PG8_STAGE(bufoff, gbase, voff) do { _Pragma("unroll") for (int _i = 0; _i < 2; ++_i) \
;         __builtin_amdgcn_global_load_lds((const unsigned*)((const char*)(gbase) + (voff)[_i]), (PG8_LAS unsigned*)(lds + (bufoff) + ldsw + _i * 8192), 16, 0, 0); } while (0)
; #define PG8_LDA(dst, b, h) do { _Pragma("unroll") for (int m = 0; m < 4; ++m) _Pragma("unroll") for (int k = 0; k < 2; ++k) dst[m][k] = *(const PG8_LAS bf16x8*)(lds + PG8_SA(b, h) + aoff + m * 2048 + k * 1024); } while (0)
; #define PG8_LDB(dst, b, h) do { _Pragma("unroll") for (int n = 0; n < 2; ++n) _Pragma("unroll") for (int k = 0; k < 2; ++k) dst[n][k] = *(const PG8_LAS bf16x8*)(lds + PG8_SB(b, h) + boff + n * 2048 + k * 1024); } while (0)
; #define PG8_MMA(ai, bj, At, Bt) do { __builtin_amdgcn_s_setprio(1); _Pragma("unroll") for (int m = 0; m < 4; ++m) _Pragma("unroll") for (int n = 0; n < 2; ++n) _Pragma("unroll") for (int k = 0; k < 2; ++k) \
;         acc[ai][bj][m][n] = __builtin_amdgcn_mfma_f32_16x16x32_bf16(Bt[n][k], At[m][k], acc[ai][bj][m][n], 0, 0, 0); __builtin_amdgcn_s_setprio(0); } while (0)
; #define PG8_WAIT_V(n) asm volatile("s_waitcnt vmcnt(" #n ")" ::: "memory")
; #define PG8_WAIT_L(n) asm volatile("s_waitcnt lgkmcnt(" #n ")" ::: "memory")
; template <class Epi, class Sched, bool ALIGN_EPI = false, bool SP2 = false>
; __device__ __forceinline__ void gemm_phase(PG8_LAS unsigned char* lds, const Gemm g, const Sched& S, const Epi& E) {
;     ...
;             const bool last = (t == nt - 2);
;             const char* a1 = cA + (size_t)(t + 1) * kstep;
;             const char* a2 = last ? nA : cA + (size_t)(t + 2) * kstep; const char* b2 = last ? nB : cB + (size_t)(t + 2) * kstep;
;             const char* a3 = a2 + kstep; const char* b3 = b2 + kstep;
;             if (last && has_next) S.a_ready(nxt);
;             if constexpr (SP2) {
;             PG8_LDB(B0, 0, 0); PG8_LDB(B1, 0, 1); PG8_SCHED; PG8_LDA(At, 0, 0); PG8_STAGE(PG8_SA(1, 1), a1 + hstep, voffA);
;             PG8_WAIT_V(8); PG8_WAIT_L(0); PG8_BAR; PG8_MMA(0, 0, At, B0); PG8_MMA(0, 1, At, B1); PG8_BAR; PG8_SCHED;
;             PG8_LDA(At, 0, 1); PG8_STAGE(PG8_SB(0, 0), b2, voffB); PG8_STAGE(PG8_SB(0, 1), b2 + hstep, voffB); PG8_STAGE(PG8_SA(0, 0), a2, voffA);
;             PG8_WAIT_V(8); PG8_WAIT_L(0); PG8_BAR; PG8_MMA(1, 0, At, B0); PG8_MMA(1, 1, At, B1); PG8_BAR; PG8_SCHED;
.LBB0_1478:
	v_add_u32_e32 v144, s31, v201
	v_add_u32_e32 v160, s52, v201
	ds_read_b128 v[132:135], v144
	ds_read_b128 v[136:139], v144 offset:1024
	ds_read_b128 v[140:143], v144 offset:2048
	ds_read_b128 v[144:147], v144 offset:3072
	ds_read_b128 v[148:151], v160
	ds_read_b128 v[152:155], v160 offset:1024
	ds_read_b128 v[156:159], v160 offset:2048
	ds_read_b128 v[160:163], v160 offset:3072
	s_add_u32 s50, s82, 0xfff00080
	s_addc_u32 s56, s83, -1
	s_and_b64 s[34:35], s[84:85], exec
	s_cselect_b32 s87, s65, s56
	s_cselect_b32 s86, s69, s50
	s_cselect_b32 s85, s67, s88
	s_cselect_b32 s84, s77, s79
	v_lshl_add_u64 v[192:193], s[82:83], 0, v[220:221]
	s_add_i32 m0, s28, 0xc000
	ds_read_b128 v[164:167], v242
	ds_read_b128 v[168:171], v242 offset:1024
	ds_read_b128 v[172:175], v242 offset:2048
	ds_read_b128 v[176:179], v242 offset:3072
	ds_read_b128 v[180:183], v242 offset:4096
	ds_read_b128 v[184:187], v242 offset:5120
	ds_read_b128 v[188:191], v242 offset:6144
	ds_read_b128 v[226:229], v242 offset:7168
	global_load_lds_dwordx4 v[192:193], off
	v_lshl_add_u64 v[192:193], s[82:83], 0, v[222:223]
	s_add_i32 m0, s28, 0xe000
	s_nop 0
	global_load_lds_dwordx4 v[192:193], off
	s_waitcnt vmcnt(8)
	s_waitcnt lgkmcnt(0)
	s_setprio 1
	s_barrier
	v_mfma_f32_16x16x32_bf16 v[126:129], v[132:135], v[164:167], v[126:129]
	v_mfma_f32_16x16x32_bf16 v[126:129], v[136:139], v[168:171], v[126:129]
	v_mfma_f32_16x16x32_bf16 v[46:49], v[144:147], v[168:171], v[46:49]
	v_mfma_f32_16x16x32_bf16 v[46:49], v[140:143], v[164:167], v[46:49]
	v_mfma_f32_16x16x32_bf16 v[122:125], v[140:143], v[172:175], v[122:125]
	v_mfma_f32_16x16x32_bf16 v[122:125], v[144:147], v[176:179], v[122:125]
	v_mfma_f32_16x16x32_bf16 v[118:121], v[136:139], v[176:179], v[118:121]
	v_mfma_f32_16x16x32_bf16 v[118:121], v[132:135], v[172:175], v[118:121]
	v_mfma_f32_16x16x32_bf16 v[110:113], v[132:135], v[180:183], v[110:113]
	v_mfma_f32_16x16x32_bf16 v[110:113], v[136:139], v[184:187], v[110:113]
	v_mfma_f32_16x16x32_bf16 v[114:117], v[144:147], v[184:187], v[114:117]
	v_mfma_f32_16x16x32_bf16 v[114:117], v[140:143], v[180:183], v[114:117]
	v_mfma_f32_16x16x32_bf16 v[106:109], v[140:143], v[188:191], v[106:109]
	v_mfma_f32_16x16x32_bf16 v[106:109], v[144:147], v[226:229], v[106:109]
	v_mfma_f32_16x16x32_bf16 v[102:105], v[136:139], v[226:229], v[102:105]
	v_mfma_f32_16x16x32_bf16 v[102:105], v[132:135], v[188:191], v[102:105]
	s_setprio 0
	s_setprio 1
	v_mfma_f32_16x16x32_bf16 v[54:57], v[148:151], v[164:167], v[54:57]
	v_mfma_f32_16x16x32_bf16 v[54:57], v[152:155], v[168:171], v[54:57]
	v_mfma_f32_16x16x32_bf16 v[38:41], v[160:163], v[168:171], v[38:41]
	v_mfma_f32_16x16x32_bf16 v[38:41], v[156:159], v[164:167], v[38:41]
	v_mfma_f32_16x16x32_bf16 v[30:33], v[156:159], v[172:175], v[30:33]
	v_mfma_f32_16x16x32_bf16 v[30:33], v[160:163], v[176:179], v[30:33]
	v_mfma_f32_16x16x32_bf16 v[58:61], v[152:155], v[176:179], v[58:61]
	v_mfma_f32_16x16x32_bf16 v[58:61], v[148:151], v[172:175], v[58:61]
	v_mfma_f32_16x16x32_bf16 v[62:65], v[148:151], v[180:183], v[62:65]
	v_mfma_f32_16x16x32_bf16 v[62:65], v[152:155], v[184:187], v[62:65]
	v_mfma_f32_16x16x32_bf16 v[22:25], v[160:163], v[184:187], v[22:25]
	v_mfma_f32_16x16x32_bf16 v[22:25], v[156:159], v[180:183], v[22:25]
	v_mfma_f32_16x16x32_bf16 v[50:53], v[156:159], v[188:191], v[50:53]
	v_mfma_f32_16x16x32_bf16 v[50:53], v[160:163], v[226:229], v[50:53]
	v_mfma_f32_16x16x32_bf16 v[98:101], v[152:155], v[226:229], v[98:101]
	v_mfma_f32_16x16x32_bf16 v[98:101], v[148:151], v[188:191], v[98:101]
	s_barrier
	s_setprio 0
	s_add_i32 s34, s31, s45
	v_lshl_add_u64 v[192:193], s[84:85], 0, v[208:209]
	s_mov_b32 m0, s34
	ds_read_b128 v[164:167], v242 offset:16384
	ds_read_b128 v[168:171], v242 offset:17408
	ds_read_b128 v[172:175], v242 offset:18432
	ds_read_b128 v[176:179], v242 offset:19456
	ds_read_b128 v[180:183], v242 offset:20480
	ds_read_b128 v[184:187], v242 offset:21504
	ds_read_b128 v[188:191], v242 offset:22528
	ds_read_b128 v[226:229], v242 offset:23552
	global_load_lds_dwordx4 v[192:193], off
	s_add_i32 m0, s34, 0x2000
	s_add_u32 s34, s84, 0x100000
	v_lshl_add_u64 v[194:195], s[84:85], 0, v[212:213]
	s_addc_u32 s35, s85, 0
	s_add_i32 s50, s52, s45
	global_load_lds_dwordx4 v[194:195], off
	v_lshl_add_u64 v[230:231], s[34:35], 0, v[208:209]
	s_mov_b32 m0, s50
	v_lshl_add_u64 v[232:233], s[86:87], 0, v[210:211]
	global_load_lds_dwordx4 v[230:231], off
	v_lshl_add_u64 v[230:231], s[34:35], 0, v[212:213]
	s_add_i32 m0, s50, 0x2000
	s_nop 0
	global_load_lds_dwordx4 v[230:231], off
	v_lshl_add_u64 v[230:231], s[86:87], 0, v[206:207]
	s_mov_b32 m0, s28
	s_nop 0
	global_load_lds_dwordx4 v[230:231], off
	s_mov_b32 m0, s29
	s_nop 0
	global_load_lds_dwordx4 v[232:233], off
	s_waitcnt vmcnt(8)
	s_waitcnt lgkmcnt(0)
	s_setprio 1
	s_barrier
; #define PG8_STAGE(bufoff, gbase, voff) do { _Pragma("unroll") for (int _i = 0; _i < 2; ++_i) \
;         __builtin_amdgcn_global_load_lds((const unsigned*)((const char*)(gbase) + (voff)[_i]), (PG8_LAS unsigned*)(lds + (bufoff) + ldsw + _i * 8192), 16, 0, 0); } while (0)
; #define PG8_LDA(dst, b, h) do { _Pragma("unroll") for (int m = 0; m < 4; ++m) _Pragma("unroll") for (int k = 0; k < 2; ++k) dst[m][k] = *(const PG8_LAS bf16x8*)(lds + PG8_SA(b, h) + aoff + m * 2048 + k * 1024); } while (0)
; #define PG8_LDB(dst, b, h) do { _Pragma("unroll") for (int n = 0; n < 2; ++n) _Pragma("unroll") for (int k = 0; k < 2; ++k) dst[n][k] = *(const PG8_LAS bf16x8*)(lds + PG8_SB(b, h) + boff + n * 2048 + k * 1024); } while (0)
; #define PG8_MMA(ai, bj, At, Bt) do { __builtin_amdgcn_s_setprio(1); _Pragma("unroll") for (int m = 0; m < 4; ++m) _Pragma("unroll") for (int n = 0; n < 2; ++n) _Pragma("unroll") for (int k = 0; k < 2; ++k) \
;         acc[ai][bj][m][n] = __builtin_amdgcn_mfma_f32_16x16x32_bf16(Bt[n][k], At[m][k], acc[ai][bj][m][n], 0, 0, 0); __builtin_amdgcn_s_setprio(0); } while (0)
; #define PG8_WAIT_V(n) asm volatile("s_waitcnt vmcnt(" #n ")" ::: "memory")
; #define PG8_WAIT_L(n) asm volatile("s_waitcnt lgkmcnt(" #n ")" ::: "memory")
; #define PG8_BAR __builtin_amdgcn_s_barrier()
; #define PG8_SCHED __builtin_amdgcn_sched_barrier(0)
; template <class Epi, class Sched, bool ALIGN_EPI = false, bool SP2 = false>
; __device__ __forceinline__ void gemm_phase(PG8_LAS unsigned char* lds, const Gemm g, const Sched& S, const Epi& E) {
;     ...
;             PG8_WAIT_V(8); PG8_WAIT_L(0); PG8_BAR; PG8_MMA(1, 0, At, B0); PG8_MMA(1, 1, At, B1); PG8_BAR; PG8_SCHED;
;             PG8_LDB(B0, 1, 0); PG8_LDB(B1, 1, 1); PG8_SCHED; PG8_LDA(At, 1, 0); PG8_STAGE(PG8_SA(0, 1), a2 + hstep, voffA);
;             PG8_WAIT_V(8); PG8_WAIT_L(0); PG8_BAR; PG8_MMA(0, 0, At, B0); PG8_MMA(0, 1, At, B1); PG8_BAR; PG8_SCHED;
	v_mfma_f32_16x16x32_bf16 v[78:81], v[132:135], v[164:167], v[78:81]
	v_mfma_f32_16x16x32_bf16 v[78:81], v[136:139], v[168:171], v[78:81]
	v_mfma_f32_16x16x32_bf16 v[14:17], v[144:147], v[168:171], v[14:17]
	v_mfma_f32_16x16x32_bf16 v[14:17], v[140:143], v[164:167], v[14:17]
	v_mfma_f32_16x16x32_bf16 v[94:97], v[140:143], v[172:175], v[94:97]
	v_mfma_f32_16x16x32_bf16 v[94:97], v[144:147], v[176:179], v[94:97]
	v_mfma_f32_16x16x32_bf16 v[66:69], v[136:139], v[176:179], v[66:69]
	v_mfma_f32_16x16x32_bf16 v[66:69], v[132:135], v[172:175], v[66:69]
	v_mfma_f32_16x16x32_bf16 v[70:73], v[132:135], v[180:183], v[70:73]
	v_mfma_f32_16x16x32_bf16 v[70:73], v[136:139], v[184:187], v[70:73]
	v_mfma_f32_16x16x32_bf16 v[90:93], v[144:147], v[184:187], v[90:93]
	v_mfma_f32_16x16x32_bf16 v[90:93], v[140:143], v[180:183], v[90:93]
	v_mfma_f32_16x16x32_bf16 v[10:13], v[140:143], v[188:191], v[10:13]
	v_mfma_f32_16x16x32_bf16 v[10:13], v[144:147], v[226:229], v[10:13]
	v_mfma_f32_16x16x32_bf16 v[74:77], v[136:139], v[226:229], v[74:77]
	v_mfma_f32_16x16x32_bf16 v[74:77], v[132:135], v[188:191], v[74:77]
	s_setprio 0
	s_setprio 1
	v_mfma_f32_16x16x32_bf16 v[42:45], v[148:151], v[164:167], v[42:45]
	v_mfma_f32_16x16x32_bf16 v[42:45], v[152:155], v[168:171], v[42:45]
	v_mfma_f32_16x16x32_bf16 v[2:5], v[160:163], v[168:171], v[2:5]
	v_mfma_f32_16x16x32_bf16 v[2:5], v[156:159], v[164:167], v[2:5]
	v_mfma_f32_16x16x32_bf16 v[6:9], v[156:159], v[172:175], v[6:9]
	v_mfma_f32_16x16x32_bf16 v[6:9], v[160:163], v[176:179], v[6:9]
	v_mfma_f32_16x16x32_bf16 v[34:37], v[152:155], v[176:179], v[34:37]
	v_mfma_f32_16x16x32_bf16 v[34:37], v[148:151], v[172:175], v[34:37]
	v_mfma_f32_16x16x32_bf16 v[86:89], v[148:151], v[180:183], v[86:89]
	v_mfma_f32_16x16x32_bf16 v[86:89], v[152:155], v[184:187], v[86:89]
	v_mfma_f32_16x16x32_bf16 v[26:29], v[160:163], v[184:187], v[26:29]
	v_mfma_f32_16x16x32_bf16 v[26:29], v[156:159], v[180:183], v[26:29]
	v_mfma_f32_16x16x32_bf16 v[18:21], v[156:159], v[188:191], v[18:21]
	v_mfma_f32_16x16x32_bf16 v[18:21], v[160:163], v[226:229], v[18:21]
	v_mfma_f32_16x16x32_bf16 v[82:85], v[152:155], v[226:229], v[82:85]
	v_mfma_f32_16x16x32_bf16 v[82:85], v[148:151], v[188:191], v[82:85]
	s_barrier
	s_setprio 0
	s_add_i32 s50, 0, 0x18000
	s_add_i32 s56, 0, 0x1c000
	v_add_u32_e32 v144, s50, v201
	v_add_u32_e32 v160, s56, v201
	ds_read_b128 v[132:135], v144
	ds_read_b128 v[136:139], v144 offset:1024
	ds_read_b128 v[140:143], v144 offset:2048
	ds_read_b128 v[144:147], v144 offset:3072
	ds_read_b128 v[148:151], v160
	ds_read_b128 v[152:155], v160 offset:1024
	ds_read_b128 v[156:159], v160 offset:2048
	ds_read_b128 v[160:163], v160 offset:3072
	s_add_u32 s34, s86, 0x100000
	s_addc_u32 s35, s87, 0
	s_mov_b32 m0, s16
	v_lshl_add_u64 v[246:247], s[34:35], 0, v[206:207]
	ds_read_b128 v[164:167], v242 offset:32768
	ds_read_b128 v[168:171], v242 offset:33792
	ds_read_b128 v[172:175], v242 offset:34816
	ds_read_b128 v[176:179], v242 offset:35840
	ds_read_b128 v[180:183], v242 offset:36864
	ds_read_b128 v[184:187], v242 offset:37888
	ds_read_b128 v[188:191], v242 offset:38912
	ds_read_b128 v[226:229], v242 offset:39936
	global_load_lds_dwordx4 v[246:247], off
	v_lshl_add_u64 v[246:247], s[34:35], 0, v[210:211]
	s_mov_b32 m0, s17
	s_nop 0
	global_load_lds_dwordx4 v[246:247], off
	s_waitcnt vmcnt(8)
	s_waitcnt lgkmcnt(0)
	s_setprio 1
	s_barrier
	v_mfma_f32_16x16x32_bf16 v[126:129], v[132:135], v[164:167], v[126:129]
	v_mfma_f32_16x16x32_bf16 v[126:129], v[136:139], v[168:171], v[126:129]
	v_mfma_f32_16x16x32_bf16 v[46:49], v[144:147], v[168:171], v[46:49]
	v_mfma_f32_16x16x32_bf16 v[46:49], v[140:143], v[164:167], v[46:49]
	v_mfma_f32_16x16x32_bf16 v[122:125], v[140:143], v[172:175], v[122:125]
	v_mfma_f32_16x16x32_bf16 v[122:125], v[144:147], v[176:179], v[122:125]
	v_mfma_f32_16x16x32_bf16 v[118:121], v[136:139], v[176:179], v[118:121]
	v_mfma_f32_16x16x32_bf16 v[118:121], v[132:135], v[172:175], v[118:121]
	v_mfma_f32_16x16x32_bf16 v[110:113], v[132:135], v[180:183], v[110:113]
	v_mfma_f32_16x16x32_bf16 v[110:113], v[136:139], v[184:187], v[110:113]
	v_mfma_f32_16x16x32_bf16 v[114:117], v[144:147], v[184:187], v[114:117]
	v_mfma_f32_16x16x32_bf16 v[114:117], v[140:143], v[180:183], v[114:117]
	v_mfma_f32_16x16x32_bf16 v[106:109], v[140:143], v[188:191], v[106:109]
	v_mfma_f32_16x16x32_bf16 v[106:109], v[144:147], v[226:229], v[106:109]
	v_mfma_f32_16x16x32_bf16 v[102:105], v[136:139], v[226:229], v[102:105]
	v_mfma_f32_16x16x32_bf16 v[102:105], v[132:135], v[188:191], v[102:105]
	s_setprio 0
	s_setprio 1
	v_mfma_f32_16x16x32_bf16 v[54:57], v[148:151], v[164:167], v[54:57]
	v_mfma_f32_16x16x32_bf16 v[54:57], v[152:155], v[168:171], v[54:57]
	v_mfma_f32_16x16x32_bf16 v[38:41], v[160:163], v[168:171], v[38:41]
	v_mfma_f32_16x16x32_bf16 v[38:41], v[156:159], v[164:167], v[38:41]
	v_mfma_f32_16x16x32_bf16 v[30:33], v[156:159], v[172:175], v[30:33]
	v_mfma_f32_16x16x32_bf16 v[30:33], v[160:163], v[176:179], v[30:33]
	v_mfma_f32_16x16x32_bf16 v[58:61], v[152:155], v[176:179], v[58:61]
	v_mfma_f32_16x16x32_bf16 v[58:61], v[148:151], v[172:175], v[58:61]
	v_mfma_f32_16x16x32_bf16 v[62:65], v[148:151], v[180:183], v[62:65]
	v_mfma_f32_16x16x32_bf16 v[62:65], v[152:155], v[184:187], v[62:65]
	v_mfma_f32_16x16x32_bf16 v[22:25], v[160:163], v[184:187], v[22:25]
	v_mfma_f32_16x16x32_bf16 v[22:25], v[156:159], v[180:183], v[22:25]
	v_mfma_f32_16x16x32_bf16 v[50:53], v[156:159], v[188:191], v[50:53]
	v_mfma_f32_16x16x32_bf16 v[50:53], v[160:163], v[226:229], v[50:53]
	v_mfma_f32_16x16x32_bf16 v[98:101], v[152:155], v[226:229], v[98:101]
	v_mfma_f32_16x16x32_bf16 v[98:101], v[148:151], v[188:191], v[98:101]
	s_barrier
; #define PG8_STAGE(bufoff, gbase, voff) do { _Pragma("unroll") for (int _i = 0; _i < 2; ++_i) \
;         __builtin_amdgcn_global_load_lds((const unsigned*)((const char*)(gbase) + (voff)[_i]), (PG8_LAS unsigned*)(lds + (bufoff) + ldsw + _i * 8192), 16, 0, 0); } while (0)
; #define PG8_LDA(dst, b, h) do { _Pragma("unroll") for (int m = 0; m < 4; ++m) _Pragma("unroll") for (int k = 0; k < 2; ++k) dst[m][k] = *(const PG8_LAS bf16x8*)(lds + PG8_SA(b, h) + aoff + m * 2048 + k * 1024); } while (0)
; #define PG8_MMA(ai, bj, At, Bt) do { __builtin_amdgcn_s_setprio(1); _Pragma("unroll") for (int m = 0; m < 4; ++m) _Pragma("unroll") for (int n = 0; n < 2; ++n) _Pragma("unroll") for (int k = 0; k < 2; ++k) \
;         acc[ai][bj][m][n] = __builtin_amdgcn_mfma_f32_16x16x32_bf16(Bt[n][k], At[m][k], acc[ai][bj][m][n], 0, 0, 0); __builtin_amdgcn_s_setprio(0); } while (0)
; #define PG8_WAIT_V(n) asm volatile("s_waitcnt vmcnt(" #n ")" ::: "memory")
; #define PG8_WAIT_L(n) asm volatile("s_waitcnt lgkmcnt(" #n ")" ::: "memory")
; #define PG8_BAR __builtin_amdgcn_s_barrier()
; #define PG8_SCHED __builtin_amdgcn_sched_barrier(0)
; template <class Epi, class Sched, bool ALIGN_EPI = false, bool SP2 = false>
; __device__ __forceinline__ void gemm_phase(PG8_LAS unsigned char* lds, const Gemm g, const Sched& S, const Epi& E) {
;     ...
;         for (int t = 0; t < nt; t += 2) {
;     ...
;             PG8_LDA(At, 1, 1); PG8_STAGE(PG8_SB(1, 0), b3, voffB); PG8_STAGE(PG8_SB(1, 1), b3 + hstep, voffB); PG8_STAGE(PG8_SA(1, 0), a3, voffA);
;             PG8_WAIT_V(8); PG8_WAIT_L(0); PG8_BAR; PG8_MMA(1, 0, At, B0); PG8_MMA(1, 1, At, B1); PG8_BAR; PG8_SCHED;
	s_setprio 0
	s_add_i32 s34, s50, s45
	v_lshl_add_u64 v[192:193], v[192:193], 0, s[54:55]
	s_mov_b32 m0, s34
	ds_read_b128 v[164:167], v242 offset:49152
	ds_read_b128 v[168:171], v242 offset:50176
	ds_read_b128 v[172:175], v242 offset:51200
	ds_read_b128 v[176:179], v242 offset:52224
	ds_read_b128 v[180:183], v242 offset:53248
	ds_read_b128 v[184:187], v242 offset:54272
	ds_read_b128 v[188:191], v242 offset:55296
	ds_read_b128 v[226:229], v242 offset:56320
	global_load_lds_dwordx4 v[192:193], off
	s_add_i32 m0, s34, 0x2000
	s_add_u32 s34, s84, 0x100080
	v_lshl_add_u64 v[192:193], v[194:195], 0, s[54:55]
	s_addc_u32 s35, s85, 0
	s_add_i32 s50, s56, s45
	global_load_lds_dwordx4 v[192:193], off
	v_lshl_add_u64 v[192:193], s[34:35], 0, v[208:209]
	s_mov_b32 m0, s50
	s_nop 0
	global_load_lds_dwordx4 v[192:193], off
	v_lshl_add_u64 v[192:193], s[34:35], 0, v[212:213]
	s_add_i32 m0, s50, 0x2000
	s_nop 0
	global_load_lds_dwordx4 v[192:193], off
	v_lshl_add_u64 v[192:193], v[230:231], 0, s[54:55]
	s_mov_b32 m0, s39
	s_nop 0
	global_load_lds_dwordx4 v[192:193], off
	v_lshl_add_u64 v[192:193], v[232:233], 0, s[54:55]
	s_mov_b32 m0, s46
	s_nop 0
	global_load_lds_dwordx4 v[192:193], off
	s_waitcnt vmcnt(8)
	s_waitcnt lgkmcnt(0)
	s_setprio 1
	s_barrier
	v_mfma_f32_16x16x32_bf16 v[78:81], v[132:135], v[164:167], v[78:81]
	v_mfma_f32_16x16x32_bf16 v[78:81], v[136:139], v[168:171], v[78:81]
	v_mfma_f32_16x16x32_bf16 v[14:17], v[144:147], v[168:171], v[14:17]
	v_mfma_f32_16x16x32_bf16 v[14:17], v[140:143], v[164:167], v[14:17]
	v_mfma_f32_16x16x32_bf16 v[94:97], v[140:143], v[172:175], v[94:97]
	v_mfma_f32_16x16x32_bf16 v[94:97], v[144:147], v[176:179], v[94:97]
	v_mfma_f32_16x16x32_bf16 v[66:69], v[136:139], v[176:179], v[66:69]
	v_mfma_f32_16x16x32_bf16 v[66:69], v[132:135], v[172:175], v[66:69]
	v_mfma_f32_16x16x32_bf16 v[70:73], v[132:135], v[180:183], v[70:73]
	v_mfma_f32_16x16x32_bf16 v[70:73], v[136:139], v[184:187], v[70:73]
	v_mfma_f32_16x16x32_bf16 v[90:93], v[144:147], v[184:187], v[90:93]
	v_mfma_f32_16x16x32_bf16 v[90:93], v[140:143], v[180:183], v[90:93]
	v_mfma_f32_16x16x32_bf16 v[10:13], v[140:143], v[188:191], v[10:13]
	v_mfma_f32_16x16x32_bf16 v[10:13], v[144:147], v[226:229], v[10:13]
	v_mfma_f32_16x16x32_bf16 v[74:77], v[136:139], v[226:229], v[74:77]
	v_mfma_f32_16x16x32_bf16 v[74:77], v[132:135], v[188:191], v[74:77]
	s_setprio 0
	s_setprio 1
	v_mfma_f32_16x16x32_bf16 v[42:45], v[148:151], v[164:167], v[42:45]
	v_mfma_f32_16x16x32_bf16 v[42:45], v[152:155], v[168:171], v[42:45]
	v_mfma_f32_16x16x32_bf16 v[2:5], v[160:163], v[168:171], v[2:5]
	v_mfma_f32_16x16x32_bf16 v[2:5], v[156:159], v[164:167], v[2:5]
	v_mfma_f32_16x16x32_bf16 v[6:9], v[156:159], v[172:175], v[6:9]
	v_mfma_f32_16x16x32_bf16 v[6:9], v[160:163], v[176:179], v[6:9]
	v_mfma_f32_16x16x32_bf16 v[34:37], v[152:155], v[176:179], v[34:37]
	v_mfma_f32_16x16x32_bf16 v[34:37], v[148:151], v[172:175], v[34:37]
	v_mfma_f32_16x16x32_bf16 v[86:89], v[148:151], v[180:183], v[86:89]
	v_mfma_f32_16x16x32_bf16 v[86:89], v[152:155], v[184:187], v[86:89]
	v_mfma_f32_16x16x32_bf16 v[26:29], v[160:163], v[184:187], v[26:29]
	v_mfma_f32_16x16x32_bf16 v[26:29], v[156:159], v[180:183], v[26:29]
	v_mfma_f32_16x16x32_bf16 v[18:21], v[156:159], v[188:191], v[18:21]
	v_mfma_f32_16x16x32_bf16 v[18:21], v[160:163], v[226:229], v[18:21]
	v_mfma_f32_16x16x32_bf16 v[82:85], v[152:155], v[226:229], v[82:85]
	v_mfma_f32_16x16x32_bf16 v[82:85], v[148:151], v[188:191], v[82:85]
	s_barrier
	s_setprio 0
	s_add_i32 s89, s89, 2
	s_add_u32 s82, s82, 0x100
	s_addc_u32 s83, s83, 0
	s_add_u32 s79, s79, 0x100
	s_addc_u32 s88, s88, 0
	s_cmp_gt_u32 s89, 61
	s_cbranch_scc1 .LBB0_1490

; #define PG8_STAGE(bufoff, gbase, voff) do { _Pragma("unroll") for (int _i = 0; _i < 2; ++_i) \
;         __builtin_amdgcn_global_load_lds((const unsigned*)((const char*)(gbase) + (voff)[_i]), (PG8_LAS unsigned*)(lds + (bufoff) + ldsw + _i * 8192), 16, 0, 0); } while (0)
; #define PG8_LDA(dst, b, h) do { _Pragma("unroll") for (int m = 0; m < 4; ++m) _Pragma("unroll") for (int k = 0; k < 2; ++k) dst[m][k] = *(const PG8_LAS bf16x8*)(lds + PG8_SA(b, h) + aoff + m * 2048 + k * 1024); } while (0)
; #define PG8_LDB(dst, b, h) do { _Pragma("unroll") for (int n = 0; n < 2; ++n) _Pragma("unroll") for (int k = 0; k < 2; ++k) dst[n][k] = *(const PG8_LAS bf16x8*)(lds + PG8_SB(b, h) + boff + n * 2048 + k * 1024); } while (0)
; #define PG8_MMA(ai, bj, At, Bt) do { __builtin_amdgcn_s_setprio(1); _Pragma("unroll") for (int m = 0; m < 4; ++m) _Pragma("unroll") for (int n = 0; n < 2; ++n) _Pragma("unroll") for (int k = 0; k < 2; ++k) \
;         acc[ai][bj][m][n] = __builtin_amdgcn_mfma_f32_16x16x32_bf16(Bt[n][k], At[m][k], acc[ai][bj][m][n], 0, 0, 0); __builtin_amdgcn_s_setprio(0); } while (0)
; #define PG8_WAIT_V(n) asm volatile("s_waitcnt vmcnt(" #n ")" ::: "memory")
; #define PG8_WAIT_L(n) asm volatile("s_waitcnt lgkmcnt(" #n ")" ::: "memory")
; template <class Epi, class Sched, bool ALIGN_EPI = false, bool SP2 = false>
; __device__ __forceinline__ void gemm_phase(PG8_LAS unsigned char* lds, const Gemm g, const Sched& S, const Epi& E) {
;     ...
;             const bool last = (t == nt - 2);
;             const char* a1 = cA + (size_t)(t + 1) * kstep;
;             const char* a2 = last ? nA : cA + (size_t)(t + 2) * kstep; const char* b2 = last ? nB : cB + (size_t)(t + 2) * kstep;
;             const char* a3 = a2 + kstep; const char* b3 = b2 + kstep;
;             if (last && has_next) S.a_ready(nxt);
;             if constexpr (SP2) {
;             PG8_LDB(B0, 0, 0); PG8_LDB(B1, 0, 1); PG8_SCHED; PG8_LDA(At, 0, 0); PG8_STAGE(PG8_SA(1, 1), a1 + hstep, voffA);
;             PG8_WAIT_V(8); PG8_WAIT_L(0); PG8_BAR; PG8_MMA(0, 0, At, B0); PG8_MMA(0, 1, At, B1); PG8_BAR; PG8_SCHED;
;             PG8_LDA(At, 0, 1); PG8_STAGE(PG8_SB(0, 0), b2, voffB); PG8_STAGE(PG8_SB(0, 1), b2 + hstep, voffB); PG8_STAGE(PG8_SA(0, 0), a2, voffA);
;             PG8_WAIT_V(8); PG8_WAIT_L(0); PG8_BAR; PG8_MMA(1, 0, At, B0); PG8_MMA(1, 1, At, B1); PG8_BAR; PG8_SCHED;
.LBB0_1731:
	ds_read_b128 v[170:173], v166
	ds_read_b128 v[174:177], v166 offset:1024
	ds_read_b128 v[178:181], v166 offset:2048
	ds_read_b128 v[182:185], v166 offset:3072
	ds_read_b128 v[186:189], v167
	ds_read_b128 v[190:193], v167 offset:1024
	ds_read_b128 v[196:199], v167 offset:2048
	ds_read_b128 v[202:205], v167 offset:3072
	s_add_u32 s48, s40, 0x100
	s_addc_u32 s49, s41, 0
	s_cmpk_eq_i32 s56, 0xa8
	s_cselect_b32 s53, s7, s49
	s_cselect_b32 s52, s6, s48
	s_cselect_b32 s51, s39, s55
	s_cselect_b32 s50, s38, s54
	v_lshl_add_u64 v[146:147], s[40:41], 0, v[138:139]
	s_add_i32 m0, s16, 0xc000
	ds_read_b128 v[206:209], v168
	ds_read_b128 v[210:213], v168 offset:1024
	ds_read_b128 v[214:217], v168 offset:2048
	ds_read_b128 v[218:221], v168 offset:3072
	ds_read_b128 v[222:225], v168 offset:4096
	ds_read_b128 v[226:229], v168 offset:5120
	ds_read_b128 v[230:233], v168 offset:6144
	ds_read_b128 v[234:237], v168 offset:7168
	global_load_lds_dwordx4 v[146:147], off
	v_lshl_add_u64 v[146:147], s[40:41], 0, v[140:141]
	s_add_i32 m0, s16, 0xe000
	s_nop 0
	global_load_lds_dwordx4 v[146:147], off
	s_waitcnt vmcnt(8)
	s_waitcnt lgkmcnt(0)
	s_setprio 1
	s_barrier
	v_mfma_f32_16x16x32_bf16 v[126:129], v[170:173], v[206:209], v[126:129]
	v_mfma_f32_16x16x32_bf16 v[126:129], v[174:177], v[210:213], v[126:129]
	v_mfma_f32_16x16x32_bf16 v[122:125], v[182:185], v[210:213], v[122:125]
	v_mfma_f32_16x16x32_bf16 v[122:125], v[178:181], v[206:209], v[122:125]
	v_mfma_f32_16x16x32_bf16 v[106:109], v[178:181], v[214:217], v[106:109]
	v_mfma_f32_16x16x32_bf16 v[106:109], v[182:185], v[218:221], v[106:109]
	v_mfma_f32_16x16x32_bf16 v[110:113], v[174:177], v[218:221], v[110:113]
	v_mfma_f32_16x16x32_bf16 v[110:113], v[170:173], v[214:217], v[110:113]
	v_mfma_f32_16x16x32_bf16 v[94:97], v[170:173], v[222:225], v[94:97]
	v_mfma_f32_16x16x32_bf16 v[94:97], v[174:177], v[226:229], v[94:97]
	v_mfma_f32_16x16x32_bf16 v[90:93], v[182:185], v[226:229], v[90:93]
	v_mfma_f32_16x16x32_bf16 v[90:93], v[178:181], v[222:225], v[90:93]
	v_mfma_f32_16x16x32_bf16 v[74:77], v[178:181], v[230:233], v[74:77]
	v_mfma_f32_16x16x32_bf16 v[74:77], v[182:185], v[234:237], v[74:77]
	v_mfma_f32_16x16x32_bf16 v[78:81], v[174:177], v[234:237], v[78:81]
	v_mfma_f32_16x16x32_bf16 v[78:81], v[170:173], v[230:233], v[78:81]
	s_setprio 0
	s_setprio 1
	v_mfma_f32_16x16x32_bf16 v[118:121], v[186:189], v[206:209], v[118:121]
	v_mfma_f32_16x16x32_bf16 v[118:121], v[190:193], v[210:213], v[118:121]
	v_mfma_f32_16x16x32_bf16 v[114:117], v[202:205], v[210:213], v[114:117]
	v_mfma_f32_16x16x32_bf16 v[114:117], v[196:199], v[206:209], v[114:117]
	v_mfma_f32_16x16x32_bf16 v[98:101], v[196:199], v[214:217], v[98:101]
	v_mfma_f32_16x16x32_bf16 v[98:101], v[202:205], v[218:221], v[98:101]
	v_mfma_f32_16x16x32_bf16 v[102:105], v[190:193], v[218:221], v[102:105]
	v_mfma_f32_16x16x32_bf16 v[102:105], v[186:189], v[214:217], v[102:105]
	v_mfma_f32_16x16x32_bf16 v[86:89], v[186:189], v[222:225], v[86:89]
	v_mfma_f32_16x16x32_bf16 v[86:89], v[190:193], v[226:229], v[86:89]
	v_mfma_f32_16x16x32_bf16 v[82:85], v[202:205], v[226:229], v[82:85]
	v_mfma_f32_16x16x32_bf16 v[82:85], v[196:199], v[222:225], v[82:85]
	v_mfma_f32_16x16x32_bf16 v[66:69], v[196:199], v[230:233], v[66:69]
	v_mfma_f32_16x16x32_bf16 v[66:69], v[202:205], v[234:237], v[66:69]
	v_mfma_f32_16x16x32_bf16 v[70:73], v[190:193], v[234:237], v[70:73]
	v_mfma_f32_16x16x32_bf16 v[70:73], v[186:189], v[230:233], v[70:73]
	s_barrier
	s_setprio 0
	s_add_i32 s40, s31, s3
	v_lshl_add_u64 v[146:147], s[50:51], 0, v[132:133]
	s_mov_b32 m0, s40
	ds_read_b128 v[206:209], v168 offset:16384
	ds_read_b128 v[210:213], v168 offset:17408
	ds_read_b128 v[214:217], v168 offset:18432
	ds_read_b128 v[218:221], v168 offset:19456
	ds_read_b128 v[222:225], v168 offset:20480
	ds_read_b128 v[226:229], v168 offset:21504
	ds_read_b128 v[230:233], v168 offset:22528
	ds_read_b128 v[234:237], v168 offset:23552
	global_load_lds_dwordx4 v[146:147], off
	s_add_i32 m0, s40, 0x2000
	s_add_u32 s40, s50, 0x2b0000
	v_lshl_add_u64 v[194:195], s[50:51], 0, v[136:137]
	s_addc_u32 s41, s51, 0
	s_add_i32 s57, s35, s3
	global_load_lds_dwordx4 v[194:195], off
	v_lshl_add_u64 v[238:239], s[40:41], 0, v[132:133]
	s_mov_b32 m0, s57
	v_lshl_add_u64 v[240:241], s[52:53], 0, v[134:135]
	global_load_lds_dwordx4 v[238:239], off
	v_lshl_add_u64 v[238:239], s[40:41], 0, v[136:137]
	s_add_i32 m0, s57, 0x2000
	s_nop 0
	global_load_lds_dwordx4 v[238:239], off
	v_lshl_add_u64 v[238:239], s[52:53], 0, v[130:131]
	s_mov_b32 m0, s16
	s_nop 0
	global_load_lds_dwordx4 v[238:239], off
	s_mov_b32 m0, s17
	s_nop 0
	global_load_lds_dwordx4 v[240:241], off
	s_waitcnt vmcnt(8)
	s_waitcnt lgkmcnt(0)
	s_setprio 1
	s_barrier
; #define PG8_STAGE(bufoff, gbase, voff) do { _Pragma("unroll") for (int _i = 0; _i < 2; ++_i) \
;         __builtin_amdgcn_global_load_lds((const unsigned*)((const char*)(gbase) + (voff)[_i]), (PG8_LAS unsigned*)(lds + (bufoff) + ldsw + _i * 8192), 16, 0, 0); } while (0)
; #define PG8_LDA(dst, b, h) do { _Pragma("unroll") for (int m = 0; m < 4; ++m) _Pragma("unroll") for (int k = 0; k < 2; ++k) dst[m][k] = *(const PG8_LAS bf16x8*)(lds + PG8_SA(b, h) + aoff + m * 2048 + k * 1024); } while (0)
; #define PG8_LDB(dst, b, h) do { _Pragma("unroll") for (int n = 0; n < 2; ++n) _Pragma("unroll") for (int k = 0; k < 2; ++k) dst[n][k] = *(const PG8_LAS bf16x8*)(lds + PG8_SB(b, h) + boff + n * 2048 + k * 1024); } while (0)
; #define PG8_MMA(ai, bj, At, Bt) do { __builtin_amdgcn_s_setprio(1); _Pragma("unroll") for (int m = 0; m < 4; ++m) _Pragma("unroll") for (int n = 0; n < 2; ++n) _Pragma("unroll") for (int k = 0; k < 2; ++k) \
;         acc[ai][bj][m][n] = __builtin_amdgcn_mfma_f32_16x16x32_bf16(Bt[n][k], At[m][k], acc[ai][bj][m][n], 0, 0, 0); __builtin_amdgcn_s_setprio(0); } while (0)
; #define PG8_WAIT_V(n) asm volatile("s_waitcnt vmcnt(" #n ")" ::: "memory")
; #define PG8_WAIT_L(n) asm volatile("s_waitcnt lgkmcnt(" #n ")" ::: "memory")
; #define PG8_BAR __builtin_amdgcn_s_barrier()
; #define PG8_SCHED __builtin_amdgcn_sched_barrier(0)
; template <class Epi, class Sched, bool ALIGN_EPI = false, bool SP2 = false>
; __device__ __forceinline__ void gemm_phase(PG8_LAS unsigned char* lds, const Gemm g, const Sched& S, const Epi& E) {
;     ...
;             PG8_WAIT_V(8); PG8_WAIT_L(0); PG8_BAR; PG8_MMA(1, 0, At, B0); PG8_MMA(1, 1, At, B1); PG8_BAR; PG8_SCHED;
;             PG8_LDB(B0, 1, 0); PG8_LDB(B1, 1, 1); PG8_SCHED; PG8_LDA(At, 1, 0); PG8_STAGE(PG8_SA(0, 1), a2 + hstep, voffA);
;             PG8_WAIT_V(8); PG8_WAIT_L(0); PG8_BAR; PG8_MMA(0, 0, At, B0); PG8_MMA(0, 1, At, B1); PG8_BAR; PG8_SCHED;
	v_mfma_f32_16x16x32_bf16 v[62:65], v[170:173], v[206:209], v[62:65]
	v_mfma_f32_16x16x32_bf16 v[62:65], v[174:177], v[210:213], v[62:65]
	v_mfma_f32_16x16x32_bf16 v[58:61], v[182:185], v[210:213], v[58:61]
	v_mfma_f32_16x16x32_bf16 v[58:61], v[178:181], v[206:209], v[58:61]
	v_mfma_f32_16x16x32_bf16 v[42:45], v[178:181], v[214:217], v[42:45]
	v_mfma_f32_16x16x32_bf16 v[42:45], v[182:185], v[218:221], v[42:45]
	v_mfma_f32_16x16x32_bf16 v[46:49], v[174:177], v[218:221], v[46:49]
	v_mfma_f32_16x16x32_bf16 v[46:49], v[170:173], v[214:217], v[46:49]
	v_mfma_f32_16x16x32_bf16 v[30:33], v[170:173], v[222:225], v[30:33]
	v_mfma_f32_16x16x32_bf16 v[30:33], v[174:177], v[226:229], v[30:33]
	v_mfma_f32_16x16x32_bf16 v[26:29], v[182:185], v[226:229], v[26:29]
	v_mfma_f32_16x16x32_bf16 v[26:29], v[178:181], v[222:225], v[26:29]
	v_mfma_f32_16x16x32_bf16 v[10:13], v[178:181], v[230:233], v[10:13]
	v_mfma_f32_16x16x32_bf16 v[10:13], v[182:185], v[234:237], v[10:13]
	v_mfma_f32_16x16x32_bf16 v[14:17], v[174:177], v[234:237], v[14:17]
	v_mfma_f32_16x16x32_bf16 v[14:17], v[170:173], v[230:233], v[14:17]
	s_setprio 0
	s_setprio 1
	v_mfma_f32_16x16x32_bf16 v[54:57], v[186:189], v[206:209], v[54:57]
	v_mfma_f32_16x16x32_bf16 v[54:57], v[190:193], v[210:213], v[54:57]
	v_mfma_f32_16x16x32_bf16 v[50:53], v[202:205], v[210:213], v[50:53]
	v_mfma_f32_16x16x32_bf16 v[50:53], v[196:199], v[206:209], v[50:53]
	v_mfma_f32_16x16x32_bf16 v[34:37], v[196:199], v[214:217], v[34:37]
	v_mfma_f32_16x16x32_bf16 v[34:37], v[202:205], v[218:221], v[34:37]
	v_mfma_f32_16x16x32_bf16 v[38:41], v[190:193], v[218:221], v[38:41]
	v_mfma_f32_16x16x32_bf16 v[38:41], v[186:189], v[214:217], v[38:41]
	v_mfma_f32_16x16x32_bf16 v[22:25], v[186:189], v[222:225], v[22:25]
	v_mfma_f32_16x16x32_bf16 v[22:25], v[190:193], v[226:229], v[22:25]
	v_mfma_f32_16x16x32_bf16 v[18:21], v[202:205], v[226:229], v[18:21]
	v_mfma_f32_16x16x32_bf16 v[18:21], v[196:199], v[222:225], v[18:21]
	v_mfma_f32_16x16x32_bf16 v[2:5], v[196:199], v[230:233], v[2:5]
	v_mfma_f32_16x16x32_bf16 v[2:5], v[202:205], v[234:237], v[2:5]
	v_mfma_f32_16x16x32_bf16 v[6:9], v[190:193], v[234:237], v[6:9]
	v_mfma_f32_16x16x32_bf16 v[6:9], v[186:189], v[230:233], v[6:9]
	s_barrier
	s_setprio 0
	s_add_i32 s57, 0, 0x18000
	v_add_u32_e32 v169, s57, v148
	s_add_i32 s58, 0, 0x1c000
	ds_read_b128 v[170:173], v169
	ds_read_b128 v[174:177], v169 offset:1024
	ds_read_b128 v[178:181], v169 offset:2048
	ds_read_b128 v[182:185], v169 offset:3072
	v_add_u32_e32 v169, s58, v148
	ds_read_b128 v[186:189], v169
	ds_read_b128 v[190:193], v169 offset:1024
	ds_read_b128 v[196:199], v169 offset:2048
	ds_read_b128 v[202:205], v169 offset:3072
	s_add_u32 s40, s52, 0x2b0000
	s_addc_u32 s41, s53, 0
	s_mov_b32 m0, s25
	v_lshl_add_u64 v[242:243], s[40:41], 0, v[130:131]
	ds_read_b128 v[206:209], v168 offset:32768
	ds_read_b128 v[210:213], v168 offset:33792
	ds_read_b128 v[214:217], v168 offset:34816
	ds_read_b128 v[218:221], v168 offset:35840
	ds_read_b128 v[222:225], v168 offset:36864
	ds_read_b128 v[226:229], v168 offset:37888
	ds_read_b128 v[230:233], v168 offset:38912
	ds_read_b128 v[234:237], v168 offset:39936
	global_load_lds_dwordx4 v[242:243], off
	v_lshl_add_u64 v[242:243], s[40:41], 0, v[134:135]
	s_mov_b32 m0, s26
	s_nop 0
	global_load_lds_dwordx4 v[242:243], off
	s_waitcnt vmcnt(8)
	s_waitcnt lgkmcnt(0)
	s_setprio 1
	s_barrier
	v_mfma_f32_16x16x32_bf16 v[126:129], v[170:173], v[206:209], v[126:129]
	v_mfma_f32_16x16x32_bf16 v[126:129], v[174:177], v[210:213], v[126:129]
	v_mfma_f32_16x16x32_bf16 v[122:125], v[182:185], v[210:213], v[122:125]
	v_mfma_f32_16x16x32_bf16 v[122:125], v[178:181], v[206:209], v[122:125]
	v_mfma_f32_16x16x32_bf16 v[106:109], v[178:181], v[214:217], v[106:109]
	v_mfma_f32_16x16x32_bf16 v[106:109], v[182:185], v[218:221], v[106:109]
	v_mfma_f32_16x16x32_bf16 v[110:113], v[174:177], v[218:221], v[110:113]
	v_mfma_f32_16x16x32_bf16 v[110:113], v[170:173], v[214:217], v[110:113]
	v_mfma_f32_16x16x32_bf16 v[94:97], v[170:173], v[222:225], v[94:97]
	v_mfma_f32_16x16x32_bf16 v[94:97], v[174:177], v[226:229], v[94:97]
	v_mfma_f32_16x16x32_bf16 v[90:93], v[182:185], v[226:229], v[90:93]
	v_mfma_f32_16x16x32_bf16 v[90:93], v[178:181], v[222:225], v[90:93]
	v_mfma_f32_16x16x32_bf16 v[74:77], v[178:181], v[230:233], v[74:77]
	v_mfma_f32_16x16x32_bf16 v[74:77], v[182:185], v[234:237], v[74:77]
	v_mfma_f32_16x16x32_bf16 v[78:81], v[174:177], v[234:237], v[78:81]
	v_mfma_f32_16x16x32_bf16 v[78:81], v[170:173], v[230:233], v[78:81]
	s_setprio 0
	s_setprio 1
	v_mfma_f32_16x16x32_bf16 v[118:121], v[186:189], v[206:209], v[118:121]
	v_mfma_f32_16x16x32_bf16 v[118:121], v[190:193], v[210:213], v[118:121]
	v_mfma_f32_16x16x32_bf16 v[114:117], v[202:205], v[210:213], v[114:117]
	v_mfma_f32_16x16x32_bf16 v[114:117], v[196:199], v[206:209], v[114:117]
	v_mfma_f32_16x16x32_bf16 v[98:101], v[196:199], v[214:217], v[98:101]
	v_mfma_f32_16x16x32_bf16 v[98:101], v[202:205], v[218:221], v[98:101]
	v_mfma_f32_16x16x32_bf16 v[102:105], v[190:193], v[218:221], v[102:105]
	v_mfma_f32_16x16x32_bf16 v[102:105], v[186:189], v[214:217], v[102:105]
	v_mfma_f32_16x16x32_bf16 v[86:89], v[186:189], v[222:225], v[86:89]
	v_mfma_f32_16x16x32_bf16 v[86:89], v[190:193], v[226:229], v[86:89]
	v_mfma_f32_16x16x32_bf16 v[82:85], v[202:205], v[226:229], v[82:85]
	v_mfma_f32_16x16x32_bf16 v[82:85], v[196:199], v[222:225], v[82:85]
	v_mfma_f32_16x16x32_bf16 v[66:69], v[196:199], v[230:233], v[66:69]
	v_mfma_f32_16x16x32_bf16 v[66:69], v[202:205], v[234:237], v[66:69]
	v_mfma_f32_16x16x32_bf16 v[70:73], v[190:193], v[234:237], v[70:73]
	v_mfma_f32_16x16x32_bf16 v[70:73], v[186:189], v[230:233], v[70:73]
	s_barrier
; #define PG8_STAGE(bufoff, gbase, voff) do { _Pragma("unroll") for (int _i = 0; _i < 2; ++_i) \
;         __builtin_amdgcn_global_load_lds((const unsigned*)((const char*)(gbase) + (voff)[_i]), (PG8_LAS unsigned*)(lds + (bufoff) + ldsw + _i * 8192), 16, 0, 0); } while (0)
; #define PG8_LDA(dst, b, h) do { _Pragma("unroll") for (int m = 0; m < 4; ++m) _Pragma("unroll") for (int k = 0; k < 2; ++k) dst[m][k] = *(const PG8_LAS bf16x8*)(lds + PG8_SA(b, h) + aoff + m * 2048 + k * 1024); } while (0)
; #define PG8_MMA(ai, bj, At, Bt) do { __builtin_amdgcn_s_setprio(1); _Pragma("unroll") for (int m = 0; m < 4; ++m) _Pragma("unroll") for (int n = 0; n < 2; ++n) _Pragma("unroll") for (int k = 0; k < 2; ++k) \
;         acc[ai][bj][m][n] = __builtin_amdgcn_mfma_f32_16x16x32_bf16(Bt[n][k], At[m][k], acc[ai][bj][m][n], 0, 0, 0); __builtin_amdgcn_s_setprio(0); } while (0)
; #define PG8_WAIT_V(n) asm volatile("s_waitcnt vmcnt(" #n ")" ::: "memory")
; #define PG8_WAIT_L(n) asm volatile("s_waitcnt lgkmcnt(" #n ")" ::: "memory")
; #define PG8_BAR __builtin_amdgcn_s_barrier()
; #define PG8_SCHED __builtin_amdgcn_sched_barrier(0)
; template <class Epi, class Sched, bool ALIGN_EPI = false, bool SP2 = false>
; __device__ __forceinline__ void gemm_phase(PG8_LAS unsigned char* lds, const Gemm g, const Sched& S, const Epi& E) {
;     ...
;             PG8_LDA(At, 1, 1); PG8_STAGE(PG8_SB(1, 0), b3, voffB); PG8_STAGE(PG8_SB(1, 1), b3 + hstep, voffB); PG8_STAGE(PG8_SA(1, 0), a3, voffA);
;             PG8_WAIT_V(8); PG8_WAIT_L(0); PG8_BAR; PG8_MMA(1, 0, At, B0); PG8_MMA(1, 1, At, B1); PG8_BAR; PG8_SCHED;
;     ...
;         if constexpr (ALIGN_EPI) { if (wr == 0) PG8_BAR; }
	s_setprio 0
	s_add_i32 s40, s57, s3
	v_lshl_add_u64 v[146:147], v[146:147], 0, s[10:11]
	s_mov_b32 m0, s40
	ds_read_b128 v[206:209], v168 offset:49152
	ds_read_b128 v[210:213], v168 offset:50176
	ds_read_b128 v[214:217], v168 offset:51200
	ds_read_b128 v[218:221], v168 offset:52224
	ds_read_b128 v[222:225], v168 offset:53248
	ds_read_b128 v[226:229], v168 offset:54272
	ds_read_b128 v[230:233], v168 offset:55296
	ds_read_b128 v[234:237], v168 offset:56320
	global_load_lds_dwordx4 v[146:147], off
	s_add_i32 m0, s40, 0x2000
	s_add_u32 s40, s50, 0x2b0080
	v_lshl_add_u64 v[146:147], v[194:195], 0, s[10:11]
	s_addc_u32 s41, s51, 0
	s_add_i32 s50, s58, s3
	global_load_lds_dwordx4 v[146:147], off
	v_lshl_add_u64 v[146:147], s[40:41], 0, v[132:133]
	s_mov_b32 m0, s50
	s_nop 0
	global_load_lds_dwordx4 v[146:147], off
	v_lshl_add_u64 v[146:147], s[40:41], 0, v[136:137]
	s_add_i32 m0, s50, 0x2000
	s_nop 0
	global_load_lds_dwordx4 v[146:147], off
	v_lshl_add_u64 v[146:147], v[238:239], 0, s[10:11]
	s_mov_b32 m0, s28
	s_nop 0
	global_load_lds_dwordx4 v[146:147], off
	v_lshl_add_u64 v[146:147], v[240:241], 0, s[10:11]
	s_mov_b32 m0, s29
	s_nop 0
	global_load_lds_dwordx4 v[146:147], off
	s_waitcnt vmcnt(8)
	s_waitcnt lgkmcnt(0)
	s_setprio 1
	s_barrier
	v_mfma_f32_16x16x32_bf16 v[62:65], v[170:173], v[206:209], v[62:65]
	v_mfma_f32_16x16x32_bf16 v[62:65], v[174:177], v[210:213], v[62:65]
	v_mfma_f32_16x16x32_bf16 v[58:61], v[182:185], v[210:213], v[58:61]
	v_mfma_f32_16x16x32_bf16 v[58:61], v[178:181], v[206:209], v[58:61]
	v_mfma_f32_16x16x32_bf16 v[42:45], v[178:181], v[214:217], v[42:45]
	v_mfma_f32_16x16x32_bf16 v[42:45], v[182:185], v[218:221], v[42:45]
	v_mfma_f32_16x16x32_bf16 v[46:49], v[174:177], v[218:221], v[46:49]
	v_mfma_f32_16x16x32_bf16 v[46:49], v[170:173], v[214:217], v[46:49]
	v_mfma_f32_16x16x32_bf16 v[30:33], v[170:173], v[222:225], v[30:33]
	v_mfma_f32_16x16x32_bf16 v[30:33], v[174:177], v[226:229], v[30:33]
	v_mfma_f32_16x16x32_bf16 v[26:29], v[182:185], v[226:229], v[26:29]
	v_mfma_f32_16x16x32_bf16 v[26:29], v[178:181], v[222:225], v[26:29]
	v_mfma_f32_16x16x32_bf16 v[10:13], v[178:181], v[230:233], v[10:13]
	v_mfma_f32_16x16x32_bf16 v[10:13], v[182:185], v[234:237], v[10:13]
	v_mfma_f32_16x16x32_bf16 v[14:17], v[174:177], v[234:237], v[14:17]
	v_mfma_f32_16x16x32_bf16 v[14:17], v[170:173], v[230:233], v[14:17]
	s_setprio 0
	s_setprio 1
	v_mfma_f32_16x16x32_bf16 v[54:57], v[186:189], v[206:209], v[54:57]
	v_mfma_f32_16x16x32_bf16 v[54:57], v[190:193], v[210:213], v[54:57]
	v_mfma_f32_16x16x32_bf16 v[50:53], v[202:205], v[210:213], v[50:53]
	v_mfma_f32_16x16x32_bf16 v[50:53], v[196:199], v[206:209], v[50:53]
	v_mfma_f32_16x16x32_bf16 v[34:37], v[196:199], v[214:217], v[34:37]
	v_mfma_f32_16x16x32_bf16 v[34:37], v[202:205], v[218:221], v[34:37]
	v_mfma_f32_16x16x32_bf16 v[38:41], v[190:193], v[218:221], v[38:41]
	v_mfma_f32_16x16x32_bf16 v[38:41], v[186:189], v[214:217], v[38:41]
	v_mfma_f32_16x16x32_bf16 v[22:25], v[186:189], v[222:225], v[22:25]
	v_mfma_f32_16x16x32_bf16 v[22:25], v[190:193], v[226:229], v[22:25]
	v_mfma_f32_16x16x32_bf16 v[18:21], v[202:205], v[226:229], v[18:21]
	v_mfma_f32_16x16x32_bf16 v[18:21], v[196:199], v[222:225], v[18:21]
	v_mfma_f32_16x16x32_bf16 v[2:5], v[196:199], v[230:233], v[2:5]
	v_mfma_f32_16x16x32_bf16 v[2:5], v[202:205], v[234:237], v[2:5]
	v_mfma_f32_16x16x32_bf16 v[6:9], v[190:193], v[234:237], v[6:9]
	v_mfma_f32_16x16x32_bf16 v[6:9], v[186:189], v[230:233], v[6:9]
	s_barrier
	s_setprio 0
	s_add_i32 s56, s56, 2
	s_add_u32 s54, s54, 0x100
	s_addc_u32 s55, s55, 0
	s_cmpk_gt_u32 s56, 0xa9
	s_mov_b64 s[40:41], s[48:49]
	s_cbranch_scc0 .LBB0_1731
	s_and_b64 vcc, exec, s[12:13]
	s_cbranch_vccz .LBB0_1734
	s_barrier

; #define PG8_STAGE(bufoff, gbase, voff) do { _Pragma("unroll") for (int _i = 0; _i < 2; ++_i) \
;         __builtin_amdgcn_global_load_lds((const unsigned*)((const char*)(gbase) + (voff)[_i]), (PG8_LAS unsigned*)(lds + (bufoff) + ldsw + _i * 8192), 16, 0, 0); } while (0)
; #define PG8_LDA(dst, b, h) do { _Pragma("unroll") for (int m = 0; m < 4; ++m) _Pragma("unroll") for (int k = 0; k < 2; ++k) dst[m][k] = *(const PG8_LAS bf16x8*)(lds + PG8_SA(b, h) + aoff + m * 2048 + k * 1024); } while (0)
; #define PG8_LDB(dst, b, h) do { _Pragma("unroll") for (int n = 0; n < 2; ++n) _Pragma("unroll") for (int k = 0; k < 2; ++k) dst[n][k] = *(const PG8_LAS bf16x8*)(lds + PG8_SB(b, h) + boff + n * 2048 + k * 1024); } while (0)
; #define PG8_MMA(ai, bj, At, Bt) do { __builtin_amdgcn_s_setprio(1); _Pragma("unroll") for (int m = 0; m < 4; ++m) _Pragma("unroll") for (int n = 0; n < 2; ++n) _Pragma("unroll") for (int k = 0; k < 2; ++k) \
;         acc[ai][bj][m][n] = __builtin_amdgcn_mfma_f32_16x16x32_bf16(Bt[n][k], At[m][k], acc[ai][bj][m][n], 0, 0, 0); __builtin_amdgcn_s_setprio(0); } while (0)
; #define PG8_WAIT_V(n) asm volatile("s_waitcnt vmcnt(" #n ")" ::: "memory")
; #define PG8_WAIT_L(n) asm volatile("s_waitcnt lgkmcnt(" #n ")" ::: "memory")
; #define PG8_BAR __builtin_amdgcn_s_barrier()
; #define PG8_SCHED __builtin_amdgcn_sched_barrier(0)
; template <class Epi, class Sched, bool ALIGN_EPI = false, bool SP2 = false>
; __device__ __forceinline__ void gemm_phase(PG8_LAS unsigned char* lds, const Gemm g, const Sched& S, const Epi& E) {
;     ...
;             const bool last = (t == nt - 2);
;             const char* a1 = cA + (size_t)(t + 1) * kstep;
;             const char* a2 = last ? nA : cA + (size_t)(t + 2) * kstep; const char* b2 = last ? nB : cB + (size_t)(t + 2) * kstep;
;             const char* a3 = a2 + kstep; const char* b3 = b2 + kstep;
;             if (last && has_next) S.a_ready(nxt);
;             if constexpr (SP2) {
;             PG8_LDB(B0, 0, 0); PG8_LDB(B1, 0, 1); PG8_SCHED; PG8_LDA(At, 0, 0); PG8_STAGE(PG8_SA(1, 1), a1 + hstep, voffA);
;             PG8_WAIT_V(8); PG8_WAIT_L(0); PG8_BAR; PG8_MMA(0, 0, At, B0); PG8_MMA(0, 1, At, B1); PG8_BAR; PG8_SCHED;
;             PG8_LDA(At, 0, 1); PG8_STAGE(PG8_SB(0, 0), b2, voffB); PG8_STAGE(PG8_SB(0, 1), b2 + hstep, voffB); PG8_STAGE(PG8_SA(0, 0), a2, voffA);
.LBB0_1746:
	ds_read_b128 v[140:143], v134
	ds_read_b128 v[144:147], v134 offset:1024
	ds_read_b128 v[148:151], v134 offset:2048
	ds_read_b128 v[152:155], v134 offset:3072
	ds_read_b128 v[156:159], v135
	ds_read_b128 v[160:163], v135 offset:1024
	ds_read_b128 v[164:167], v135 offset:2048
	ds_read_b128 v[168:171], v135 offset:3072
	s_add_i32 s36, s38, 2
	s_mov_b32 s37, s11
	s_or_b32 s10, s38, 1
	s_lshl_b64 s[40:41], s[36:37], 7
	s_cmp_lg_u32 s38, s42
	s_cselect_b32 s38, s40, 0
	s_cselect_b32 s37, s41, 0
	s_add_u32 s40, s6, s38
	s_addc_u32 s41, s7, s37
	s_add_u32 s38, s2, s38
	s_addc_u32 s39, s3, s37
	s_lshl_b64 s[52:53], s[10:11], 7
	s_add_u32 s52, s8, s52
	s_addc_u32 s53, s9, s53
	s_mov_b32 m0, s43
	v_lshl_add_u64 v[192:193], s[52:53], 0, v[128:129]
	ds_read_b128 v[172:175], v136
	ds_read_b128 v[176:179], v136 offset:1024
	ds_read_b128 v[180:183], v136 offset:2048
	ds_read_b128 v[184:187], v136 offset:3072
	ds_read_b128 v[188:191], v136 offset:4096
	ds_read_b128 v[196:199], v136 offset:5120
	ds_read_b128 v[202:205], v136 offset:6144
	ds_read_b128 v[206:209], v136 offset:7168
	global_load_lds_dwordx4 v[192:193], off
	v_lshl_add_u64 v[192:193], s[52:53], 0, v[130:131]
	s_mov_b32 m0, s44
	s_nop 0
	global_load_lds_dwordx4 v[192:193], off
	s_waitcnt vmcnt(8)
	s_waitcnt lgkmcnt(0)
	s_setprio 1
	s_barrier
	v_mfma_f32_16x16x32_bf16 v[124:127], v[140:143], v[172:175], v[124:127]
	v_mfma_f32_16x16x32_bf16 v[124:127], v[144:147], v[176:179], v[124:127]
	v_mfma_f32_16x16x32_bf16 v[120:123], v[152:155], v[176:179], v[120:123]
	v_mfma_f32_16x16x32_bf16 v[120:123], v[148:151], v[172:175], v[120:123]
	v_mfma_f32_16x16x32_bf16 v[112:115], v[148:151], v[180:183], v[112:115]
	v_mfma_f32_16x16x32_bf16 v[112:115], v[152:155], v[184:187], v[112:115]
	v_mfma_f32_16x16x32_bf16 v[116:119], v[144:147], v[184:187], v[116:119]
	v_mfma_f32_16x16x32_bf16 v[116:119], v[140:143], v[180:183], v[116:119]
	v_mfma_f32_16x16x32_bf16 v[104:107], v[140:143], v[188:191], v[104:107]
	v_mfma_f32_16x16x32_bf16 v[104:107], v[144:147], v[196:199], v[104:107]
	v_mfma_f32_16x16x32_bf16 v[96:99], v[152:155], v[196:199], v[96:99]
	v_mfma_f32_16x16x32_bf16 v[96:99], v[148:151], v[188:191], v[96:99]
	v_mfma_f32_16x16x32_bf16 v[80:83], v[148:151], v[202:205], v[80:83]
	v_mfma_f32_16x16x32_bf16 v[80:83], v[152:155], v[206:209], v[80:83]
	v_mfma_f32_16x16x32_bf16 v[88:91], v[144:147], v[206:209], v[88:91]
	v_mfma_f32_16x16x32_bf16 v[88:91], v[140:143], v[202:205], v[88:91]
	s_setprio 0
	s_setprio 1
	v_mfma_f32_16x16x32_bf16 v[108:111], v[156:159], v[172:175], v[108:111]
	v_mfma_f32_16x16x32_bf16 v[108:111], v[160:163], v[176:179], v[108:111]
	v_mfma_f32_16x16x32_bf16 v[100:103], v[168:171], v[176:179], v[100:103]
	v_mfma_f32_16x16x32_bf16 v[100:103], v[164:167], v[172:175], v[100:103]
	v_mfma_f32_16x16x32_bf16 v[84:87], v[164:167], v[180:183], v[84:87]
	v_mfma_f32_16x16x32_bf16 v[84:87], v[168:171], v[184:187], v[84:87]
	v_mfma_f32_16x16x32_bf16 v[92:95], v[160:163], v[184:187], v[92:95]
	v_mfma_f32_16x16x32_bf16 v[92:95], v[156:159], v[180:183], v[92:95]
	v_mfma_f32_16x16x32_bf16 v[76:79], v[156:159], v[188:191], v[76:79]
	v_mfma_f32_16x16x32_bf16 v[76:79], v[160:163], v[196:199], v[76:79]
	v_mfma_f32_16x16x32_bf16 v[72:75], v[168:171], v[196:199], v[72:75]
	v_mfma_f32_16x16x32_bf16 v[72:75], v[164:167], v[188:191], v[72:75]
	v_mfma_f32_16x16x32_bf16 v[64:67], v[164:167], v[202:205], v[64:67]
	v_mfma_f32_16x16x32_bf16 v[64:67], v[168:171], v[206:209], v[64:67]
	v_mfma_f32_16x16x32_bf16 v[68:71], v[160:163], v[206:209], v[68:71]
	v_mfma_f32_16x16x32_bf16 v[68:71], v[156:159], v[202:205], v[68:71]
	s_barrier
	s_setprio 0
	s_mov_b32 m0, s31
	v_lshl_add_u64 v[192:193], s[38:39], 0, v[128:129]
	s_add_u32 s52, s38, 0x2b0000
	ds_read_b128 v[172:175], v136 offset:16384
	ds_read_b128 v[176:179], v136 offset:17408
	ds_read_b128 v[180:183], v136 offset:18432
	ds_read_b128 v[184:187], v136 offset:19456
	ds_read_b128 v[188:191], v136 offset:20480
	ds_read_b128 v[196:199], v136 offset:21504
	ds_read_b128 v[202:205], v136 offset:22528
	ds_read_b128 v[206:209], v136 offset:23552
	global_load_lds_dwordx4 v[192:193], off
	v_lshl_add_u64 v[194:195], s[38:39], 0, v[130:131]
	s_mov_b32 m0, s45
	s_addc_u32 s53, s39, 0
	global_load_lds_dwordx4 v[194:195], off
	v_lshl_add_u64 v[210:211], s[52:53], 0, v[128:129]
	s_mov_b32 m0, s46
	v_lshl_add_u64 v[212:213], s[40:41], 0, v[130:131]
	global_load_lds_dwordx4 v[210:211], off
	v_lshl_add_u64 v[210:211], s[52:53], 0, v[130:131]
	s_mov_b32 m0, s47
	s_nop 0
	global_load_lds_dwordx4 v[210:211], off
	v_lshl_add_u64 v[210:211], s[40:41], 0, v[128:129]
	s_mov_b32 m0, s26
	s_nop 0
	global_load_lds_dwordx4 v[210:211], off
	s_mov_b32 m0, s27
	s_nop 0
	global_load_lds_dwordx4 v[212:213], off
	s_waitcnt vmcnt(8)
	s_waitcnt lgkmcnt(0)
	s_setprio 1
	s_barrier
; #define PG8_STAGE(bufoff, gbase, voff) do { _Pragma("unroll") for (int _i = 0; _i < 2; ++_i) \
;         __builtin_amdgcn_global_load_lds((const unsigned*)((const char*)(gbase) + (voff)[_i]), (PG8_LAS unsigned*)(lds + (bufoff) + ldsw + _i * 8192), 16, 0, 0); } while (0)
; #define PG8_LDA(dst, b, h) do { _Pragma("unroll") for (int m = 0; m < 4; ++m) _Pragma("unroll") for (int k = 0; k < 2; ++k) dst[m][k] = *(const PG8_LAS bf16x8*)(lds + PG8_SA(b, h) + aoff + m * 2048 + k * 1024); } while (0)
; #define PG8_LDB(dst, b, h) do { _Pragma("unroll") for (int n = 0; n < 2; ++n) _Pragma("unroll") for (int k = 0; k < 2; ++k) dst[n][k] = *(const PG8_LAS bf16x8*)(lds + PG8_SB(b, h) + boff + n * 2048 + k * 1024); } while (0)
; #define PG8_MMA(ai, bj, At, Bt) do { __builtin_amdgcn_s_setprio(1); _Pragma("unroll") for (int m = 0; m < 4; ++m) _Pragma("unroll") for (int n = 0; n < 2; ++n) _Pragma("unroll") for (int k = 0; k < 2; ++k) \
;         acc[ai][bj][m][n] = __builtin_amdgcn_mfma_f32_16x16x32_bf16(Bt[n][k], At[m][k], acc[ai][bj][m][n], 0, 0, 0); __builtin_amdgcn_s_setprio(0); } while (0)
; #define PG8_WAIT_V(n) asm volatile("s_waitcnt vmcnt(" #n ")" ::: "memory")
; #define PG8_WAIT_L(n) asm volatile("s_waitcnt lgkmcnt(" #n ")" ::: "memory")
; #define PG8_BAR __builtin_amdgcn_s_barrier()
; #define PG8_SCHED __builtin_amdgcn_sched_barrier(0)
; template <class Epi, class Sched, bool ALIGN_EPI = false, bool SP2 = false>
; __device__ __forceinline__ void gemm_phase(PG8_LAS unsigned char* lds, const Gemm g, const Sched& S, const Epi& E) {
;     ...
;             PG8_WAIT_V(8); PG8_WAIT_L(0); PG8_BAR; PG8_MMA(1, 0, At, B0); PG8_MMA(1, 1, At, B1); PG8_BAR; PG8_SCHED;
;             PG8_LDB(B0, 1, 0); PG8_LDB(B1, 1, 1); PG8_SCHED; PG8_LDA(At, 1, 0); PG8_STAGE(PG8_SA(0, 1), a2 + hstep, voffA);
;             PG8_WAIT_V(8); PG8_WAIT_L(0); PG8_BAR; PG8_MMA(0, 0, At, B0); PG8_MMA(0, 1, At, B1); PG8_BAR; PG8_SCHED;
	v_mfma_f32_16x16x32_bf16 v[60:63], v[140:143], v[172:175], v[60:63]
	v_mfma_f32_16x16x32_bf16 v[60:63], v[144:147], v[176:179], v[60:63]
	v_mfma_f32_16x16x32_bf16 v[56:59], v[152:155], v[176:179], v[56:59]
	v_mfma_f32_16x16x32_bf16 v[56:59], v[148:151], v[172:175], v[56:59]
	v_mfma_f32_16x16x32_bf16 v[48:51], v[148:151], v[180:183], v[48:51]
	v_mfma_f32_16x16x32_bf16 v[48:51], v[152:155], v[184:187], v[48:51]
	v_mfma_f32_16x16x32_bf16 v[52:55], v[144:147], v[184:187], v[52:55]
	v_mfma_f32_16x16x32_bf16 v[52:55], v[140:143], v[180:183], v[52:55]
	v_mfma_f32_16x16x32_bf16 v[40:43], v[140:143], v[188:191], v[40:43]
	v_mfma_f32_16x16x32_bf16 v[40:43], v[144:147], v[196:199], v[40:43]
	v_mfma_f32_16x16x32_bf16 v[32:35], v[152:155], v[196:199], v[32:35]
	v_mfma_f32_16x16x32_bf16 v[32:35], v[148:151], v[188:191], v[32:35]
	v_mfma_f32_16x16x32_bf16 v[16:19], v[148:151], v[202:205], v[16:19]
	v_mfma_f32_16x16x32_bf16 v[16:19], v[152:155], v[206:209], v[16:19]
	v_mfma_f32_16x16x32_bf16 v[24:27], v[144:147], v[206:209], v[24:27]
	v_mfma_f32_16x16x32_bf16 v[24:27], v[140:143], v[202:205], v[24:27]
	s_setprio 0
	s_setprio 1
	v_mfma_f32_16x16x32_bf16 v[44:47], v[156:159], v[172:175], v[44:47]
	v_mfma_f32_16x16x32_bf16 v[44:47], v[160:163], v[176:179], v[44:47]
	v_mfma_f32_16x16x32_bf16 v[36:39], v[168:171], v[176:179], v[36:39]
	v_mfma_f32_16x16x32_bf16 v[36:39], v[164:167], v[172:175], v[36:39]
	v_mfma_f32_16x16x32_bf16 v[20:23], v[164:167], v[180:183], v[20:23]
	v_mfma_f32_16x16x32_bf16 v[20:23], v[168:171], v[184:187], v[20:23]
	v_mfma_f32_16x16x32_bf16 v[28:31], v[160:163], v[184:187], v[28:31]
	v_mfma_f32_16x16x32_bf16 v[28:31], v[156:159], v[180:183], v[28:31]
	v_mfma_f32_16x16x32_bf16 v[12:15], v[156:159], v[188:191], v[12:15]
	v_mfma_f32_16x16x32_bf16 v[12:15], v[160:163], v[196:199], v[12:15]
	v_mfma_f32_16x16x32_bf16 v[8:11], v[168:171], v[196:199], v[8:11]
	v_mfma_f32_16x16x32_bf16 v[8:11], v[164:167], v[188:191], v[8:11]
	v_mfma_f32_16x16x32_bf16 v[0:3], v[164:167], v[202:205], v[0:3]
	v_mfma_f32_16x16x32_bf16 v[0:3], v[168:171], v[206:209], v[0:3]
	v_mfma_f32_16x16x32_bf16 v[4:7], v[160:163], v[206:209], v[4:7]
	v_mfma_f32_16x16x32_bf16 v[4:7], v[156:159], v[202:205], v[4:7]
	s_barrier
	s_setprio 0
	ds_read_b128 v[140:143], v137
	ds_read_b128 v[144:147], v137 offset:1024
	ds_read_b128 v[148:151], v137 offset:2048
	ds_read_b128 v[152:155], v137 offset:3072
	ds_read_b128 v[156:159], v138
	ds_read_b128 v[160:163], v138 offset:1024
	ds_read_b128 v[164:167], v138 offset:2048
	ds_read_b128 v[168:171], v138 offset:3072
	s_add_u32 s40, s40, 0x2b0000
	s_addc_u32 s41, s41, 0
	s_mov_b32 m0, s28
	v_lshl_add_u64 v[214:215], s[40:41], 0, v[128:129]
	ds_read_b128 v[172:175], v136 offset:32768
	ds_read_b128 v[176:179], v136 offset:33792
	ds_read_b128 v[180:183], v136 offset:34816
	ds_read_b128 v[184:187], v136 offset:35840
	ds_read_b128 v[188:191], v136 offset:36864
	ds_read_b128 v[196:199], v136 offset:37888
	ds_read_b128 v[202:205], v136 offset:38912
	ds_read_b128 v[206:209], v136 offset:39936
	global_load_lds_dwordx4 v[214:215], off
	v_lshl_add_u64 v[214:215], s[40:41], 0, v[130:131]
	s_mov_b32 m0, s30
	s_nop 0
	global_load_lds_dwordx4 v[214:215], off
	s_waitcnt vmcnt(8)
	s_waitcnt lgkmcnt(0)
	s_setprio 1
	s_barrier
	v_mfma_f32_16x16x32_bf16 v[124:127], v[140:143], v[172:175], v[124:127]
	v_mfma_f32_16x16x32_bf16 v[124:127], v[144:147], v[176:179], v[124:127]
	v_mfma_f32_16x16x32_bf16 v[120:123], v[152:155], v[176:179], v[120:123]
	v_mfma_f32_16x16x32_bf16 v[120:123], v[148:151], v[172:175], v[120:123]
	v_mfma_f32_16x16x32_bf16 v[112:115], v[148:151], v[180:183], v[112:115]
	v_mfma_f32_16x16x32_bf16 v[112:115], v[152:155], v[184:187], v[112:115]
	v_mfma_f32_16x16x32_bf16 v[116:119], v[144:147], v[184:187], v[116:119]
	v_mfma_f32_16x16x32_bf16 v[116:119], v[140:143], v[180:183], v[116:119]
	v_mfma_f32_16x16x32_bf16 v[104:107], v[140:143], v[188:191], v[104:107]
	v_mfma_f32_16x16x32_bf16 v[104:107], v[144:147], v[196:199], v[104:107]
	v_mfma_f32_16x16x32_bf16 v[96:99], v[152:155], v[196:199], v[96:99]
	v_mfma_f32_16x16x32_bf16 v[96:99], v[148:151], v[188:191], v[96:99]
	v_mfma_f32_16x16x32_bf16 v[80:83], v[148:151], v[202:205], v[80:83]
	v_mfma_f32_16x16x32_bf16 v[80:83], v[152:155], v[206:209], v[80:83]
	v_mfma_f32_16x16x32_bf16 v[88:91], v[144:147], v[206:209], v[88:91]
	v_mfma_f32_16x16x32_bf16 v[88:91], v[140:143], v[202:205], v[88:91]
	s_setprio 0
	s_setprio 1
	v_mfma_f32_16x16x32_bf16 v[108:111], v[156:159], v[172:175], v[108:111]
	v_mfma_f32_16x16x32_bf16 v[108:111], v[160:163], v[176:179], v[108:111]
	v_mfma_f32_16x16x32_bf16 v[100:103], v[168:171], v[176:179], v[100:103]
	v_mfma_f32_16x16x32_bf16 v[100:103], v[164:167], v[172:175], v[100:103]
	v_mfma_f32_16x16x32_bf16 v[84:87], v[164:167], v[180:183], v[84:87]
	v_mfma_f32_16x16x32_bf16 v[84:87], v[168:171], v[184:187], v[84:87]
	v_mfma_f32_16x16x32_bf16 v[92:95], v[160:163], v[184:187], v[92:95]
	v_mfma_f32_16x16x32_bf16 v[92:95], v[156:159], v[180:183], v[92:95]
	v_mfma_f32_16x16x32_bf16 v[76:79], v[156:159], v[188:191], v[76:79]
	v_mfma_f32_16x16x32_bf16 v[76:79], v[160:163], v[196:199], v[76:79]
	v_mfma_f32_16x16x32_bf16 v[72:75], v[168:171], v[196:199], v[72:75]
	v_mfma_f32_16x16x32_bf16 v[72:75], v[164:167], v[188:191], v[72:75]
	v_mfma_f32_16x16x32_bf16 v[64:67], v[164:167], v[202:205], v[64:67]
	v_mfma_f32_16x16x32_bf16 v[64:67], v[168:171], v[206:209], v[64:67]
	v_mfma_f32_16x16x32_bf16 v[68:71], v[160:163], v[206:209], v[68:71]
	v_mfma_f32_16x16x32_bf16 v[68:71], v[156:159], v[202:205], v[68:71]
	s_barrier
; #define PG8_STAGE(bufoff, gbase, voff) do { _Pragma("unroll") for (int _i = 0; _i < 2; ++_i) \
;         __builtin_amdgcn_global_load_lds((const unsigned*)((const char*)(gbase) + (voff)[_i]), (PG8_LAS unsigned*)(lds + (bufoff) + ldsw + _i * 8192), 16, 0, 0); } while (0)
; #define PG8_LDA(dst, b, h) do { _Pragma("unroll") for (int m = 0; m < 4; ++m) _Pragma("unroll") for (int k = 0; k < 2; ++k) dst[m][k] = *(const PG8_LAS bf16x8*)(lds + PG8_SA(b, h) + aoff + m * 2048 + k * 1024); } while (0)
; #define PG8_MMA(ai, bj, At, Bt) do { __builtin_amdgcn_s_setprio(1); _Pragma("unroll") for (int m = 0; m < 4; ++m) _Pragma("unroll") for (int n = 0; n < 2; ++n) _Pragma("unroll") for (int k = 0; k < 2; ++k) \
;         acc[ai][bj][m][n] = __builtin_amdgcn_mfma_f32_16x16x32_bf16(Bt[n][k], At[m][k], acc[ai][bj][m][n], 0, 0, 0); __builtin_amdgcn_s_setprio(0); } while (0)
; #define PG8_WAIT_V(n) asm volatile("s_waitcnt vmcnt(" #n ")" ::: "memory")
; #define PG8_WAIT_L(n) asm volatile("s_waitcnt lgkmcnt(" #n ")" ::: "memory")
; #define PG8_BAR __builtin_amdgcn_s_barrier()
; #define PG8_SCHED __builtin_amdgcn_sched_barrier(0)
; template <class Epi, class Sched, bool ALIGN_EPI = false, bool SP2 = false>
; __device__ __forceinline__ void gemm_phase(PG8_LAS unsigned char* lds, const Gemm g, const Sched& S, const Epi& E) {
;     ...
;             PG8_LDA(At, 1, 1); PG8_STAGE(PG8_SB(1, 0), b3, voffB); PG8_STAGE(PG8_SB(1, 1), b3 + hstep, voffB); PG8_STAGE(PG8_SA(1, 0), a3, voffA);
;             PG8_WAIT_V(8); PG8_WAIT_L(0); PG8_BAR; PG8_MMA(1, 0, At, B0); PG8_MMA(1, 1, At, B1); PG8_BAR; PG8_SCHED;
;     ...
;         if constexpr (ALIGN_EPI) { if (wr == 0) PG8_BAR; }
	s_setprio 0
	s_mov_b32 m0, s48
	v_lshl_add_u64 v[192:193], v[192:193], 0, s[12:13]
	s_add_u32 s38, s38, 0x2b0080
	ds_read_b128 v[172:175], v136 offset:49152
	ds_read_b128 v[176:179], v136 offset:50176
	ds_read_b128 v[180:183], v136 offset:51200
	ds_read_b128 v[184:187], v136 offset:52224
	ds_read_b128 v[188:191], v136 offset:53248
	ds_read_b128 v[196:199], v136 offset:54272
	ds_read_b128 v[202:205], v136 offset:55296
	ds_read_b128 v[206:209], v136 offset:56320
	global_load_lds_dwordx4 v[192:193], off
	v_lshl_add_u64 v[192:193], v[194:195], 0, s[12:13]
	s_mov_b32 m0, s49
	s_addc_u32 s39, s39, 0
	global_load_lds_dwordx4 v[192:193], off
	v_lshl_add_u64 v[192:193], s[38:39], 0, v[128:129]
	s_mov_b32 m0, s50
	s_nop 0
	global_load_lds_dwordx4 v[192:193], off
	v_lshl_add_u64 v[192:193], s[38:39], 0, v[130:131]
	s_mov_b32 m0, s51
	s_nop 0
	global_load_lds_dwordx4 v[192:193], off
	v_lshl_add_u64 v[192:193], v[210:211], 0, s[12:13]
	s_mov_b32 m0, s34
	s_nop 0
	global_load_lds_dwordx4 v[192:193], off
	v_lshl_add_u64 v[192:193], v[212:213], 0, s[12:13]
	s_mov_b32 m0, s35
	s_nop 0
	global_load_lds_dwordx4 v[192:193], off
	s_waitcnt vmcnt(8)
	s_waitcnt lgkmcnt(0)
	s_setprio 1
	s_barrier
	v_mfma_f32_16x16x32_bf16 v[60:63], v[140:143], v[172:175], v[60:63]
	v_mfma_f32_16x16x32_bf16 v[60:63], v[144:147], v[176:179], v[60:63]
	v_mfma_f32_16x16x32_bf16 v[56:59], v[152:155], v[176:179], v[56:59]
	v_mfma_f32_16x16x32_bf16 v[56:59], v[148:151], v[172:175], v[56:59]
	v_mfma_f32_16x16x32_bf16 v[48:51], v[148:151], v[180:183], v[48:51]
	v_mfma_f32_16x16x32_bf16 v[48:51], v[152:155], v[184:187], v[48:51]
	v_mfma_f32_16x16x32_bf16 v[52:55], v[144:147], v[184:187], v[52:55]
	v_mfma_f32_16x16x32_bf16 v[52:55], v[140:143], v[180:183], v[52:55]
	v_mfma_f32_16x16x32_bf16 v[40:43], v[140:143], v[188:191], v[40:43]
	v_mfma_f32_16x16x32_bf16 v[40:43], v[144:147], v[196:199], v[40:43]
	v_mfma_f32_16x16x32_bf16 v[32:35], v[152:155], v[196:199], v[32:35]
	v_mfma_f32_16x16x32_bf16 v[32:35], v[148:151], v[188:191], v[32:35]
	v_mfma_f32_16x16x32_bf16 v[16:19], v[148:151], v[202:205], v[16:19]
	v_mfma_f32_16x16x32_bf16 v[16:19], v[152:155], v[206:209], v[16:19]
	v_mfma_f32_16x16x32_bf16 v[24:27], v[144:147], v[206:209], v[24:27]
	v_mfma_f32_16x16x32_bf16 v[24:27], v[140:143], v[202:205], v[24:27]
	s_setprio 0
	s_setprio 1
	v_mfma_f32_16x16x32_bf16 v[44:47], v[156:159], v[172:175], v[44:47]
	v_mfma_f32_16x16x32_bf16 v[44:47], v[160:163], v[176:179], v[44:47]
	v_mfma_f32_16x16x32_bf16 v[36:39], v[168:171], v[176:179], v[36:39]
	v_mfma_f32_16x16x32_bf16 v[36:39], v[164:167], v[172:175], v[36:39]
	v_mfma_f32_16x16x32_bf16 v[20:23], v[164:167], v[180:183], v[20:23]
	v_mfma_f32_16x16x32_bf16 v[20:23], v[168:171], v[184:187], v[20:23]
	v_mfma_f32_16x16x32_bf16 v[28:31], v[160:163], v[184:187], v[28:31]
	v_mfma_f32_16x16x32_bf16 v[28:31], v[156:159], v[180:183], v[28:31]
	v_mfma_f32_16x16x32_bf16 v[12:15], v[156:159], v[188:191], v[12:15]
	v_mfma_f32_16x16x32_bf16 v[12:15], v[160:163], v[196:199], v[12:15]
	v_mfma_f32_16x16x32_bf16 v[8:11], v[168:171], v[196:199], v[8:11]
	v_mfma_f32_16x16x32_bf16 v[8:11], v[164:167], v[188:191], v[8:11]
	v_mfma_f32_16x16x32_bf16 v[0:3], v[164:167], v[202:205], v[0:3]
	v_mfma_f32_16x16x32_bf16 v[0:3], v[168:171], v[206:209], v[0:3]
	v_mfma_f32_16x16x32_bf16 v[4:7], v[160:163], v[206:209], v[4:7]
	v_mfma_f32_16x16x32_bf16 v[4:7], v[156:159], v[202:205], v[4:7]
	s_barrier
	s_setprio 0
	s_cmp_ge_u32 s36, s5
	s_mov_b32 s38, s36
	s_cbranch_scc0 .LBB0_1746
	s_cmpk_lt_u32 s16, 0x100
	s_cbranch_scc0 .LBB0_1749
	s_barrier
